# loader-prep-in-mfma-shadow
# speedup vs baseline: 1.0127x; 1.0025x over previous
; #define PG8_STAGE(bufoff, gbase, voff) do { _Pragma("unroll") for (int _i = 0; _i < 2; ++_i) \
;         __builtin_amdgcn_global_load_lds((const unsigned*)((const char*)(gbase) + (voff)[_i]), (LAS unsigned*)(lds + (bufoff) + ldsw + _i * 8192), 16, 0, 0); } while (0)
; #define PG8_LDA(dst, b, h) do { _Pragma("unroll") for (int m = 0; m < 4; ++m) _Pragma("unroll") for (int k = 0; k < 2; ++k) dst[m][k] = *(const LAS bf16x8*)(lds + PG8_SA(b, h) + aoff + m * 2048 + k * 1024); } while (0)
; #define PG8_LDB(dst, b, h) do { _Pragma("unroll") for (int n = 0; n < 2; ++n) _Pragma("unroll") for (int k = 0; k < 2; ++k) dst[n][k] = *(const LAS bf16x8*)(lds + PG8_SB(b, h) + boff + n * 2048 + k * 1024); } while (0)
; #define PG8_MMA(ai, bj, At, Bt) do { __builtin_amdgcn_s_setprio(1); _Pragma("unroll") for (int m = 0; m < 4; ++m) _Pragma("unroll") for (int n = 0; n < 2; ++n) _Pragma("unroll") for (int k = 0; k < 2; ++k) \
;         acc[ai][bj][m][n] = __builtin_amdgcn_mfma_f32_16x16x32_bf16(Bt[n][k], At[m][k], acc[ai][bj][m][n], 0, 0, 0); __builtin_amdgcn_s_setprio(0); } while (0)
; #define PG8_WAIT_V(n) asm volatile("s_waitcnt vmcnt(" #n ")" ::: "memory")
; #define PG8_WAIT_L(n) asm volatile("s_waitcnt lgkmcnt(" #n ")" ::: "memory")
; template <class Epi, class Sched, bool ATILE = false>
; __device__ __forceinline__ void gemm_phase(LAS unsigned char* lds, const Gemm g, const Sched& S, const Epi& E) {
;     ...
;         for (int t = 0; t < nt; t += 2) {
;             const bool last = (t == nt - 2);
;             const char* a1 = cA + (size_t)(t + 1) * kstepA;
;             const char* a2 = last ? nA : cA + (size_t)(t + 2) * kstepA; const char* b2 = last ? nB : cB + (size_t)(t + 2) * kstep;
;             const char* a3 = a2 + kstepA; const char* b3 = b2 + kstep;
;             PG8_LDB(B0, 0, 0); PG8_SCHED; PG8_LDA(At, 0, 0); PG8_STAGE(PG8_SA(1, 1), a1 + hstepA, voffA);
;             PG8_WAIT_L(8); PG8_BAR; PG8_WAIT_L(0); PG8_MMA(0, 0, At, B0); PG8_BAR; PG8_SCHED;
;             PG8_LDB(B1, 0, 1); PG8_STAGE(PG8_SB(0, 0), b2, voffB);
;             PG8_BAR; PG8_WAIT_L(0); PG8_MMA(0, 1, At, B1); PG8_BAR;
;             PG8_LDA(At, 0, 1); PG8_STAGE(PG8_SA(0, 0), a2, voffA);
;             PG8_BAR; PG8_WAIT_L(0); PG8_MMA(1, 0, At, B0); PG8_BAR; PG8_SCHED;
;             PG8_STAGE(PG8_SB(0, 1), b2 + hstepB, voffB);
;             PG8_WAIT_V(6); PG8_BAR; PG8_MMA(1, 1, At, B1); PG8_BAR;
.LBB0_625:
	ds_read_b128 v[182:185], v139
	ds_read_b128 v[186:189], v139 offset:1024
	ds_read_b128 v[190:193], v139 offset:2048
	ds_read_b128 v[194:197], v139 offset:3072
	s_add_i32 s62, s28, 2
	s_add_u32 s29, s26, 0xfff80080
	s_addc_u32 s30, s27, -1
	s_cmp_eq_u32 s59, s28
	s_cselect_b32 s28, s58, s60
	s_cselect_b32 s31, s13, s30
	s_cselect_b32 s30, s56, s29
	s_cselect_b32 s29, s57, s61
	s_add_i32 m0, s35, 0xc000
	ds_read_b128 v[198:201], v163
	ds_read_b128 v[202:205], v163 offset:1024
	ds_read_b128 v[206:209], v163 offset:2048
	ds_read_b128 v[210:213], v163 offset:3072
	ds_read_b128 v[214:217], v163 offset:4096
	ds_read_b128 v[218:221], v163 offset:5120
	ds_read_b128 v[222:225], v163 offset:6144
	ds_read_b128 v[226:229], v163 offset:7168
	global_load_lds_dwordx4 v172, s[26:27]
	s_add_i32 m0, s35, 0xe000
	s_nop 0
	global_load_lds_dwordx4 v174, s[26:27]
	s_waitcnt lgkmcnt(8)
	s_setprio 1
	s_barrier
	s_waitcnt lgkmcnt(0)
	v_mfma_f32_16x16x32_bf16 v[120:123], v[182:185], v[198:201], v[120:123]
	v_mfma_f32_16x16x32_bf16 v[112:115], v[190:193], v[198:201], v[112:115]
	v_mfma_f32_16x16x32_bf16 v[104:107], v[182:185], v[206:209], v[104:107]
	v_mfma_f32_16x16x32_bf16 v[96:99], v[190:193], v[206:209], v[96:99]
	v_mfma_f32_16x16x32_bf16 v[88:91], v[182:185], v[214:217], v[88:91]
	v_mfma_f32_16x16x32_bf16 v[80:83], v[190:193], v[214:217], v[80:83]
	v_mfma_f32_16x16x32_bf16 v[72:75], v[182:185], v[222:225], v[72:75]
	v_mfma_f32_16x16x32_bf16 v[64:67], v[190:193], v[222:225], v[64:67]
	s_add_i32 s63, s53, s34
	v_mfma_f32_16x16x32_bf16 v[120:123], v[186:189], v[202:205], v[120:123]
	s_add_u32 s98, s28, s0
	v_mfma_f32_16x16x32_bf16 v[112:115], v[194:197], v[202:205], v[112:115]
	s_addc_u32 s99, s29, s1
	v_mfma_f32_16x16x32_bf16 v[104:107], v[186:189], v[210:213], v[104:107]
	s_mov_b32 m0, s63
	v_mfma_f32_16x16x32_bf16 v[96:99], v[194:197], v[210:213], v[96:99]
	v_mfma_f32_16x16x32_bf16 v[88:91], v[186:189], v[218:221], v[88:91]
	v_mfma_f32_16x16x32_bf16 v[80:83], v[194:197], v[218:221], v[80:83]
	v_mfma_f32_16x16x32_bf16 v[72:75], v[186:189], v[226:229], v[72:75]
	v_mfma_f32_16x16x32_bf16 v[64:67], v[194:197], v[226:229], v[64:67]
	s_barrier
	s_setprio 0
	ds_read_b128 v[230:233], v167
	ds_read_b128 v[234:237], v167 offset:1024
	ds_read_b128 v[238:241], v167 offset:2048
	ds_read_b128 v[242:245], v167 offset:3072
	global_load_lds_dwordx4 v130, s[28:29]
	s_add_i32 m0, s63, 0x2000
	s_nop 0
	global_load_lds_dwordx4 v134, s[28:29]
	s_setprio 1
	s_barrier
	s_waitcnt lgkmcnt(0)
	v_mfma_f32_16x16x32_bf16 v[124:127], v[230:233], v[198:201], v[124:127]
	v_mfma_f32_16x16x32_bf16 v[116:119], v[238:241], v[198:201], v[116:119]
	v_mfma_f32_16x16x32_bf16 v[108:111], v[230:233], v[206:209], v[108:111]
	v_mfma_f32_16x16x32_bf16 v[100:103], v[238:241], v[206:209], v[100:103]
	v_mfma_f32_16x16x32_bf16 v[92:95], v[230:233], v[214:217], v[92:95]
	v_mfma_f32_16x16x32_bf16 v[84:87], v[238:241], v[214:217], v[84:87]
	v_mfma_f32_16x16x32_bf16 v[76:79], v[230:233], v[222:225], v[76:79]
	v_mfma_f32_16x16x32_bf16 v[68:71], v[238:241], v[222:225], v[68:71]
	s_mov_b32 m0, s35
	v_mfma_f32_16x16x32_bf16 v[124:127], v[234:237], v[202:205], v[124:127]
	s_add_u32 s100, s30, s0
	v_mfma_f32_16x16x32_bf16 v[116:119], v[242:245], v[202:205], v[116:119]
	s_addc_u32 s101, s31, s1
	v_mfma_f32_16x16x32_bf16 v[108:111], v[234:237], v[210:213], v[108:111]
	v_mfma_f32_16x16x32_bf16 v[100:103], v[242:245], v[210:213], v[100:103]
	v_mfma_f32_16x16x32_bf16 v[92:95], v[234:237], v[218:221], v[92:95]
	v_mfma_f32_16x16x32_bf16 v[84:87], v[242:245], v[218:221], v[84:87]
	v_mfma_f32_16x16x32_bf16 v[76:79], v[234:237], v[226:229], v[76:79]
	v_mfma_f32_16x16x32_bf16 v[68:71], v[242:245], v[226:229], v[68:71]
	s_barrier
	s_setprio 0
	ds_read_b128 v[198:201], v163 offset:16384
	ds_read_b128 v[202:205], v163 offset:17408
	ds_read_b128 v[206:209], v163 offset:18432
	ds_read_b128 v[210:213], v163 offset:19456
	ds_read_b128 v[214:217], v163 offset:20480
	ds_read_b128 v[218:221], v163 offset:21504
	ds_read_b128 v[222:225], v163 offset:22528
	ds_read_b128 v[226:229], v163 offset:23552
	global_load_lds_dwordx4 v128, s[30:31]
	s_mov_b32 m0, s36
	s_nop 0
	global_load_lds_dwordx4 v132, s[30:31]
	s_setprio 1
	s_barrier
	s_waitcnt lgkmcnt(0)
	v_mfma_f32_16x16x32_bf16 v[56:59], v[182:185], v[198:201], v[56:59]
	v_mfma_f32_16x16x32_bf16 v[48:51], v[190:193], v[198:201], v[48:51]
	v_mfma_f32_16x16x32_bf16 v[40:43], v[182:185], v[206:209], v[40:43]
	v_mfma_f32_16x16x32_bf16 v[32:35], v[190:193], v[206:209], v[32:35]
	v_mfma_f32_16x16x32_bf16 v[24:27], v[182:185], v[214:217], v[24:27]
	v_mfma_f32_16x16x32_bf16 v[16:19], v[190:193], v[214:217], v[16:19]
	v_mfma_f32_16x16x32_bf16 v[8:11], v[182:185], v[222:225], v[8:11]
	v_mfma_f32_16x16x32_bf16 v[4:7], v[190:193], v[222:225], v[4:7]
	s_add_u32 s64, s28, 0x80000
	v_mfma_f32_16x16x32_bf16 v[56:59], v[186:189], v[202:205], v[56:59]
	s_addc_u32 s65, s29, 0
	v_mfma_f32_16x16x32_bf16 v[48:51], v[194:197], v[202:205], v[48:51]
	s_add_i32 s63, s54, s34
	v_mfma_f32_16x16x32_bf16 v[40:43], v[186:189], v[210:213], v[40:43]
	s_mov_b32 m0, s63
	v_mfma_f32_16x16x32_bf16 v[32:35], v[194:197], v[210:213], v[32:35]
	v_mfma_f32_16x16x32_bf16 v[24:27], v[186:189], v[218:221], v[24:27]
	v_mfma_f32_16x16x32_bf16 v[16:19], v[194:197], v[218:221], v[16:19]
	v_mfma_f32_16x16x32_bf16 v[8:11], v[186:189], v[226:229], v[8:11]
	v_mfma_f32_16x16x32_bf16 v[4:7], v[194:197], v[226:229], v[4:7]
	s_barrier
	s_setprio 0
	s_nop 0
	global_load_lds_dwordx4 v130, s[64:65]
	s_add_i32 m0, s63, 0x2000
	s_nop 0
	global_load_lds_dwordx4 v134, s[64:65]
	s_waitcnt vmcnt(6)
	s_setprio 1
	s_barrier
; #define PG8_STAGE(bufoff, gbase, voff) do { _Pragma("unroll") for (int _i = 0; _i < 2; ++_i) \
;         __builtin_amdgcn_global_load_lds((const unsigned*)((const char*)(gbase) + (voff)[_i]), (LAS unsigned*)(lds + (bufoff) + ldsw + _i * 8192), 16, 0, 0); } while (0)
; #define PG8_LDA(dst, b, h) do { _Pragma("unroll") for (int m = 0; m < 4; ++m) _Pragma("unroll") for (int k = 0; k < 2; ++k) dst[m][k] = *(const LAS bf16x8*)(lds + PG8_SA(b, h) + aoff + m * 2048 + k * 1024); } while (0)
; #define PG8_LDB(dst, b, h) do { _Pragma("unroll") for (int n = 0; n < 2; ++n) _Pragma("unroll") for (int k = 0; k < 2; ++k) dst[n][k] = *(const LAS bf16x8*)(lds + PG8_SB(b, h) + boff + n * 2048 + k * 1024); } while (0)
; #define PG8_MMA(ai, bj, At, Bt) do { __builtin_amdgcn_s_setprio(1); _Pragma("unroll") for (int m = 0; m < 4; ++m) _Pragma("unroll") for (int n = 0; n < 2; ++n) _Pragma("unroll") for (int k = 0; k < 2; ++k) \
;         acc[ai][bj][m][n] = __builtin_amdgcn_mfma_f32_16x16x32_bf16(Bt[n][k], At[m][k], acc[ai][bj][m][n], 0, 0, 0); __builtin_amdgcn_s_setprio(0); } while (0)
; #define PG8_WAIT_V(n) asm volatile("s_waitcnt vmcnt(" #n ")" ::: "memory")
; #define PG8_WAIT_L(n) asm volatile("s_waitcnt lgkmcnt(" #n ")" ::: "memory")
; #define PG8_BAR __builtin_amdgcn_s_barrier()
; #define PG8_SCHED __builtin_amdgcn_sched_barrier(0)
; template <class Epi, class Sched, bool ATILE = false>
; __device__ __forceinline__ void gemm_phase(LAS unsigned char* lds, const Gemm g, const Sched& S, const Epi& E) {
;     ...
;             PG8_WAIT_V(6); PG8_BAR; PG8_MMA(1, 1, At, B1); PG8_BAR;
;             PG8_LDB(B0, 1, 0); PG8_SCHED; PG8_LDA(At, 1, 0); PG8_STAGE(PG8_SA(0, 1), a2 + hstepA, voffA);
;             PG8_WAIT_L(8); PG8_BAR; PG8_WAIT_L(0); PG8_MMA(0, 0, At, B0); PG8_BAR; PG8_SCHED;
;             PG8_LDB(B1, 1, 1); PG8_STAGE(PG8_SB(1, 0), b3, voffB);
;             PG8_BAR; PG8_WAIT_L(0); PG8_MMA(0, 1, At, B1); PG8_BAR;
	v_mfma_f32_16x16x32_bf16 v[60:63], v[230:233], v[198:201], v[60:63]
	v_mfma_f32_16x16x32_bf16 v[52:55], v[238:241], v[198:201], v[52:55]
	v_mfma_f32_16x16x32_bf16 v[44:47], v[230:233], v[206:209], v[44:47]
	v_mfma_f32_16x16x32_bf16 v[36:39], v[238:241], v[206:209], v[36:39]
	v_mfma_f32_16x16x32_bf16 v[28:31], v[230:233], v[214:217], v[28:31]
	v_mfma_f32_16x16x32_bf16 v[20:23], v[238:241], v[214:217], v[20:23]
	v_mfma_f32_16x16x32_bf16 v[12:15], v[230:233], v[222:225], v[12:15]
	v_mfma_f32_16x16x32_bf16 v[0:3], v[238:241], v[222:225], v[0:3]
	s_add_i32 s63, 0, 0x18000
	v_mfma_f32_16x16x32_bf16 v[60:63], v[234:237], v[202:205], v[60:63]
	v_add_u32_e32 v176, s63, v161
	v_mfma_f32_16x16x32_bf16 v[52:55], v[242:245], v[202:205], v[52:55]
	v_mfma_f32_16x16x32_bf16 v[44:47], v[234:237], v[210:213], v[44:47]
	v_mfma_f32_16x16x32_bf16 v[36:39], v[242:245], v[210:213], v[36:39]
	v_mfma_f32_16x16x32_bf16 v[28:31], v[234:237], v[218:221], v[28:31]
	v_mfma_f32_16x16x32_bf16 v[20:23], v[242:245], v[218:221], v[20:23]
	v_mfma_f32_16x16x32_bf16 v[12:15], v[234:237], v[226:229], v[12:15]
	v_mfma_f32_16x16x32_bf16 v[0:3], v[242:245], v[226:229], v[0:3]
	s_barrier
	s_setprio 0
	ds_read_b128 v[182:185], v176
	ds_read_b128 v[186:189], v176 offset:1024
	ds_read_b128 v[190:193], v176 offset:2048
	ds_read_b128 v[194:197], v176 offset:3072
	s_add_u32 s30, s30, 0x80000
	s_addc_u32 s31, s31, 0
	s_mov_b32 m0, s37
	ds_read_b128 v[198:201], v163 offset:32768
	ds_read_b128 v[202:205], v163 offset:33792
	ds_read_b128 v[206:209], v163 offset:34816
	ds_read_b128 v[210:213], v163 offset:35840
	ds_read_b128 v[214:217], v163 offset:36864
	ds_read_b128 v[218:221], v163 offset:37888
	ds_read_b128 v[222:225], v163 offset:38912
	ds_read_b128 v[226:229], v163 offset:39936
	global_load_lds_dwordx4 v128, s[30:31]
	s_mov_b32 m0, s38
	s_nop 0
	global_load_lds_dwordx4 v132, s[30:31]
	s_waitcnt lgkmcnt(8)
	s_setprio 1
	s_barrier
	s_waitcnt lgkmcnt(0)
	v_mfma_f32_16x16x32_bf16 v[120:123], v[182:185], v[198:201], v[120:123]
	v_mfma_f32_16x16x32_bf16 v[112:115], v[190:193], v[198:201], v[112:115]
	v_mfma_f32_16x16x32_bf16 v[104:107], v[182:185], v[206:209], v[104:107]
	v_mfma_f32_16x16x32_bf16 v[96:99], v[190:193], v[206:209], v[96:99]
	v_mfma_f32_16x16x32_bf16 v[88:91], v[182:185], v[214:217], v[88:91]
	v_mfma_f32_16x16x32_bf16 v[80:83], v[190:193], v[214:217], v[80:83]
	v_mfma_f32_16x16x32_bf16 v[72:75], v[182:185], v[222:225], v[72:75]
	v_mfma_f32_16x16x32_bf16 v[64:67], v[190:193], v[222:225], v[64:67]
	s_add_i32 s30, 0, 0x1c000
	v_mfma_f32_16x16x32_bf16 v[120:123], v[186:189], v[202:205], v[120:123]
	s_add_i32 s31, s63, s34
	v_mfma_f32_16x16x32_bf16 v[112:115], v[194:197], v[202:205], v[112:115]
	v_add_u32_e32 v176, s30, v161
	v_mfma_f32_16x16x32_bf16 v[104:107], v[186:189], v[210:213], v[104:107]
	s_mov_b32 m0, s31
	v_mfma_f32_16x16x32_bf16 v[96:99], v[194:197], v[210:213], v[96:99]
	v_mfma_f32_16x16x32_bf16 v[88:91], v[186:189], v[218:221], v[88:91]
	v_mfma_f32_16x16x32_bf16 v[80:83], v[194:197], v[218:221], v[80:83]
	v_mfma_f32_16x16x32_bf16 v[72:75], v[186:189], v[226:229], v[72:75]
	v_mfma_f32_16x16x32_bf16 v[64:67], v[194:197], v[226:229], v[64:67]
	s_barrier
	s_setprio 0
	ds_read_b128 v[230:233], v176
	ds_read_b128 v[234:237], v176 offset:1024
	ds_read_b128 v[238:241], v176 offset:2048
	ds_read_b128 v[242:245], v176 offset:3072
	global_load_lds_dwordx4 v130, s[98:99]
	s_add_i32 m0, s31, 0x2000
	s_nop 0
	global_load_lds_dwordx4 v134, s[98:99]
	s_setprio 1
	s_barrier
; #define PG8_STAGE(bufoff, gbase, voff) do { _Pragma("unroll") for (int _i = 0; _i < 2; ++_i) \
;         __builtin_amdgcn_global_load_lds((const unsigned*)((const char*)(gbase) + (voff)[_i]), (LAS unsigned*)(lds + (bufoff) + ldsw + _i * 8192), 16, 0, 0); } while (0)
; #define PG8_LDA(dst, b, h) do { _Pragma("unroll") for (int m = 0; m < 4; ++m) _Pragma("unroll") for (int k = 0; k < 2; ++k) dst[m][k] = *(const LAS bf16x8*)(lds + PG8_SA(b, h) + aoff + m * 2048 + k * 1024); } while (0)
; #define PG8_MMA(ai, bj, At, Bt) do { __builtin_amdgcn_s_setprio(1); _Pragma("unroll") for (int m = 0; m < 4; ++m) _Pragma("unroll") for (int n = 0; n < 2; ++n) _Pragma("unroll") for (int k = 0; k < 2; ++k) \
;         acc[ai][bj][m][n] = __builtin_amdgcn_mfma_f32_16x16x32_bf16(Bt[n][k], At[m][k], acc[ai][bj][m][n], 0, 0, 0); __builtin_amdgcn_s_setprio(0); } while (0)
; #define PG8_WAIT_V(n) asm volatile("s_waitcnt vmcnt(" #n ")" ::: "memory")
; #define PG8_WAIT_L(n) asm volatile("s_waitcnt lgkmcnt(" #n ")" ::: "memory")
; #define PG8_BAR __builtin_amdgcn_s_barrier()
; #define PG8_SCHED __builtin_amdgcn_sched_barrier(0)
; template <class Epi, class Sched, bool ATILE = false>
; __device__ __forceinline__ void gemm_phase(LAS unsigned char* lds, const Gemm g, const Sched& S, const Epi& E) {
;     ...
;             PG8_BAR; PG8_WAIT_L(0); PG8_MMA(0, 1, At, B1); PG8_BAR;
;             PG8_LDA(At, 1, 1); PG8_STAGE(PG8_SA(1, 0), a3, voffA);
;             PG8_BAR; PG8_WAIT_L(0); PG8_MMA(1, 0, At, B0); PG8_BAR; PG8_SCHED;
;             PG8_STAGE(PG8_SB(1, 1), b3 + hstepB, voffB);
;             PG8_WAIT_V(6); PG8_BAR; PG8_MMA(1, 1, At, B1); PG8_BAR;
;         }
	s_waitcnt lgkmcnt(0)
	v_mfma_f32_16x16x32_bf16 v[124:127], v[230:233], v[198:201], v[124:127]
	v_mfma_f32_16x16x32_bf16 v[116:119], v[238:241], v[198:201], v[116:119]
	v_mfma_f32_16x16x32_bf16 v[108:111], v[230:233], v[206:209], v[108:111]
	v_mfma_f32_16x16x32_bf16 v[100:103], v[238:241], v[206:209], v[100:103]
	v_mfma_f32_16x16x32_bf16 v[92:95], v[230:233], v[214:217], v[92:95]
	v_mfma_f32_16x16x32_bf16 v[84:87], v[238:241], v[214:217], v[84:87]
	v_mfma_f32_16x16x32_bf16 v[76:79], v[230:233], v[222:225], v[76:79]
	v_mfma_f32_16x16x32_bf16 v[68:71], v[238:241], v[222:225], v[68:71]
	s_mov_b32 m0, s41
	v_mfma_f32_16x16x32_bf16 v[124:127], v[234:237], v[202:205], v[124:127]
	v_mfma_f32_16x16x32_bf16 v[116:119], v[242:245], v[202:205], v[116:119]
	v_mfma_f32_16x16x32_bf16 v[108:111], v[234:237], v[210:213], v[108:111]
	v_mfma_f32_16x16x32_bf16 v[100:103], v[242:245], v[210:213], v[100:103]
	v_mfma_f32_16x16x32_bf16 v[92:95], v[234:237], v[218:221], v[92:95]
	v_mfma_f32_16x16x32_bf16 v[84:87], v[242:245], v[218:221], v[84:87]
	v_mfma_f32_16x16x32_bf16 v[76:79], v[234:237], v[226:229], v[76:79]
	v_mfma_f32_16x16x32_bf16 v[68:71], v[242:245], v[226:229], v[68:71]
	s_barrier
	s_setprio 0
	ds_read_b128 v[198:201], v163 offset:49152
	ds_read_b128 v[202:205], v163 offset:50176
	ds_read_b128 v[206:209], v163 offset:51200
	ds_read_b128 v[210:213], v163 offset:52224
	ds_read_b128 v[214:217], v163 offset:53248
	ds_read_b128 v[218:221], v163 offset:54272
	ds_read_b128 v[222:225], v163 offset:55296
	ds_read_b128 v[226:229], v163 offset:56320
	global_load_lds_dwordx4 v128, s[100:101]
	s_mov_b32 m0, s42
	s_nop 0
	global_load_lds_dwordx4 v132, s[100:101]
	s_setprio 1
	s_barrier
	s_waitcnt lgkmcnt(0)
	v_mfma_f32_16x16x32_bf16 v[56:59], v[182:185], v[198:201], v[56:59]
	v_mfma_f32_16x16x32_bf16 v[48:51], v[190:193], v[198:201], v[48:51]
	v_mfma_f32_16x16x32_bf16 v[40:43], v[182:185], v[206:209], v[40:43]
	v_mfma_f32_16x16x32_bf16 v[32:35], v[190:193], v[206:209], v[32:35]
	v_mfma_f32_16x16x32_bf16 v[24:27], v[182:185], v[214:217], v[24:27]
	v_mfma_f32_16x16x32_bf16 v[16:19], v[190:193], v[214:217], v[16:19]
	v_mfma_f32_16x16x32_bf16 v[8:11], v[182:185], v[222:225], v[8:11]
	v_mfma_f32_16x16x32_bf16 v[4:7], v[190:193], v[222:225], v[4:7]
	s_add_u32 s28, s28, 0x80080
	v_mfma_f32_16x16x32_bf16 v[56:59], v[186:189], v[202:205], v[56:59]
	s_addc_u32 s29, s29, 0
	v_mfma_f32_16x16x32_bf16 v[48:51], v[194:197], v[202:205], v[48:51]
	s_add_i32 s30, s30, s34
	v_mfma_f32_16x16x32_bf16 v[40:43], v[186:189], v[210:213], v[40:43]
	s_mov_b32 m0, s30
	v_mfma_f32_16x16x32_bf16 v[32:35], v[194:197], v[210:213], v[32:35]
	v_mfma_f32_16x16x32_bf16 v[24:27], v[186:189], v[218:221], v[24:27]
	v_mfma_f32_16x16x32_bf16 v[16:19], v[194:197], v[218:221], v[16:19]
	v_mfma_f32_16x16x32_bf16 v[8:11], v[186:189], v[226:229], v[8:11]
	v_mfma_f32_16x16x32_bf16 v[4:7], v[194:197], v[226:229], v[4:7]
	s_barrier
	s_setprio 0
	s_nop 0
	global_load_lds_dwordx4 v130, s[28:29]
	s_add_i32 m0, s30, 0x2000
	s_nop 0
	global_load_lds_dwordx4 v134, s[28:29]
	s_waitcnt vmcnt(6)
	s_setprio 1
	s_barrier
	v_mfma_f32_16x16x32_bf16 v[60:63], v[230:233], v[198:201], v[60:63]
	v_mfma_f32_16x16x32_bf16 v[52:55], v[238:241], v[198:201], v[52:55]
	v_mfma_f32_16x16x32_bf16 v[44:47], v[230:233], v[206:209], v[44:47]
	v_mfma_f32_16x16x32_bf16 v[36:39], v[238:241], v[206:209], v[36:39]
	v_mfma_f32_16x16x32_bf16 v[28:31], v[230:233], v[214:217], v[28:31]
	v_mfma_f32_16x16x32_bf16 v[20:23], v[238:241], v[214:217], v[20:23]
	v_mfma_f32_16x16x32_bf16 v[12:15], v[230:233], v[222:225], v[12:15]
	s_add_u32 s26, s26, 0x100
	v_mfma_f32_16x16x32_bf16 v[0:3], v[238:241], v[222:225], v[0:3]
	s_addc_u32 s27, s27, 0
	v_mfma_f32_16x16x32_bf16 v[60:63], v[234:237], v[202:205], v[60:63]
	s_add_u32 s60, s60, 0x100
	v_mfma_f32_16x16x32_bf16 v[52:55], v[242:245], v[202:205], v[52:55]
	s_addc_u32 s61, s61, 0
	v_mfma_f32_16x16x32_bf16 v[44:47], v[234:237], v[210:213], v[44:47]
	s_cmp_ge_i32 s62, s11
	v_mfma_f32_16x16x32_bf16 v[36:39], v[242:245], v[210:213], v[36:39]
	s_mov_b32 s28, s62
	v_mfma_f32_16x16x32_bf16 v[28:31], v[234:237], v[218:221], v[28:31]
	v_mfma_f32_16x16x32_bf16 v[20:23], v[242:245], v[218:221], v[20:23]
	v_mfma_f32_16x16x32_bf16 v[12:15], v[234:237], v[226:229], v[12:15]
	v_mfma_f32_16x16x32_bf16 v[0:3], v[242:245], v[226:229], v[0:3]
	s_barrier
	s_setprio 0
	s_cbranch_scc0 .LBB0_625
	s_nop 5
	s_branch .LBB0_616

; #define PG8_STAGE(bufoff, gbase, voff) do { _Pragma("unroll") for (int _i = 0; _i < 2; ++_i) \
;         __builtin_amdgcn_global_load_lds((const unsigned*)((const char*)(gbase) + (voff)[_i]), (LAS unsigned*)(lds + (bufoff) + ldsw + _i * 8192), 16, 0, 0); } while (0)
; #define PG8_LDA(dst, b, h) do { _Pragma("unroll") for (int m = 0; m < 4; ++m) _Pragma("unroll") for (int k = 0; k < 2; ++k) dst[m][k] = *(const LAS bf16x8*)(lds + PG8_SA(b, h) + aoff + m * 2048 + k * 1024); } while (0)
; #define PG8_LDB(dst, b, h) do { _Pragma("unroll") for (int n = 0; n < 2; ++n) _Pragma("unroll") for (int k = 0; k < 2; ++k) dst[n][k] = *(const LAS bf16x8*)(lds + PG8_SB(b, h) + boff + n * 2048 + k * 1024); } while (0)
; #define PG8_MMA(ai, bj, At, Bt) do { __builtin_amdgcn_s_setprio(1); _Pragma("unroll") for (int m = 0; m < 4; ++m) _Pragma("unroll") for (int n = 0; n < 2; ++n) _Pragma("unroll") for (int k = 0; k < 2; ++k) \
;         acc[ai][bj][m][n] = __builtin_amdgcn_mfma_f32_16x16x32_bf16(Bt[n][k], At[m][k], acc[ai][bj][m][n], 0, 0, 0); __builtin_amdgcn_s_setprio(0); } while (0)
; #define PG8_WAIT_V(n) asm volatile("s_waitcnt vmcnt(" #n ")" ::: "memory")
; #define PG8_WAIT_L(n) asm volatile("s_waitcnt lgkmcnt(" #n ")" ::: "memory")
; template <class Epi, class Sched, bool ATILE = false>
; __device__ __forceinline__ void gemm_phase(LAS unsigned char* lds, const Gemm g, const Sched& S, const Epi& E) {
;     ...
;         for (int t = 0; t < nt; t += 2) {
;             const bool last = (t == nt - 2);
;             const char* a1 = cA + (size_t)(t + 1) * kstepA;
;             const char* a2 = last ? nA : cA + (size_t)(t + 2) * kstepA; const char* b2 = last ? nB : cB + (size_t)(t + 2) * kstep;
;             const char* a3 = a2 + kstepA; const char* b3 = b2 + kstep;
;             PG8_LDB(B0, 0, 0); PG8_SCHED; PG8_LDA(At, 0, 0); PG8_STAGE(PG8_SA(1, 1), a1 + hstepA, voffA);
;             PG8_WAIT_L(8); PG8_BAR; PG8_WAIT_L(0); PG8_MMA(0, 0, At, B0); PG8_BAR; PG8_SCHED;
;             PG8_LDB(B1, 0, 1); PG8_STAGE(PG8_SB(0, 0), b2, voffB);
;             PG8_BAR; PG8_WAIT_L(0); PG8_MMA(0, 1, At, B1); PG8_BAR;
;             PG8_LDA(At, 0, 1); PG8_STAGE(PG8_SA(0, 0), a2, voffA);
;             PG8_BAR; PG8_WAIT_L(0); PG8_MMA(1, 0, At, B0); PG8_BAR; PG8_SCHED;
;             PG8_STAGE(PG8_SB(0, 1), b2 + hstepB, voffB);
;             PG8_WAIT_V(6); PG8_BAR; PG8_MMA(1, 1, At, B1); PG8_BAR;
.LBB0_739:
	ds_read_b128 v[20:23], v165
	ds_read_b128 v[28:31], v165 offset:1024
	ds_read_b128 v[136:139], v165 offset:2048
	ds_read_b128 v[140:143], v165 offset:3072
	s_add_i32 s62, s26, 2
	s_add_u32 s27, s24, 0x4000
	s_addc_u32 s28, s25, 0
	s_cmp_eq_u32 s11, s26
	s_cselect_b32 s30, s20, s27
	s_cselect_b32 s31, s21, s28
	s_cselect_b32 s26, s22, s60
	s_cselect_b32 s27, s23, s61
	s_add_u32 s28, s30, 0x8000
	s_addc_u32 s29, s31, 0
	s_add_i32 m0, s34, 0xc000
	ds_read_b128 v[144:147], v167
	ds_read_b128 v[148:151], v167 offset:1024
	ds_read_b128 v[200:203], v167 offset:2048
	ds_read_b128 v[204:207], v167 offset:3072
	ds_read_b128 v[208:211], v167 offset:4096
	ds_read_b128 v[212:215], v167 offset:5120
	ds_read_b128 v[220:223], v167 offset:6144
	ds_read_b128 v[224:227], v167 offset:7168
	global_load_lds_dwordx4 v194, s[24:25]
	s_add_i32 m0, s34, 0xe000
	s_nop 0
	global_load_lds_dwordx4 v196, s[24:25]
	s_waitcnt lgkmcnt(8)
	s_setprio 1
	s_barrier
	s_waitcnt lgkmcnt(0)
	v_mfma_f32_16x16x32_bf16 v[0:3], v[20:23], v[144:147], v[0:3]
	v_mfma_f32_16x16x32_bf16 v[4:7], v[136:139], v[144:147], v[4:7]
	v_mfma_f32_16x16x32_bf16 v[44:47], v[20:23], v[200:203], v[44:47]
	v_mfma_f32_16x16x32_bf16 v[36:39], v[136:139], v[200:203], v[36:39]
	v_mfma_f32_16x16x32_bf16 v[52:55], v[20:23], v[208:211], v[52:55]
	v_mfma_f32_16x16x32_bf16 v[48:51], v[136:139], v[208:211], v[48:51]
	v_mfma_f32_16x16x32_bf16 v[92:95], v[20:23], v[220:223], v[92:95]
	v_mfma_f32_16x16x32_bf16 v[84:87], v[136:139], v[220:223], v[84:87]
	s_add_i32 s63, s52, s33
	v_mfma_f32_16x16x32_bf16 v[0:3], v[28:31], v[148:151], v[0:3]
	s_add_u32 s98, s26, s6
	v_mfma_f32_16x16x32_bf16 v[4:7], v[140:143], v[148:151], v[4:7]
	s_addc_u32 s99, s27, s7
	v_mfma_f32_16x16x32_bf16 v[44:47], v[28:31], v[204:207], v[44:47]
	s_mov_b32 m0, s63
	v_mfma_f32_16x16x32_bf16 v[36:39], v[140:143], v[204:207], v[36:39]
	v_mfma_f32_16x16x32_bf16 v[52:55], v[28:31], v[212:215], v[52:55]
	v_mfma_f32_16x16x32_bf16 v[48:51], v[140:143], v[212:215], v[48:51]
	v_mfma_f32_16x16x32_bf16 v[92:95], v[28:31], v[224:227], v[92:95]
	v_mfma_f32_16x16x32_bf16 v[84:87], v[140:143], v[224:227], v[84:87]
	s_barrier
	s_setprio 0
	ds_read_b128 v[228:231], v177
	ds_read_b128 v[232:235], v177 offset:1024
	ds_read_b128 v[236:239], v177 offset:2048
	ds_read_b128 v[240:243], v177 offset:3072
	global_load_lds_dwordx4 v170, s[26:27]
	s_add_i32 m0, s63, 0x2000
	s_nop 0
	global_load_lds_dwordx4 v174, s[26:27]
	s_setprio 1
	s_barrier
	s_waitcnt lgkmcnt(0)
	v_mfma_f32_16x16x32_bf16 v[12:15], v[228:231], v[144:147], v[12:15]
	v_mfma_f32_16x16x32_bf16 v[8:11], v[236:239], v[144:147], v[8:11]
	v_mfma_f32_16x16x32_bf16 v[24:27], v[228:231], v[200:203], v[24:27]
	v_mfma_f32_16x16x32_bf16 v[16:19], v[236:239], v[200:203], v[16:19]
	v_mfma_f32_16x16x32_bf16 v[40:43], v[228:231], v[208:211], v[40:43]
	v_mfma_f32_16x16x32_bf16 v[32:35], v[236:239], v[208:211], v[32:35]
	v_mfma_f32_16x16x32_bf16 v[56:59], v[228:231], v[220:223], v[56:59]
	v_mfma_f32_16x16x32_bf16 v[60:63], v[236:239], v[220:223], v[60:63]
	s_mov_b32 m0, s34
	v_mfma_f32_16x16x32_bf16 v[12:15], v[232:235], v[148:151], v[12:15]
	v_mfma_f32_16x16x32_bf16 v[8:11], v[240:243], v[148:151], v[8:11]
	v_mfma_f32_16x16x32_bf16 v[24:27], v[232:235], v[204:207], v[24:27]
	v_mfma_f32_16x16x32_bf16 v[16:19], v[240:243], v[204:207], v[16:19]
	v_mfma_f32_16x16x32_bf16 v[40:43], v[232:235], v[212:215], v[40:43]
	v_mfma_f32_16x16x32_bf16 v[32:35], v[240:243], v[212:215], v[32:35]
	v_mfma_f32_16x16x32_bf16 v[56:59], v[232:235], v[224:227], v[56:59]
	v_mfma_f32_16x16x32_bf16 v[60:63], v[240:243], v[224:227], v[60:63]
	s_barrier
	s_setprio 0
	ds_read_b128 v[144:147], v167 offset:16384
	ds_read_b128 v[148:151], v167 offset:17408
	ds_read_b128 v[200:203], v167 offset:18432
	ds_read_b128 v[204:207], v167 offset:19456
	ds_read_b128 v[208:211], v167 offset:20480
	ds_read_b128 v[212:215], v167 offset:21504
	ds_read_b128 v[220:223], v167 offset:22528
	ds_read_b128 v[224:227], v167 offset:23552
	global_load_lds_dwordx4 v168, s[30:31]
	s_mov_b32 m0, s35
	s_nop 0
	global_load_lds_dwordx4 v172, s[30:31]
	s_setprio 1
	s_barrier
	s_waitcnt lgkmcnt(0)
	v_mfma_f32_16x16x32_bf16 v[64:67], v[20:23], v[144:147], v[64:67]
	v_mfma_f32_16x16x32_bf16 v[68:71], v[136:139], v[144:147], v[68:71]
	v_mfma_f32_16x16x32_bf16 v[108:111], v[20:23], v[200:203], v[108:111]
	v_mfma_f32_16x16x32_bf16 v[100:103], v[136:139], v[200:203], v[100:103]
	v_mfma_f32_16x16x32_bf16 v[116:119], v[20:23], v[208:211], v[116:119]
	v_mfma_f32_16x16x32_bf16 v[112:115], v[136:139], v[208:211], v[112:115]
	v_mfma_f32_16x16x32_bf16 v[20:23], v[20:23], v[220:223], v[132:135]
	v_mfma_f32_16x16x32_bf16 v[64:67], v[28:31], v[148:151], v[64:67]
	s_add_u32 s64, s26, 0x158000
	v_mfma_f32_16x16x32_bf16 v[68:71], v[140:143], v[148:151], v[68:71]
	s_addc_u32 s65, s27, 0
	v_mfma_f32_16x16x32_bf16 v[108:111], v[28:31], v[204:207], v[108:111]
	s_add_i32 s63, s53, s33
	v_mfma_f32_16x16x32_bf16 v[100:103], v[140:143], v[204:207], v[100:103]
	s_mov_b32 m0, s63
	v_mfma_f32_16x16x32_bf16 v[116:119], v[28:31], v[212:215], v[116:119]
	v_mfma_f32_16x16x32_bf16 v[112:115], v[140:143], v[212:215], v[112:115]
	v_mfma_f32_16x16x32_bf16 v[20:23], v[28:31], v[224:227], v[20:23]
	v_mfma_f32_16x16x32_bf16 v[28:31], v[136:139], v[220:223], v[128:131]
	v_mfma_f32_16x16x32_bf16 v[28:31], v[140:143], v[224:227], v[28:31]
	s_barrier
	s_setprio 0
	s_nop 0
	global_load_lds_dwordx4 v170, s[64:65]
	s_add_i32 m0, s63, 0x2000
	s_nop 0
	global_load_lds_dwordx4 v174, s[64:65]
	s_waitcnt vmcnt(6)
	s_setprio 1
	s_barrier
; #define PG8_STAGE(bufoff, gbase, voff) do { _Pragma("unroll") for (int _i = 0; _i < 2; ++_i) \
;         __builtin_amdgcn_global_load_lds((const unsigned*)((const char*)(gbase) + (voff)[_i]), (LAS unsigned*)(lds + (bufoff) + ldsw + _i * 8192), 16, 0, 0); } while (0)
; #define PG8_LDA(dst, b, h) do { _Pragma("unroll") for (int m = 0; m < 4; ++m) _Pragma("unroll") for (int k = 0; k < 2; ++k) dst[m][k] = *(const LAS bf16x8*)(lds + PG8_SA(b, h) + aoff + m * 2048 + k * 1024); } while (0)
; #define PG8_LDB(dst, b, h) do { _Pragma("unroll") for (int n = 0; n < 2; ++n) _Pragma("unroll") for (int k = 0; k < 2; ++k) dst[n][k] = *(const LAS bf16x8*)(lds + PG8_SB(b, h) + boff + n * 2048 + k * 1024); } while (0)
; #define PG8_MMA(ai, bj, At, Bt) do { __builtin_amdgcn_s_setprio(1); _Pragma("unroll") for (int m = 0; m < 4; ++m) _Pragma("unroll") for (int n = 0; n < 2; ++n) _Pragma("unroll") for (int k = 0; k < 2; ++k) \
;         acc[ai][bj][m][n] = __builtin_amdgcn_mfma_f32_16x16x32_bf16(Bt[n][k], At[m][k], acc[ai][bj][m][n], 0, 0, 0); __builtin_amdgcn_s_setprio(0); } while (0)
; #define PG8_WAIT_V(n) asm volatile("s_waitcnt vmcnt(" #n ")" ::: "memory")
; #define PG8_WAIT_L(n) asm volatile("s_waitcnt lgkmcnt(" #n ")" ::: "memory")
; #define PG8_BAR __builtin_amdgcn_s_barrier()
; #define PG8_SCHED __builtin_amdgcn_sched_barrier(0)
; template <class Epi, class Sched, bool ATILE = false>
; __device__ __forceinline__ void gemm_phase(LAS unsigned char* lds, const Gemm g, const Sched& S, const Epi& E) {
;     ...
;             PG8_WAIT_V(6); PG8_BAR; PG8_MMA(1, 1, At, B1); PG8_BAR;
;             PG8_LDB(B0, 1, 0); PG8_SCHED; PG8_LDA(At, 1, 0); PG8_STAGE(PG8_SA(0, 1), a2 + hstepA, voffA);
;             PG8_WAIT_L(8); PG8_BAR; PG8_WAIT_L(0); PG8_MMA(0, 0, At, B0); PG8_BAR; PG8_SCHED;
;             PG8_LDB(B1, 1, 1); PG8_STAGE(PG8_SB(1, 0), b3, voffB);
;             PG8_BAR; PG8_WAIT_L(0); PG8_MMA(0, 1, At, B1); PG8_BAR;
;             PG8_LDA(At, 1, 1); PG8_STAGE(PG8_SA(1, 0), a3, voffA);
	v_mfma_f32_16x16x32_bf16 v[76:79], v[228:231], v[144:147], v[76:79]
	v_mfma_f32_16x16x32_bf16 v[72:75], v[236:239], v[144:147], v[72:75]
	v_mfma_f32_16x16x32_bf16 v[88:91], v[228:231], v[200:203], v[88:91]
	v_mfma_f32_16x16x32_bf16 v[80:83], v[236:239], v[200:203], v[80:83]
	v_mfma_f32_16x16x32_bf16 v[104:107], v[228:231], v[208:211], v[104:107]
	v_mfma_f32_16x16x32_bf16 v[96:99], v[236:239], v[208:211], v[96:99]
	v_mfma_f32_16x16x32_bf16 v[120:123], v[228:231], v[220:223], v[120:123]
	v_mfma_f32_16x16x32_bf16 v[124:127], v[236:239], v[220:223], v[124:127]
	s_add_i32 s63, 0, 0x18000
	v_mfma_f32_16x16x32_bf16 v[76:79], v[232:235], v[148:151], v[76:79]
	v_add_u32_e32 v140, s63, v161
	v_mfma_f32_16x16x32_bf16 v[72:75], v[240:243], v[148:151], v[72:75]
	v_mfma_f32_16x16x32_bf16 v[88:91], v[232:235], v[204:207], v[88:91]
	v_mfma_f32_16x16x32_bf16 v[80:83], v[240:243], v[204:207], v[80:83]
	v_mfma_f32_16x16x32_bf16 v[104:107], v[232:235], v[212:215], v[104:107]
	v_mfma_f32_16x16x32_bf16 v[96:99], v[240:243], v[212:215], v[96:99]
	v_mfma_f32_16x16x32_bf16 v[120:123], v[232:235], v[224:227], v[120:123]
	v_mfma_f32_16x16x32_bf16 v[124:127], v[240:243], v[224:227], v[124:127]
	s_barrier
	s_setprio 0
	ds_read_b128 v[128:131], v140
	ds_read_b128 v[132:135], v140 offset:1024
	ds_read_b128 v[136:139], v140 offset:2048
	ds_read_b128 v[140:143], v140 offset:3072
	s_add_u32 s30, s30, 0x4000
	s_addc_u32 s31, s31, 0
	s_mov_b32 m0, s36
	ds_read_b128 v[144:147], v167 offset:32768
	ds_read_b128 v[148:151], v167 offset:33792
	ds_read_b128 v[200:203], v167 offset:34816
	ds_read_b128 v[204:207], v167 offset:35840
	ds_read_b128 v[208:211], v167 offset:36864
	ds_read_b128 v[212:215], v167 offset:37888
	ds_read_b128 v[220:223], v167 offset:38912
	ds_read_b128 v[224:227], v167 offset:39936
	global_load_lds_dwordx4 v168, s[30:31]
	s_mov_b32 m0, s37
	s_nop 0
	global_load_lds_dwordx4 v172, s[30:31]
	s_waitcnt lgkmcnt(8)
	s_setprio 1
	s_barrier
	s_waitcnt lgkmcnt(0)
	v_mfma_f32_16x16x32_bf16 v[0:3], v[128:131], v[144:147], v[0:3]
	v_mfma_f32_16x16x32_bf16 v[4:7], v[136:139], v[144:147], v[4:7]
	v_mfma_f32_16x16x32_bf16 v[44:47], v[128:131], v[200:203], v[44:47]
	v_mfma_f32_16x16x32_bf16 v[36:39], v[136:139], v[200:203], v[36:39]
	v_mfma_f32_16x16x32_bf16 v[52:55], v[128:131], v[208:211], v[52:55]
	v_mfma_f32_16x16x32_bf16 v[48:51], v[136:139], v[208:211], v[48:51]
	v_mfma_f32_16x16x32_bf16 v[92:95], v[128:131], v[220:223], v[92:95]
	v_mfma_f32_16x16x32_bf16 v[84:87], v[136:139], v[220:223], v[84:87]
	s_add_i32 s30, 0, 0x1c000
	v_mfma_f32_16x16x32_bf16 v[0:3], v[132:135], v[148:151], v[0:3]
	s_add_i32 s31, s63, s33
	v_mfma_f32_16x16x32_bf16 v[4:7], v[140:143], v[148:151], v[4:7]
	v_add_u32_e32 v219, s30, v161
	v_mfma_f32_16x16x32_bf16 v[44:47], v[132:135], v[204:207], v[44:47]
	s_mov_b32 m0, s31
	v_mfma_f32_16x16x32_bf16 v[36:39], v[140:143], v[204:207], v[36:39]
	v_mfma_f32_16x16x32_bf16 v[52:55], v[132:135], v[212:215], v[52:55]
	v_mfma_f32_16x16x32_bf16 v[48:51], v[140:143], v[212:215], v[48:51]
	v_mfma_f32_16x16x32_bf16 v[92:95], v[132:135], v[224:227], v[92:95]
	v_mfma_f32_16x16x32_bf16 v[84:87], v[140:143], v[224:227], v[84:87]
	s_barrier
	s_setprio 0
	ds_read_b128 v[228:231], v219
	ds_read_b128 v[232:235], v219 offset:1024
	ds_read_b128 v[236:239], v219 offset:2048
	ds_read_b128 v[240:243], v219 offset:3072
	global_load_lds_dwordx4 v170, s[98:99]
	s_add_i32 m0, s31, 0x2000
	s_nop 0
	global_load_lds_dwordx4 v174, s[98:99]
	s_setprio 1
	s_barrier
	s_waitcnt lgkmcnt(0)
	v_mfma_f32_16x16x32_bf16 v[12:15], v[228:231], v[144:147], v[12:15]
	v_mfma_f32_16x16x32_bf16 v[8:11], v[236:239], v[144:147], v[8:11]
	v_mfma_f32_16x16x32_bf16 v[24:27], v[228:231], v[200:203], v[24:27]
	v_mfma_f32_16x16x32_bf16 v[16:19], v[236:239], v[200:203], v[16:19]
	v_mfma_f32_16x16x32_bf16 v[40:43], v[228:231], v[208:211], v[40:43]
	v_mfma_f32_16x16x32_bf16 v[32:35], v[236:239], v[208:211], v[32:35]
	v_mfma_f32_16x16x32_bf16 v[56:59], v[228:231], v[220:223], v[56:59]
	v_mfma_f32_16x16x32_bf16 v[60:63], v[236:239], v[220:223], v[60:63]
	s_mov_b32 m0, s39
	v_mfma_f32_16x16x32_bf16 v[12:15], v[232:235], v[148:151], v[12:15]
	v_mfma_f32_16x16x32_bf16 v[8:11], v[240:243], v[148:151], v[8:11]
	v_mfma_f32_16x16x32_bf16 v[24:27], v[232:235], v[204:207], v[24:27]
	v_mfma_f32_16x16x32_bf16 v[16:19], v[240:243], v[204:207], v[16:19]
	v_mfma_f32_16x16x32_bf16 v[40:43], v[232:235], v[212:215], v[40:43]
	v_mfma_f32_16x16x32_bf16 v[32:35], v[240:243], v[212:215], v[32:35]
	v_mfma_f32_16x16x32_bf16 v[56:59], v[232:235], v[224:227], v[56:59]
	v_mfma_f32_16x16x32_bf16 v[60:63], v[240:243], v[224:227], v[60:63]
	s_barrier
	s_setprio 0
	ds_read_b128 v[144:147], v167 offset:49152
	ds_read_b128 v[148:151], v167 offset:50176
	ds_read_b128 v[200:203], v167 offset:51200
	ds_read_b128 v[204:207], v167 offset:52224
	ds_read_b128 v[208:211], v167 offset:53248
	ds_read_b128 v[212:215], v167 offset:54272
	ds_read_b128 v[220:223], v167 offset:55296
	ds_read_b128 v[224:227], v167 offset:56320
	global_load_lds_dwordx4 v168, s[28:29]
	s_mov_b32 m0, s40
	s_nop 0
	global_load_lds_dwordx4 v172, s[28:29]
	s_setprio 1
	s_barrier
; __device__ __forceinline__ float bflo(unsigned w) { return __uint_as_float(w << 16); }
; __device__ __forceinline__ float bfhi(unsigned w) { return __uint_as_float(w & 0xffff0000u); }
; #define PG8_STAGE(bufoff, gbase, voff) do { _Pragma("unroll") for (int _i = 0; _i < 2; ++_i) \
;         __builtin_amdgcn_global_load_lds((const unsigned*)((const char*)(gbase) + (voff)[_i]), (LAS unsigned*)(lds + (bufoff) + ldsw + _i * 8192), 16, 0, 0); } while (0)
; #define PG8_LDA(dst, b, h) do { _Pragma("unroll") for (int m = 0; m < 4; ++m) _Pragma("unroll") for (int k = 0; k < 2; ++k) dst[m][k] = *(const LAS bf16x8*)(lds + PG8_SA(b, h) + aoff + m * 2048 + k * 1024); } while (0)
; #define PG8_MMA(ai, bj, At, Bt) do { __builtin_amdgcn_s_setprio(1); _Pragma("unroll") for (int m = 0; m < 4; ++m) _Pragma("unroll") for (int n = 0; n < 2; ++n) _Pragma("unroll") for (int k = 0; k < 2; ++k) \
;         acc[ai][bj][m][n] = __builtin_amdgcn_mfma_f32_16x16x32_bf16(Bt[n][k], At[m][k], acc[ai][bj][m][n], 0, 0, 0); __builtin_amdgcn_s_setprio(0); } while (0)
; #define PG8_WAIT_V(n) asm volatile("s_waitcnt vmcnt(" #n ")" ::: "memory")
; #define PG8_WAIT_L(n) asm volatile("s_waitcnt lgkmcnt(" #n ")" ::: "memory")
; #define PG8_BAR __builtin_amdgcn_s_barrier()
; #define PG8_SCHED __builtin_amdgcn_sched_barrier(0)
; template <class Epi, class Sched, bool ATILE = false>
; __device__ __forceinline__ void gemm_phase(LAS unsigned char* lds, const Gemm g, const Sched& S, const Epi& E) {
;     ...
;             PG8_LDA(At, 1, 1); PG8_STAGE(PG8_SA(1, 0), a3, voffA);
;             PG8_BAR; PG8_WAIT_L(0); PG8_MMA(1, 0, At, B0); PG8_BAR; PG8_SCHED;
;             PG8_STAGE(PG8_SB(1, 1), b3 + hstepB, voffB);
;             PG8_WAIT_V(6); PG8_BAR; PG8_MMA(1, 1, At, B1); PG8_BAR;
;         }
;     __device__ __forceinline__ void operator()(const f32x4 (&acc)[2][2][4][2], const Unit& u, int wr, int wc, int fr, int fq) const {
;     ...
;                     const f32x4 v0 = (f32x4){bflo(x.x), bfhi(x.x), bflo(x.y), bfhi(x.y)} + alpha * acc[ai][bj][m][0];
;                     const f32x4 v1 = (f32x4){bflo(x.z), bfhi(x.z), bflo(x.w), bfhi(x.w)} + alpha * acc[ai][bj][m][1];
	s_waitcnt lgkmcnt(0)
	v_mfma_f32_16x16x32_bf16 v[64:67], v[128:131], v[144:147], v[64:67]
	v_mfma_f32_16x16x32_bf16 v[108:111], v[128:131], v[200:203], v[108:111]
	v_mfma_f32_16x16x32_bf16 v[116:119], v[128:131], v[208:211], v[116:119]
	v_mfma_f32_16x16x32_bf16 v[20:23], v[128:131], v[220:223], v[20:23]
	v_mfma_f32_16x16x32_bf16 v[64:67], v[132:135], v[148:151], v[64:67]
	v_mfma_f32_16x16x32_bf16 v[68:71], v[136:139], v[144:147], v[68:71]
	v_mfma_f32_16x16x32_bf16 v[108:111], v[132:135], v[204:207], v[108:111]
	v_mfma_f32_16x16x32_bf16 v[100:103], v[136:139], v[200:203], v[100:103]
	s_add_u32 s26, s26, 0x158080
	v_mfma_f32_16x16x32_bf16 v[116:119], v[132:135], v[212:215], v[116:119]
	s_addc_u32 s27, s27, 0
	v_mfma_f32_16x16x32_bf16 v[112:115], v[136:139], v[208:211], v[112:115]
	s_add_i32 s28, s30, s33
	v_mfma_f32_16x16x32_bf16 v[132:135], v[132:135], v[224:227], v[20:23]
	s_mov_b32 m0, s28
	v_mfma_f32_16x16x32_bf16 v[20:23], v[136:139], v[220:223], v[28:31]
	v_mfma_f32_16x16x32_bf16 v[68:71], v[140:143], v[148:151], v[68:71]
	v_mfma_f32_16x16x32_bf16 v[100:103], v[140:143], v[204:207], v[100:103]
	v_mfma_f32_16x16x32_bf16 v[112:115], v[140:143], v[212:215], v[112:115]
	v_mfma_f32_16x16x32_bf16 v[128:131], v[140:143], v[224:227], v[20:23]
	s_barrier
	s_setprio 0
	s_nop 0
	global_load_lds_dwordx4 v170, s[26:27]
	s_add_i32 m0, s28, 0x2000
	s_nop 0
	global_load_lds_dwordx4 v174, s[26:27]
	s_waitcnt vmcnt(6)
	s_setprio 1
	s_barrier
	v_mfma_f32_16x16x32_bf16 v[20:23], v[228:231], v[144:147], v[76:79]
	v_mfma_f32_16x16x32_bf16 v[76:79], v[232:235], v[148:151], v[20:23]
	v_mfma_f32_16x16x32_bf16 v[20:23], v[236:239], v[144:147], v[72:75]
	v_mfma_f32_16x16x32_bf16 v[72:75], v[240:243], v[148:151], v[20:23]
	v_mfma_f32_16x16x32_bf16 v[20:23], v[228:231], v[200:203], v[88:91]
	v_mfma_f32_16x16x32_bf16 v[88:91], v[232:235], v[204:207], v[20:23]
	v_mfma_f32_16x16x32_bf16 v[20:23], v[236:239], v[200:203], v[80:83]
	s_add_u32 s60, s60, 0x100
	v_mfma_f32_16x16x32_bf16 v[80:83], v[240:243], v[204:207], v[20:23]
	s_addc_u32 s61, s61, 0
	v_mfma_f32_16x16x32_bf16 v[20:23], v[228:231], v[208:211], v[104:107]
	s_add_u32 s24, s24, 0x10000
	v_mfma_f32_16x16x32_bf16 v[104:107], v[232:235], v[212:215], v[20:23]
	s_addc_u32 s25, s25, 0
	v_mfma_f32_16x16x32_bf16 v[20:23], v[236:239], v[208:211], v[96:99]
	s_cmp_ge_i32 s62, s59
	v_mfma_f32_16x16x32_bf16 v[96:99], v[240:243], v[212:215], v[20:23]
	s_mov_b32 s26, s62
	v_mfma_f32_16x16x32_bf16 v[20:23], v[228:231], v[220:223], v[120:123]
	v_mfma_f32_16x16x32_bf16 v[120:123], v[232:235], v[224:227], v[20:23]
	v_mfma_f32_16x16x32_bf16 v[20:23], v[236:239], v[220:223], v[124:127]
	v_mfma_f32_16x16x32_bf16 v[124:127], v[240:243], v[224:227], v[20:23]
	s_barrier
	s_setprio 0
	s_cbranch_scc0 .LBB0_739
	s_nop 5
	v_pk_mul_f32 v[2:3], v[2:3], 0.5 op_sel_hi:[1,0]
	v_pk_mul_f32 v[0:1], v[0:1], 0.5 op_sel_hi:[1,0]
	v_pk_mul_f32 v[6:7], v[6:7], 0.5 op_sel_hi:[1,0]
	v_pk_mul_f32 v[4:5], v[4:5], 0.5 op_sel_hi:[1,0]
	v_pk_mul_f32 v[22:23], v[14:15], 0.5 op_sel_hi:[1,0]
	v_pk_mul_f32 v[20:21], v[12:13], 0.5 op_sel_hi:[1,0]
	v_pk_mul_f32 v[30:31], v[10:11], 0.5 op_sel_hi:[1,0]
	v_pk_mul_f32 v[28:29], v[8:9], 0.5 op_sel_hi:[1,0]
	v_pk_mul_f32 v[10:11], v[46:47], 0.5 op_sel_hi:[1,0]
	v_pk_mul_f32 v[8:9], v[44:45], 0.5 op_sel_hi:[1,0]
	v_pk_mul_f32 v[14:15], v[38:39], 0.5 op_sel_hi:[1,0]
	v_pk_mul_f32 v[12:13], v[36:37], 0.5 op_sel_hi:[1,0]
	v_pk_mul_f32 v[38:39], v[26:27], 0.5 op_sel_hi:[1,0]
	v_pk_mul_f32 v[36:37], v[24:25], 0.5 op_sel_hi:[1,0]
	v_pk_mul_f32 v[46:47], v[18:19], 0.5 op_sel_hi:[1,0]
	v_pk_mul_f32 v[44:45], v[16:17], 0.5 op_sel_hi:[1,0]
	v_pk_mul_f32 v[18:19], v[54:55], 0.5 op_sel_hi:[1,0]
	v_pk_mul_f32 v[16:17], v[52:53], 0.5 op_sel_hi:[1,0]
	v_pk_mul_f32 v[26:27], v[50:51], 0.5 op_sel_hi:[1,0]
	v_pk_mul_f32 v[24:25], v[48:49], 0.5 op_sel_hi:[1,0]
	v_pk_mul_f32 v[50:51], v[42:43], 0.5 op_sel_hi:[1,0]
	v_pk_mul_f32 v[48:49], v[40:41], 0.5 op_sel_hi:[1,0]
	v_pk_mul_f32 v[54:55], v[34:35], 0.5 op_sel_hi:[1,0]
	v_pk_mul_f32 v[52:53], v[32:33], 0.5 op_sel_hi:[1,0]
	v_pk_mul_f32 v[34:35], v[94:95], 0.5 op_sel_hi:[1,0]
	v_pk_mul_f32 v[32:33], v[92:93], 0.5 op_sel_hi:[1,0]
	v_pk_mul_f32 v[42:43], v[86:87], 0.5 op_sel_hi:[1,0]
	v_pk_mul_f32 v[40:41], v[84:85], 0.5 op_sel_hi:[1,0]
	v_pk_mul_f32 v[58:59], v[58:59], 0.5 op_sel_hi:[1,0]
	v_pk_mul_f32 v[56:57], v[56:57], 0.5 op_sel_hi:[1,0]
	v_pk_mul_f32 v[62:63], v[62:63], 0.5 op_sel_hi:[1,0]
	v_pk_mul_f32 v[60:61], v[60:61], 0.5 op_sel_hi:[1,0]
	v_pk_mul_f32 v[66:67], v[66:67], 0.5 op_sel_hi:[1,0]
	v_pk_mul_f32 v[64:65], v[64:65], 0.5 op_sel_hi:[1,0]
	v_pk_mul_f32 v[70:71], v[70:71], 0.5 op_sel_hi:[1,0]
	v_pk_mul_f32 v[68:69], v[68:69], 0.5 op_sel_hi:[1,0]
	v_pk_mul_f32 v[86:87], v[78:79], 0.5 op_sel_hi:[1,0]
	v_pk_mul_f32 v[84:85], v[76:77], 0.5 op_sel_hi:[1,0]
	v_pk_mul_f32 v[94:95], v[74:75], 0.5 op_sel_hi:[1,0]
	v_pk_mul_f32 v[92:93], v[72:73], 0.5 op_sel_hi:[1,0]
	v_pk_mul_f32 v[74:75], v[110:111], 0.5 op_sel_hi:[1,0]
	v_pk_mul_f32 v[72:73], v[108:109], 0.5 op_sel_hi:[1,0]
	v_pk_mul_f32 v[78:79], v[102:103], 0.5 op_sel_hi:[1,0]
	v_pk_mul_f32 v[76:77], v[100:101], 0.5 op_sel_hi:[1,0]
	v_pk_mul_f32 v[102:103], v[90:91], 0.5 op_sel_hi:[1,0]
	v_pk_mul_f32 v[100:101], v[88:89], 0.5 op_sel_hi:[1,0]
	v_pk_mul_f32 v[110:111], v[82:83], 0.5 op_sel_hi:[1,0]
	v_pk_mul_f32 v[108:109], v[80:81], 0.5 op_sel_hi:[1,0]
	v_pk_mul_f32 v[82:83], v[118:119], 0.5 op_sel_hi:[1,0]
	v_pk_mul_f32 v[80:81], v[116:117], 0.5 op_sel_hi:[1,0]
	v_pk_mul_f32 v[90:91], v[114:115], 0.5 op_sel_hi:[1,0]
	v_pk_mul_f32 v[88:89], v[112:113], 0.5 op_sel_hi:[1,0]
	v_pk_mul_f32 v[114:115], v[106:107], 0.5 op_sel_hi:[1,0]
	v_pk_mul_f32 v[112:113], v[104:105], 0.5 op_sel_hi:[1,0]
	v_pk_mul_f32 v[118:119], v[98:99], 0.5 op_sel_hi:[1,0]
	v_pk_mul_f32 v[116:117], v[96:97], 0.5 op_sel_hi:[1,0]
	v_pk_mul_f32 v[98:99], v[134:135], 0.5 op_sel_hi:[1,0]
	v_pk_mul_f32 v[96:97], v[132:133], 0.5 op_sel_hi:[1,0]
	v_pk_mul_f32 v[106:107], v[130:131], 0.5 op_sel_hi:[1,0]
	v_pk_mul_f32 v[104:105], v[128:129], 0.5 op_sel_hi:[1,0]
	v_pk_mul_f32 v[122:123], v[122:123], 0.5 op_sel_hi:[1,0]
	v_pk_mul_f32 v[120:121], v[120:121], 0.5 op_sel_hi:[1,0]
	v_pk_mul_f32 v[126:127], v[126:127], 0.5 op_sel_hi:[1,0]
	v_pk_mul_f32 v[124:125], v[124:125], 0.5 op_sel_hi:[1,0]
	s_branch .LBB0_744

; #define PG8_STAGE(bufoff, gbase, voff) do { _Pragma("unroll") for (int _i = 0; _i < 2; ++_i) \
;         __builtin_amdgcn_global_load_lds((const unsigned*)((const char*)(gbase) + (voff)[_i]), (LAS unsigned*)(lds + (bufoff) + ldsw + _i * 8192), 16, 0, 0); } while (0)
; #define PG8_LDA(dst, b, h) do { _Pragma("unroll") for (int m = 0; m < 4; ++m) _Pragma("unroll") for (int k = 0; k < 2; ++k) dst[m][k] = *(const LAS bf16x8*)(lds + PG8_SA(b, h) + aoff + m * 2048 + k * 1024); } while (0)
; #define PG8_LDB(dst, b, h) do { _Pragma("unroll") for (int n = 0; n < 2; ++n) _Pragma("unroll") for (int k = 0; k < 2; ++k) dst[n][k] = *(const LAS bf16x8*)(lds + PG8_SB(b, h) + boff + n * 2048 + k * 1024); } while (0)
; #define PG8_MMA(ai, bj, At, Bt) do { __builtin_amdgcn_s_setprio(1); _Pragma("unroll") for (int m = 0; m < 4; ++m) _Pragma("unroll") for (int n = 0; n < 2; ++n) _Pragma("unroll") for (int k = 0; k < 2; ++k) \
;         acc[ai][bj][m][n] = __builtin_amdgcn_mfma_f32_16x16x32_bf16(Bt[n][k], At[m][k], acc[ai][bj][m][n], 0, 0, 0); __builtin_amdgcn_s_setprio(0); } while (0)
; #define PG8_WAIT_V(n) asm volatile("s_waitcnt vmcnt(" #n ")" ::: "memory")
; #define PG8_WAIT_L(n) asm volatile("s_waitcnt lgkmcnt(" #n ")" ::: "memory")
; template <class Epi, class Sched, bool ATILE = false>
; __device__ __forceinline__ void gemm_phase(LAS unsigned char* lds, const Gemm g, const Sched& S, const Epi& E) {
;     ...
;         for (int t = 0; t < nt; t += 2) {
;             const bool last = (t == nt - 2);
;             const char* a1 = cA + (size_t)(t + 1) * kstepA;
;             const char* a2 = last ? nA : cA + (size_t)(t + 2) * kstepA; const char* b2 = last ? nB : cB + (size_t)(t + 2) * kstep;
;             const char* a3 = a2 + kstepA; const char* b3 = b2 + kstep;
;             PG8_LDB(B0, 0, 0); PG8_SCHED; PG8_LDA(At, 0, 0); PG8_STAGE(PG8_SA(1, 1), a1 + hstepA, voffA);
;             PG8_WAIT_L(8); PG8_BAR; PG8_WAIT_L(0); PG8_MMA(0, 0, At, B0); PG8_BAR; PG8_SCHED;
;             PG8_LDB(B1, 0, 1); PG8_STAGE(PG8_SB(0, 0), b2, voffB);
;             PG8_BAR; PG8_WAIT_L(0); PG8_MMA(0, 1, At, B1); PG8_BAR;
;             PG8_LDA(At, 0, 1); PG8_STAGE(PG8_SA(0, 0), a2, voffA);
;             PG8_BAR; PG8_WAIT_L(0); PG8_MMA(1, 0, At, B0); PG8_BAR; PG8_SCHED;
;             PG8_STAGE(PG8_SB(0, 1), b2 + hstepB, voffB);
;             PG8_WAIT_V(6); PG8_BAR; PG8_MMA(1, 1, At, B1); PG8_BAR;
.LBB0_895:
	ds_read_b128 v[32:35], v165
	ds_read_b128 v[36:39], v165 offset:1024
	ds_read_b128 v[178:181], v165 offset:2048
	ds_read_b128 v[182:185], v165 offset:3072
	s_add_i32 s88, s73, 2
	s_add_u32 s84, s12, 0xfff80080
	s_addc_u32 s85, s13, -1
	s_cmp_eq_u32 s53, s73
	s_cselect_b32 s87, s11, s85
	s_cselect_b32 s86, s20, s84
	s_cselect_b32 s85, s41, s63
	s_cselect_b32 s84, s52, s62
	s_add_i32 m0, s35, 0xc000
	ds_read_b128 v[192:195], v167
	ds_read_b128 v[196:199], v167 offset:1024
	ds_read_b128 v[200:203], v167 offset:2048
	ds_read_b128 v[204:207], v167 offset:3072
	ds_read_b128 v[208:211], v167 offset:4096
	ds_read_b128 v[212:215], v167 offset:5120
	ds_read_b128 v[216:219], v167 offset:6144
	ds_read_b128 v[220:223], v167 offset:7168
	global_load_lds_dwordx4 v170, s[12:13]
	s_add_i32 m0, s35, 0xe000
	s_nop 0
	global_load_lds_dwordx4 v172, s[12:13]
	s_waitcnt lgkmcnt(8)
	s_setprio 1
	s_barrier
	s_waitcnt lgkmcnt(0)
	v_mfma_f32_16x16x32_bf16 v[132:135], v[32:35], v[192:195], v[132:135]
	v_mfma_f32_16x16x32_bf16 v[128:131], v[178:181], v[192:195], v[128:131]
	v_mfma_f32_16x16x32_bf16 v[116:119], v[32:35], v[200:203], v[116:119]
	v_mfma_f32_16x16x32_bf16 v[112:115], v[178:181], v[200:203], v[112:115]
	v_mfma_f32_16x16x32_bf16 v[100:103], v[32:35], v[208:211], v[100:103]
	v_mfma_f32_16x16x32_bf16 v[96:99], v[178:181], v[208:211], v[96:99]
	v_mfma_f32_16x16x32_bf16 v[84:87], v[32:35], v[216:219], v[84:87]
	v_mfma_f32_16x16x32_bf16 v[80:83], v[178:181], v[216:219], v[80:83]
	s_add_i32 s73, s43, s31
	v_mfma_f32_16x16x32_bf16 v[132:135], v[36:39], v[196:199], v[132:135]
	s_add_u32 s98, s84, s22
	v_mfma_f32_16x16x32_bf16 v[128:131], v[182:185], v[196:199], v[128:131]
	s_addc_u32 s99, s85, s23
	v_mfma_f32_16x16x32_bf16 v[116:119], v[36:39], v[204:207], v[116:119]
	s_mov_b32 m0, s73
	v_mfma_f32_16x16x32_bf16 v[112:115], v[182:185], v[204:207], v[112:115]
	v_mfma_f32_16x16x32_bf16 v[100:103], v[36:39], v[212:215], v[100:103]
	v_mfma_f32_16x16x32_bf16 v[96:99], v[182:185], v[212:215], v[96:99]
	v_mfma_f32_16x16x32_bf16 v[84:87], v[36:39], v[220:223], v[84:87]
	v_mfma_f32_16x16x32_bf16 v[80:83], v[182:185], v[220:223], v[80:83]
	s_barrier
	s_setprio 0
	ds_read_b128 v[224:227], v186
	ds_read_b128 v[228:231], v186 offset:1024
	ds_read_b128 v[232:235], v186 offset:2048
	ds_read_b128 v[236:239], v186 offset:3072
	global_load_lds_dwordx4 v138, s[84:85]
	s_add_i32 m0, s73, 0x2000
	s_nop 0
	global_load_lds_dwordx4 v142, s[84:85]
	s_setprio 1
	s_barrier
	s_waitcnt lgkmcnt(0)
	v_mfma_f32_16x16x32_bf16 v[124:127], v[224:227], v[192:195], v[124:127]
	v_mfma_f32_16x16x32_bf16 v[120:123], v[232:235], v[192:195], v[120:123]
	v_mfma_f32_16x16x32_bf16 v[108:111], v[224:227], v[200:203], v[108:111]
	v_mfma_f32_16x16x32_bf16 v[104:107], v[232:235], v[200:203], v[104:107]
	v_mfma_f32_16x16x32_bf16 v[92:95], v[224:227], v[208:211], v[92:95]
	v_mfma_f32_16x16x32_bf16 v[88:91], v[232:235], v[208:211], v[88:91]
	v_mfma_f32_16x16x32_bf16 v[76:79], v[224:227], v[216:219], v[76:79]
	v_mfma_f32_16x16x32_bf16 v[72:75], v[232:235], v[216:219], v[72:75]
	s_mov_b32 m0, s35
	v_mfma_f32_16x16x32_bf16 v[124:127], v[228:231], v[196:199], v[124:127]
	s_add_u32 s100, s86, s22
	v_mfma_f32_16x16x32_bf16 v[120:123], v[236:239], v[196:199], v[120:123]
	s_addc_u32 s101, s87, s23
	v_mfma_f32_16x16x32_bf16 v[108:111], v[228:231], v[204:207], v[108:111]
	v_mfma_f32_16x16x32_bf16 v[104:107], v[236:239], v[204:207], v[104:107]
	v_mfma_f32_16x16x32_bf16 v[92:95], v[228:231], v[212:215], v[92:95]
	v_mfma_f32_16x16x32_bf16 v[88:91], v[236:239], v[212:215], v[88:91]
	v_mfma_f32_16x16x32_bf16 v[76:79], v[228:231], v[220:223], v[76:79]
	v_mfma_f32_16x16x32_bf16 v[72:75], v[236:239], v[220:223], v[72:75]
	s_barrier
	s_setprio 0
	ds_read_b128 v[192:195], v167 offset:16384
	ds_read_b128 v[196:199], v167 offset:17408
	ds_read_b128 v[200:203], v167 offset:18432
	ds_read_b128 v[204:207], v167 offset:19456
	ds_read_b128 v[208:211], v167 offset:20480
	ds_read_b128 v[212:215], v167 offset:21504
	ds_read_b128 v[216:219], v167 offset:22528
	ds_read_b128 v[220:223], v167 offset:23552
	global_load_lds_dwordx4 v136, s[86:87]
	s_mov_b32 m0, s37
	s_nop 0
	global_load_lds_dwordx4 v140, s[86:87]
	s_setprio 1
	s_barrier
	s_waitcnt lgkmcnt(0)
	v_mfma_f32_16x16x32_bf16 v[68:71], v[32:35], v[192:195], v[68:71]
	v_mfma_f32_16x16x32_bf16 v[64:67], v[178:181], v[192:195], v[64:67]
	v_mfma_f32_16x16x32_bf16 v[52:55], v[32:35], v[200:203], v[52:55]
	v_mfma_f32_16x16x32_bf16 v[48:51], v[178:181], v[200:203], v[48:51]
	v_mfma_f32_16x16x32_bf16 v[28:31], v[32:35], v[208:211], v[28:31]
	v_mfma_f32_16x16x32_bf16 v[24:27], v[178:181], v[208:211], v[24:27]
	v_mfma_f32_16x16x32_bf16 v[12:15], v[32:35], v[216:219], v[12:15]
	v_mfma_f32_16x16x32_bf16 v[8:11], v[178:181], v[216:219], v[8:11]
	s_add_u32 vcc_lo, s84, 0x80000
	v_mfma_f32_16x16x32_bf16 v[68:71], v[36:39], v[196:199], v[68:71]
	s_addc_u32 vcc_hi, s85, 0
	v_mfma_f32_16x16x32_bf16 v[64:67], v[182:185], v[196:199], v[64:67]
	s_add_i32 s73, s56, s31
	v_mfma_f32_16x16x32_bf16 v[52:55], v[36:39], v[204:207], v[52:55]
	v_mfma_f32_16x16x32_bf16 v[48:51], v[182:185], v[204:207], v[48:51]
	v_mfma_f32_16x16x32_bf16 v[28:31], v[36:39], v[212:215], v[28:31]
	v_mfma_f32_16x16x32_bf16 v[24:27], v[182:185], v[212:215], v[24:27]
	v_mfma_f32_16x16x32_bf16 v[12:15], v[36:39], v[220:223], v[12:15]
	v_mfma_f32_16x16x32_bf16 v[8:11], v[182:185], v[220:223], v[8:11]
	s_barrier
	s_setprio 0
	v_lshl_add_u64 v[32:33], vcc, 0, v[138:139]
	s_mov_b32 m0, s73
	s_nop 0
	global_load_lds_dwordx4 v[32:33], off
	v_lshl_add_u64 v[32:33], vcc, 0, v[142:143]
	s_add_i32 m0, s73, 0x2000
	s_nop 0
	global_load_lds_dwordx4 v[32:33], off
	s_waitcnt vmcnt(6)
	s_setprio 1
	s_barrier
; #define PG8_STAGE(bufoff, gbase, voff) do { _Pragma("unroll") for (int _i = 0; _i < 2; ++_i) \
;         __builtin_amdgcn_global_load_lds((const unsigned*)((const char*)(gbase) + (voff)[_i]), (LAS unsigned*)(lds + (bufoff) + ldsw + _i * 8192), 16, 0, 0); } while (0)
; #define PG8_LDA(dst, b, h) do { _Pragma("unroll") for (int m = 0; m < 4; ++m) _Pragma("unroll") for (int k = 0; k < 2; ++k) dst[m][k] = *(const LAS bf16x8*)(lds + PG8_SA(b, h) + aoff + m * 2048 + k * 1024); } while (0)
; #define PG8_LDB(dst, b, h) do { _Pragma("unroll") for (int n = 0; n < 2; ++n) _Pragma("unroll") for (int k = 0; k < 2; ++k) dst[n][k] = *(const LAS bf16x8*)(lds + PG8_SB(b, h) + boff + n * 2048 + k * 1024); } while (0)
; #define PG8_MMA(ai, bj, At, Bt) do { __builtin_amdgcn_s_setprio(1); _Pragma("unroll") for (int m = 0; m < 4; ++m) _Pragma("unroll") for (int n = 0; n < 2; ++n) _Pragma("unroll") for (int k = 0; k < 2; ++k) \
;         acc[ai][bj][m][n] = __builtin_amdgcn_mfma_f32_16x16x32_bf16(Bt[n][k], At[m][k], acc[ai][bj][m][n], 0, 0, 0); __builtin_amdgcn_s_setprio(0); } while (0)
; #define PG8_WAIT_V(n) asm volatile("s_waitcnt vmcnt(" #n ")" ::: "memory")
; #define PG8_WAIT_L(n) asm volatile("s_waitcnt lgkmcnt(" #n ")" ::: "memory")
; #define PG8_BAR __builtin_amdgcn_s_barrier()
; #define PG8_SCHED __builtin_amdgcn_sched_barrier(0)
; template <class Epi, class Sched, bool ATILE = false>
; __device__ __forceinline__ void gemm_phase(LAS unsigned char* lds, const Gemm g, const Sched& S, const Epi& E) {
;     ...
;             PG8_WAIT_V(6); PG8_BAR; PG8_MMA(1, 1, At, B1); PG8_BAR;
;             PG8_LDB(B0, 1, 0); PG8_SCHED; PG8_LDA(At, 1, 0); PG8_STAGE(PG8_SA(0, 1), a2 + hstepA, voffA);
;             PG8_WAIT_L(8); PG8_BAR; PG8_WAIT_L(0); PG8_MMA(0, 0, At, B0); PG8_BAR; PG8_SCHED;
;             PG8_LDB(B1, 1, 1); PG8_STAGE(PG8_SB(1, 0), b3, voffB);
;             PG8_BAR; PG8_WAIT_L(0); PG8_MMA(0, 1, At, B1); PG8_BAR;
	v_mfma_f32_16x16x32_bf16 v[44:47], v[224:227], v[200:203], v[44:47]
	v_mfma_f32_16x16x32_bf16 v[40:43], v[232:235], v[200:203], v[40:43]
	v_mfma_f32_16x16x32_bf16 v[20:23], v[224:227], v[208:211], v[20:23]
	v_mfma_f32_16x16x32_bf16 v[16:19], v[232:235], v[208:211], v[16:19]
	v_mfma_f32_16x16x32_bf16 v[4:7], v[224:227], v[216:219], v[4:7]
	v_mfma_f32_16x16x32_bf16 v[0:3], v[232:235], v[216:219], v[0:3]
	v_mfma_f32_16x16x32_bf16 v[32:35], v[224:227], v[192:195], v[60:63]
	v_mfma_f32_16x16x32_bf16 v[36:39], v[232:235], v[192:195], v[56:59]
	s_add_i32 s73, 0, 0x18000
	v_mfma_f32_16x16x32_bf16 v[44:47], v[228:231], v[204:207], v[44:47]
	v_add_u32_e32 v144, s73, v161
	v_mfma_f32_16x16x32_bf16 v[40:43], v[236:239], v[204:207], v[40:43]
	v_mfma_f32_16x16x32_bf16 v[20:23], v[228:231], v[212:215], v[20:23]
	v_mfma_f32_16x16x32_bf16 v[16:19], v[236:239], v[212:215], v[16:19]
	v_mfma_f32_16x16x32_bf16 v[4:7], v[228:231], v[220:223], v[4:7]
	v_mfma_f32_16x16x32_bf16 v[0:3], v[236:239], v[220:223], v[0:3]
	v_mfma_f32_16x16x32_bf16 v[32:35], v[228:231], v[196:199], v[32:35]
	v_mfma_f32_16x16x32_bf16 v[36:39], v[236:239], v[196:199], v[36:39]
	s_barrier
	s_setprio 0
	ds_read_b128 v[56:59], v144
	ds_read_b128 v[60:63], v144 offset:1024
	ds_read_b128 v[178:181], v144 offset:2048
	ds_read_b128 v[182:185], v144 offset:3072
	s_add_u32 s86, s86, 0x80000
	s_addc_u32 s87, s87, 0
	s_mov_b32 m0, s39
	ds_read_b128 v[192:195], v167 offset:32768
	ds_read_b128 v[196:199], v167 offset:33792
	ds_read_b128 v[200:203], v167 offset:34816
	ds_read_b128 v[204:207], v167 offset:35840
	ds_read_b128 v[208:211], v167 offset:36864
	ds_read_b128 v[212:215], v167 offset:37888
	ds_read_b128 v[216:219], v167 offset:38912
	ds_read_b128 v[220:223], v167 offset:39936
	global_load_lds_dwordx4 v136, s[86:87]
	s_mov_b32 m0, s97
	s_nop 0
	global_load_lds_dwordx4 v140, s[86:87]
	s_waitcnt lgkmcnt(8)
	s_setprio 1
	s_barrier
	s_waitcnt lgkmcnt(0)
	v_mfma_f32_16x16x32_bf16 v[132:135], v[56:59], v[192:195], v[132:135]
	v_mfma_f32_16x16x32_bf16 v[128:131], v[178:181], v[192:195], v[128:131]
	v_mfma_f32_16x16x32_bf16 v[116:119], v[56:59], v[200:203], v[116:119]
	v_mfma_f32_16x16x32_bf16 v[112:115], v[178:181], v[200:203], v[112:115]
	v_mfma_f32_16x16x32_bf16 v[100:103], v[56:59], v[208:211], v[100:103]
	v_mfma_f32_16x16x32_bf16 v[96:99], v[178:181], v[208:211], v[96:99]
	v_mfma_f32_16x16x32_bf16 v[84:87], v[56:59], v[216:219], v[84:87]
	v_mfma_f32_16x16x32_bf16 v[80:83], v[178:181], v[216:219], v[80:83]
	s_add_i32 s86, 0, 0x1c000
	v_mfma_f32_16x16x32_bf16 v[132:135], v[60:63], v[196:199], v[132:135]
	s_add_i32 s73, s73, s31
	v_mfma_f32_16x16x32_bf16 v[128:131], v[182:185], v[196:199], v[128:131]
	v_add_u32_e32 v144, s86, v161
	v_mfma_f32_16x16x32_bf16 v[116:119], v[60:63], v[204:207], v[116:119]
	s_mov_b32 m0, s73
	v_mfma_f32_16x16x32_bf16 v[112:115], v[182:185], v[204:207], v[112:115]
	v_mfma_f32_16x16x32_bf16 v[100:103], v[60:63], v[212:215], v[100:103]
	v_mfma_f32_16x16x32_bf16 v[96:99], v[182:185], v[212:215], v[96:99]
	v_mfma_f32_16x16x32_bf16 v[84:87], v[60:63], v[220:223], v[84:87]
	v_mfma_f32_16x16x32_bf16 v[80:83], v[182:185], v[220:223], v[80:83]
	s_barrier
	s_setprio 0
	ds_read_b128 v[224:227], v144
	ds_read_b128 v[228:231], v144 offset:1024
	ds_read_b128 v[232:235], v144 offset:2048
	ds_read_b128 v[236:239], v144 offset:3072
	global_load_lds_dwordx4 v138, s[98:99]
	s_add_i32 m0, s73, 0x2000
	s_nop 0
	global_load_lds_dwordx4 v142, s[98:99]
	s_setprio 1
	s_barrier
; #define PG8_STAGE(bufoff, gbase, voff) do { _Pragma("unroll") for (int _i = 0; _i < 2; ++_i) \
;         __builtin_amdgcn_global_load_lds((const unsigned*)((const char*)(gbase) + (voff)[_i]), (LAS unsigned*)(lds + (bufoff) + ldsw + _i * 8192), 16, 0, 0); } while (0)
; #define PG8_LDA(dst, b, h) do { _Pragma("unroll") for (int m = 0; m < 4; ++m) _Pragma("unroll") for (int k = 0; k < 2; ++k) dst[m][k] = *(const LAS bf16x8*)(lds + PG8_SA(b, h) + aoff + m * 2048 + k * 1024); } while (0)
; #define PG8_MMA(ai, bj, At, Bt) do { __builtin_amdgcn_s_setprio(1); _Pragma("unroll") for (int m = 0; m < 4; ++m) _Pragma("unroll") for (int n = 0; n < 2; ++n) _Pragma("unroll") for (int k = 0; k < 2; ++k) \
;         acc[ai][bj][m][n] = __builtin_amdgcn_mfma_f32_16x16x32_bf16(Bt[n][k], At[m][k], acc[ai][bj][m][n], 0, 0, 0); __builtin_amdgcn_s_setprio(0); } while (0)
; #define PG8_WAIT_V(n) asm volatile("s_waitcnt vmcnt(" #n ")" ::: "memory")
; #define PG8_WAIT_L(n) asm volatile("s_waitcnt lgkmcnt(" #n ")" ::: "memory")
; #define PG8_BAR __builtin_amdgcn_s_barrier()
; #define PG8_SCHED __builtin_amdgcn_sched_barrier(0)
; template <class Epi, class Sched, bool ATILE = false>
; __device__ __forceinline__ void gemm_phase(LAS unsigned char* lds, const Gemm g, const Sched& S, const Epi& E) {
;     ...
;             PG8_BAR; PG8_WAIT_L(0); PG8_MMA(0, 1, At, B1); PG8_BAR;
;             PG8_LDA(At, 1, 1); PG8_STAGE(PG8_SA(1, 0), a3, voffA);
;             PG8_BAR; PG8_WAIT_L(0); PG8_MMA(1, 0, At, B0); PG8_BAR; PG8_SCHED;
;             PG8_STAGE(PG8_SB(1, 1), b3 + hstepB, voffB);
;             PG8_WAIT_V(6); PG8_BAR; PG8_MMA(1, 1, At, B1); PG8_BAR;
;         }
	s_waitcnt lgkmcnt(0)
	v_mfma_f32_16x16x32_bf16 v[124:127], v[224:227], v[192:195], v[124:127]
	v_mfma_f32_16x16x32_bf16 v[120:123], v[232:235], v[192:195], v[120:123]
	v_mfma_f32_16x16x32_bf16 v[108:111], v[224:227], v[200:203], v[108:111]
	v_mfma_f32_16x16x32_bf16 v[104:107], v[232:235], v[200:203], v[104:107]
	v_mfma_f32_16x16x32_bf16 v[92:95], v[224:227], v[208:211], v[92:95]
	v_mfma_f32_16x16x32_bf16 v[88:91], v[232:235], v[208:211], v[88:91]
	v_mfma_f32_16x16x32_bf16 v[76:79], v[224:227], v[216:219], v[76:79]
	v_mfma_f32_16x16x32_bf16 v[72:75], v[232:235], v[216:219], v[72:75]
	s_mov_b32 m0, s4
	v_mfma_f32_16x16x32_bf16 v[124:127], v[228:231], v[196:199], v[124:127]
	v_mfma_f32_16x16x32_bf16 v[120:123], v[236:239], v[196:199], v[120:123]
	v_mfma_f32_16x16x32_bf16 v[108:111], v[228:231], v[204:207], v[108:111]
	v_mfma_f32_16x16x32_bf16 v[104:107], v[236:239], v[204:207], v[104:107]
	v_mfma_f32_16x16x32_bf16 v[92:95], v[228:231], v[212:215], v[92:95]
	v_mfma_f32_16x16x32_bf16 v[88:91], v[236:239], v[212:215], v[88:91]
	v_mfma_f32_16x16x32_bf16 v[76:79], v[228:231], v[220:223], v[76:79]
	v_mfma_f32_16x16x32_bf16 v[72:75], v[236:239], v[220:223], v[72:75]
	s_barrier
	s_setprio 0
	ds_read_b128 v[192:195], v167 offset:49152
	ds_read_b128 v[196:199], v167 offset:50176
	ds_read_b128 v[200:203], v167 offset:51200
	ds_read_b128 v[204:207], v167 offset:52224
	ds_read_b128 v[208:211], v167 offset:53248
	ds_read_b128 v[212:215], v167 offset:54272
	ds_read_b128 v[216:219], v167 offset:55296
	ds_read_b128 v[220:223], v167 offset:56320
	global_load_lds_dwordx4 v136, s[100:101]
	s_mov_b32 m0, s5
	s_nop 0
	global_load_lds_dwordx4 v140, s[100:101]
	s_setprio 1
	s_barrier
	s_waitcnt lgkmcnt(0)
	v_mfma_f32_16x16x32_bf16 v[68:71], v[56:59], v[192:195], v[68:71]
	v_mfma_f32_16x16x32_bf16 v[64:67], v[178:181], v[192:195], v[64:67]
	v_mfma_f32_16x16x32_bf16 v[52:55], v[56:59], v[200:203], v[52:55]
	v_mfma_f32_16x16x32_bf16 v[48:51], v[178:181], v[200:203], v[48:51]
	v_mfma_f32_16x16x32_bf16 v[28:31], v[56:59], v[208:211], v[28:31]
	v_mfma_f32_16x16x32_bf16 v[24:27], v[178:181], v[208:211], v[24:27]
	v_mfma_f32_16x16x32_bf16 v[12:15], v[56:59], v[216:219], v[12:15]
	v_mfma_f32_16x16x32_bf16 v[8:11], v[178:181], v[216:219], v[8:11]
	s_add_u32 s84, s84, 0x80080
	v_mfma_f32_16x16x32_bf16 v[68:71], v[60:63], v[196:199], v[68:71]
	s_addc_u32 s85, s85, 0
	v_mfma_f32_16x16x32_bf16 v[64:67], v[182:185], v[196:199], v[64:67]
	s_add_i32 s73, s86, s31
	v_mfma_f32_16x16x32_bf16 v[52:55], v[60:63], v[204:207], v[52:55]
	s_mov_b32 m0, s73
	v_mfma_f32_16x16x32_bf16 v[48:51], v[182:185], v[204:207], v[48:51]
	v_mfma_f32_16x16x32_bf16 v[28:31], v[60:63], v[212:215], v[28:31]
	v_mfma_f32_16x16x32_bf16 v[24:27], v[182:185], v[212:215], v[24:27]
	v_mfma_f32_16x16x32_bf16 v[12:15], v[60:63], v[220:223], v[12:15]
	v_mfma_f32_16x16x32_bf16 v[8:11], v[182:185], v[220:223], v[8:11]
	s_barrier
	s_setprio 0
	s_nop 0
	global_load_lds_dwordx4 v138, s[84:85]
	s_add_i32 m0, s73, 0x2000
	s_nop 0
	global_load_lds_dwordx4 v142, s[84:85]
	s_waitcnt vmcnt(6)
	s_setprio 1
	s_barrier
	v_mfma_f32_16x16x32_bf16 v[32:35], v[224:227], v[192:195], v[32:35]
	v_mfma_f32_16x16x32_bf16 v[60:63], v[228:231], v[196:199], v[32:35]
	v_mfma_f32_16x16x32_bf16 v[32:35], v[232:235], v[192:195], v[36:39]
	v_mfma_f32_16x16x32_bf16 v[56:59], v[236:239], v[196:199], v[32:35]
	v_mfma_f32_16x16x32_bf16 v[32:35], v[224:227], v[200:203], v[44:47]
	v_mfma_f32_16x16x32_bf16 v[44:47], v[228:231], v[204:207], v[32:35]
	v_mfma_f32_16x16x32_bf16 v[32:35], v[232:235], v[200:203], v[40:43]
	s_add_u32 s12, s12, 0x100
	v_mfma_f32_16x16x32_bf16 v[20:23], v[224:227], v[208:211], v[20:23]
	s_addc_u32 s13, s13, 0
	v_mfma_f32_16x16x32_bf16 v[16:19], v[232:235], v[208:211], v[16:19]
	s_add_u32 s62, s62, 0x100
	v_mfma_f32_16x16x32_bf16 v[4:7], v[224:227], v[216:219], v[4:7]
	s_addc_u32 s63, s63, 0
	v_mfma_f32_16x16x32_bf16 v[0:3], v[232:235], v[216:219], v[0:3]
	s_cmp_ge_i32 s88, s1
	v_mfma_f32_16x16x32_bf16 v[40:43], v[236:239], v[204:207], v[32:35]
	s_mov_b32 s73, s88
	v_mfma_f32_16x16x32_bf16 v[20:23], v[228:231], v[212:215], v[20:23]
	v_mfma_f32_16x16x32_bf16 v[16:19], v[236:239], v[212:215], v[16:19]
	v_mfma_f32_16x16x32_bf16 v[4:7], v[228:231], v[220:223], v[4:7]
	v_mfma_f32_16x16x32_bf16 v[0:3], v[236:239], v[220:223], v[0:3]
	s_barrier
	s_setprio 0
	s_cbranch_scc0 .LBB0_895
	s_nop 5
	s_branch .LBB0_897

; #define PG8_STAGE(bufoff, gbase, voff) do { _Pragma("unroll") for (int _i = 0; _i < 2; ++_i) \
;         __builtin_amdgcn_global_load_lds((const unsigned*)((const char*)(gbase) + (voff)[_i]), (LAS unsigned*)(lds + (bufoff) + ldsw + _i * 8192), 16, 0, 0); } while (0)
; #define PG8_LDA(dst, b, h) do { _Pragma("unroll") for (int m = 0; m < 4; ++m) _Pragma("unroll") for (int k = 0; k < 2; ++k) dst[m][k] = *(const LAS bf16x8*)(lds + PG8_SA(b, h) + aoff + m * 2048 + k * 1024); } while (0)
; #define PG8_LDB(dst, b, h) do { _Pragma("unroll") for (int n = 0; n < 2; ++n) _Pragma("unroll") for (int k = 0; k < 2; ++k) dst[n][k] = *(const LAS bf16x8*)(lds + PG8_SB(b, h) + boff + n * 2048 + k * 1024); } while (0)
; #define PG8_MMA(ai, bj, At, Bt) do { __builtin_amdgcn_s_setprio(1); _Pragma("unroll") for (int m = 0; m < 4; ++m) _Pragma("unroll") for (int n = 0; n < 2; ++n) _Pragma("unroll") for (int k = 0; k < 2; ++k) \
;         acc[ai][bj][m][n] = __builtin_amdgcn_mfma_f32_16x16x32_bf16(Bt[n][k], At[m][k], acc[ai][bj][m][n], 0, 0, 0); __builtin_amdgcn_s_setprio(0); } while (0)
; #define PG8_WAIT_V(n) asm volatile("s_waitcnt vmcnt(" #n ")" ::: "memory")
; #define PG8_WAIT_L(n) asm volatile("s_waitcnt lgkmcnt(" #n ")" ::: "memory")
; template <class Epi, class Sched, bool ATILE = false>
; __device__ __forceinline__ void gemm_phase(LAS unsigned char* lds, const Gemm g, const Sched& S, const Epi& E) {
;     ...
;         for (int t = 0; t < nt; t += 2) {
;             const bool last = (t == nt - 2);
;             const char* a1 = cA + (size_t)(t + 1) * kstepA;
;             const char* a2 = last ? nA : cA + (size_t)(t + 2) * kstepA; const char* b2 = last ? nB : cB + (size_t)(t + 2) * kstep;
;             const char* a3 = a2 + kstepA; const char* b3 = b2 + kstep;
;             PG8_LDB(B0, 0, 0); PG8_SCHED; PG8_LDA(At, 0, 0); PG8_STAGE(PG8_SA(1, 1), a1 + hstepA, voffA);
;             PG8_WAIT_L(8); PG8_BAR; PG8_WAIT_L(0); PG8_MMA(0, 0, At, B0); PG8_BAR; PG8_SCHED;
;             PG8_LDB(B1, 0, 1); PG8_STAGE(PG8_SB(0, 0), b2, voffB);
;             PG8_BAR; PG8_WAIT_L(0); PG8_MMA(0, 1, At, B1); PG8_BAR;
;             PG8_LDA(At, 0, 1); PG8_STAGE(PG8_SA(0, 0), a2, voffA);
;             PG8_BAR; PG8_WAIT_L(0); PG8_MMA(1, 0, At, B0); PG8_BAR; PG8_SCHED;
;             PG8_STAGE(PG8_SB(0, 1), b2 + hstepB, voffB);
;             PG8_WAIT_V(6); PG8_BAR; PG8_MMA(1, 1, At, B1); PG8_BAR;
.LBB0_1298:
	ds_read_b128 v[82:85], v79
	ds_read_b128 v[86:89], v79 offset:1024
	ds_read_b128 v[90:93], v79 offset:2048
	ds_read_b128 v[94:97], v79 offset:3072
	s_add_i32 s60, s20, 2
	s_add_u32 s18, s16, 0x100
	s_addc_u32 s19, s17, 0
	s_cmp_eq_u32 s57, s20
	s_cselect_b32 s20, s56, s58
	s_cselect_b32 s23, s9, s19
	s_cselect_b32 s22, s8, s18
	s_cselect_b32 s21, s55, s59
	s_mov_b32 m0, s38
	v_lshl_add_u64 v[130:131], s[16:17], 0, v[74:75]
	ds_read_b128 v[98:101], v80
	ds_read_b128 v[102:105], v80 offset:1024
	ds_read_b128 v[106:109], v80 offset:2048
	ds_read_b128 v[110:113], v80 offset:3072
	ds_read_b128 v[114:117], v80 offset:4096
	ds_read_b128 v[118:121], v80 offset:5120
	ds_read_b128 v[122:125], v80 offset:6144
	ds_read_b128 v[126:129], v80 offset:7168
	global_load_lds_dwordx4 v[130:131], off
	v_lshl_add_u64 v[130:131], s[16:17], 0, v[76:77]
	s_mov_b32 m0, s39
	s_nop 0
	global_load_lds_dwordx4 v[130:131], off
	s_waitcnt lgkmcnt(8)
	s_setprio 1
	s_barrier
	s_waitcnt lgkmcnt(0)
	v_mfma_f32_16x16x32_bf16 v[60:63], v[82:85], v[98:101], v[60:63]
	v_mfma_f32_16x16x32_bf16 v[56:59], v[90:93], v[98:101], v[56:59]
	v_mfma_f32_16x16x32_bf16 v[52:55], v[82:85], v[106:109], v[52:55]
	v_mfma_f32_16x16x32_bf16 v[48:51], v[90:93], v[106:109], v[48:51]
	v_mfma_f32_16x16x32_bf16 v[44:47], v[82:85], v[114:117], v[44:47]
	v_mfma_f32_16x16x32_bf16 v[40:43], v[90:93], v[114:117], v[40:43]
	v_mfma_f32_16x16x32_bf16 v[36:39], v[82:85], v[122:125], v[36:39]
	v_mfma_f32_16x16x32_bf16 v[32:35], v[90:93], v[122:125], v[32:35]
	s_mov_b32 m0, s40
	v_mfma_f32_16x16x32_bf16 v[60:63], v[86:89], v[102:105], v[60:63]
	v_mfma_f32_16x16x32_bf16 v[56:59], v[94:97], v[102:105], v[56:59]
	v_mfma_f32_16x16x32_bf16 v[52:55], v[86:89], v[110:113], v[52:55]
	v_mfma_f32_16x16x32_bf16 v[48:51], v[94:97], v[110:113], v[48:51]
	v_mfma_f32_16x16x32_bf16 v[44:47], v[86:89], v[118:121], v[44:47]
	v_mfma_f32_16x16x32_bf16 v[40:43], v[94:97], v[118:121], v[40:43]
	v_mfma_f32_16x16x32_bf16 v[36:39], v[86:89], v[126:129], v[36:39]
	v_mfma_f32_16x16x32_bf16 v[32:35], v[94:97], v[126:129], v[32:35]
	s_barrier
	s_setprio 0
	v_lshl_add_u64 v[130:131], s[20:21], 0, v[68:69]
	global_load_lds_dwordx4 v[130:131], off
	v_lshl_add_u64 v[132:133], s[20:21], 0, v[64:65]
	s_mov_b32 m0, s41
	s_nop 0
	global_load_lds_dwordx4 v[132:133], off
	s_barrier
	s_waitcnt lgkmcnt(0)
	s_setprio 1
	s_setprio 0
	s_mov_b32 m0, s25
	v_lshl_add_u64 v[134:135], s[22:23], 0, v[70:71]
	s_barrier
	ds_read_b128 v[98:101], v80 offset:16384
	ds_read_b128 v[102:105], v80 offset:17408
	ds_read_b128 v[106:109], v80 offset:18432
	ds_read_b128 v[110:113], v80 offset:19456
	ds_read_b128 v[114:117], v80 offset:20480
	ds_read_b128 v[118:121], v80 offset:21504
	ds_read_b128 v[122:125], v80 offset:22528
	ds_read_b128 v[126:129], v80 offset:23552
	global_load_lds_dwordx4 v[134:135], off
	v_lshl_add_u64 v[136:137], s[22:23], 0, v[66:67]
	s_mov_b32 m0, s26
	s_nop 0
	global_load_lds_dwordx4 v[136:137], off
	s_setprio 1
	s_barrier
	s_waitcnt lgkmcnt(0)
	v_mfma_f32_16x16x32_bf16 v[28:31], v[82:85], v[98:101], v[28:31]
	v_mfma_f32_16x16x32_bf16 v[24:27], v[90:93], v[98:101], v[24:27]
	v_mfma_f32_16x16x32_bf16 v[20:23], v[82:85], v[106:109], v[20:23]
	v_mfma_f32_16x16x32_bf16 v[16:19], v[90:93], v[106:109], v[16:19]
	v_mfma_f32_16x16x32_bf16 v[12:15], v[82:85], v[114:117], v[12:15]
	v_mfma_f32_16x16x32_bf16 v[8:11], v[90:93], v[114:117], v[8:11]
	v_mfma_f32_16x16x32_bf16 v[4:7], v[82:85], v[122:125], v[4:7]
	v_mfma_f32_16x16x32_bf16 v[0:3], v[90:93], v[122:125], v[0:3]
	s_add_u32 s16, s20, 0x10000
	v_mfma_f32_16x16x32_bf16 v[28:31], v[86:89], v[102:105], v[28:31]
	s_addc_u32 s17, s21, 0
	v_mfma_f32_16x16x32_bf16 v[24:27], v[94:97], v[102:105], v[24:27]
	s_mov_b32 m0, s27
	v_mfma_f32_16x16x32_bf16 v[20:23], v[86:89], v[110:113], v[20:23]
	v_mfma_f32_16x16x32_bf16 v[16:19], v[94:97], v[110:113], v[16:19]
	v_mfma_f32_16x16x32_bf16 v[12:15], v[86:89], v[118:121], v[12:15]
	v_mfma_f32_16x16x32_bf16 v[8:11], v[94:97], v[118:121], v[8:11]
	v_mfma_f32_16x16x32_bf16 v[4:7], v[86:89], v[126:129], v[4:7]
	v_mfma_f32_16x16x32_bf16 v[0:3], v[94:97], v[126:129], v[0:3]
	s_barrier
	s_setprio 0
	s_nop 0
	global_load_lds_dwordx4 v68, s[16:17]
	s_mov_b32 m0, s28
	s_nop 0
	global_load_lds_dwordx4 v64, s[16:17]
	s_waitcnt vmcnt(6)
	s_barrier
; #define PG8_STAGE(bufoff, gbase, voff) do { _Pragma("unroll") for (int _i = 0; _i < 2; ++_i) \
;         __builtin_amdgcn_global_load_lds((const unsigned*)((const char*)(gbase) + (voff)[_i]), (LAS unsigned*)(lds + (bufoff) + ldsw + _i * 8192), 16, 0, 0); } while (0)
; #define PG8_LDA(dst, b, h) do { _Pragma("unroll") for (int m = 0; m < 4; ++m) _Pragma("unroll") for (int k = 0; k < 2; ++k) dst[m][k] = *(const LAS bf16x8*)(lds + PG8_SA(b, h) + aoff + m * 2048 + k * 1024); } while (0)
; #define PG8_LDB(dst, b, h) do { _Pragma("unroll") for (int n = 0; n < 2; ++n) _Pragma("unroll") for (int k = 0; k < 2; ++k) dst[n][k] = *(const LAS bf16x8*)(lds + PG8_SB(b, h) + boff + n * 2048 + k * 1024); } while (0)
; #define PG8_MMA(ai, bj, At, Bt) do { __builtin_amdgcn_s_setprio(1); _Pragma("unroll") for (int m = 0; m < 4; ++m) _Pragma("unroll") for (int n = 0; n < 2; ++n) _Pragma("unroll") for (int k = 0; k < 2; ++k) \
;         acc[ai][bj][m][n] = __builtin_amdgcn_mfma_f32_16x16x32_bf16(Bt[n][k], At[m][k], acc[ai][bj][m][n], 0, 0, 0); __builtin_amdgcn_s_setprio(0); } while (0)
; #define PG8_WAIT_V(n) asm volatile("s_waitcnt vmcnt(" #n ")" ::: "memory")
; #define PG8_WAIT_L(n) asm volatile("s_waitcnt lgkmcnt(" #n ")" ::: "memory")
; #define PG8_BAR __builtin_amdgcn_s_barrier()
; #define PG8_SCHED __builtin_amdgcn_sched_barrier(0)
; template <class Epi, class Sched, bool ATILE = false>
; __device__ __forceinline__ void gemm_phase(LAS unsigned char* lds, const Gemm g, const Sched& S, const Epi& E) {
;     ...
;             PG8_WAIT_V(6); PG8_BAR; PG8_MMA(1, 1, At, B1); PG8_BAR;
;             PG8_LDB(B0, 1, 0); PG8_SCHED; PG8_LDA(At, 1, 0); PG8_STAGE(PG8_SA(0, 1), a2 + hstepA, voffA);
;             PG8_WAIT_L(8); PG8_BAR; PG8_WAIT_L(0); PG8_MMA(0, 0, At, B0); PG8_BAR; PG8_SCHED;
;             PG8_LDB(B1, 1, 1); PG8_STAGE(PG8_SB(1, 0), b3, voffB);
;             PG8_BAR; PG8_WAIT_L(0); PG8_MMA(0, 1, At, B1); PG8_BAR;
;             PG8_LDA(At, 1, 1); PG8_STAGE(PG8_SA(1, 0), a3, voffA);
;             PG8_BAR; PG8_WAIT_L(0); PG8_MMA(1, 0, At, B0); PG8_BAR; PG8_SCHED;
;             PG8_STAGE(PG8_SB(1, 1), b3 + hstepB, voffB);
;             PG8_WAIT_V(6); PG8_BAR; PG8_MMA(1, 1, At, B1); PG8_BAR;
;         }
	s_setprio 1
	s_setprio 0
	s_barrier
	ds_read_b128 v[82:85], v81
	ds_read_b128 v[86:89], v81 offset:1024
	ds_read_b128 v[90:93], v81 offset:2048
	ds_read_b128 v[94:97], v81 offset:3072
	s_add_u32 s16, s22, 0x18000
	s_addc_u32 s17, s23, 0
	s_mov_b32 m0, s29
	ds_read_b128 v[98:101], v80 offset:32768
	ds_read_b128 v[102:105], v80 offset:33792
	ds_read_b128 v[106:109], v80 offset:34816
	ds_read_b128 v[110:113], v80 offset:35840
	ds_read_b128 v[114:117], v80 offset:36864
	ds_read_b128 v[118:121], v80 offset:37888
	ds_read_b128 v[122:125], v80 offset:38912
	ds_read_b128 v[126:129], v80 offset:39936
	global_load_lds_dwordx4 v70, s[16:17]
	s_mov_b32 m0, s30
	s_nop 0
	global_load_lds_dwordx4 v66, s[16:17]
	s_waitcnt lgkmcnt(8)
	s_setprio 1
	s_barrier
	s_waitcnt lgkmcnt(0)
	v_mfma_f32_16x16x32_bf16 v[60:63], v[82:85], v[98:101], v[60:63]
	v_mfma_f32_16x16x32_bf16 v[56:59], v[90:93], v[98:101], v[56:59]
	v_mfma_f32_16x16x32_bf16 v[52:55], v[82:85], v[106:109], v[52:55]
	v_mfma_f32_16x16x32_bf16 v[48:51], v[90:93], v[106:109], v[48:51]
	v_mfma_f32_16x16x32_bf16 v[44:47], v[82:85], v[114:117], v[44:47]
	v_mfma_f32_16x16x32_bf16 v[40:43], v[90:93], v[114:117], v[40:43]
	v_mfma_f32_16x16x32_bf16 v[36:39], v[82:85], v[122:125], v[36:39]
	v_mfma_f32_16x16x32_bf16 v[32:35], v[90:93], v[122:125], v[32:35]
	s_mov_b32 m0, s43
	v_mfma_f32_16x16x32_bf16 v[60:63], v[86:89], v[102:105], v[60:63]
	v_mfma_f32_16x16x32_bf16 v[56:59], v[94:97], v[102:105], v[56:59]
	v_mfma_f32_16x16x32_bf16 v[52:55], v[86:89], v[110:113], v[52:55]
	v_mfma_f32_16x16x32_bf16 v[48:51], v[94:97], v[110:113], v[48:51]
	v_mfma_f32_16x16x32_bf16 v[44:47], v[86:89], v[118:121], v[44:47]
	v_mfma_f32_16x16x32_bf16 v[40:43], v[94:97], v[118:121], v[40:43]
	v_mfma_f32_16x16x32_bf16 v[36:39], v[86:89], v[126:129], v[36:39]
	v_mfma_f32_16x16x32_bf16 v[32:35], v[94:97], v[126:129], v[32:35]
	s_barrier
	s_setprio 0
	v_lshl_add_u64 v[98:99], v[130:131], 0, s[6:7]
	global_load_lds_dwordx4 v[98:99], off
	v_lshl_add_u64 v[98:99], v[132:133], 0, s[6:7]
	s_mov_b32 m0, s44
	s_nop 0
	global_load_lds_dwordx4 v[98:99], off
	s_barrier
	s_waitcnt lgkmcnt(0)
	s_setprio 1
	s_setprio 0
	s_mov_b32 m0, s34
	v_lshl_add_u64 v[130:131], v[134:135], 0, s[6:7]
	s_barrier
	ds_read_b128 v[98:101], v80 offset:49152
	ds_read_b128 v[102:105], v80 offset:50176
	ds_read_b128 v[106:109], v80 offset:51200
	ds_read_b128 v[110:113], v80 offset:52224
	ds_read_b128 v[114:117], v80 offset:53248
	ds_read_b128 v[118:121], v80 offset:54272
	ds_read_b128 v[122:125], v80 offset:55296
	ds_read_b128 v[126:129], v80 offset:56320
	global_load_lds_dwordx4 v[130:131], off
	v_lshl_add_u64 v[130:131], v[136:137], 0, s[6:7]
	s_mov_b32 m0, s35
	s_nop 0
	global_load_lds_dwordx4 v[130:131], off
	s_setprio 1
	s_barrier
	s_waitcnt lgkmcnt(0)
	v_mfma_f32_16x16x32_bf16 v[28:31], v[82:85], v[98:101], v[28:31]
	v_mfma_f32_16x16x32_bf16 v[24:27], v[90:93], v[98:101], v[24:27]
	v_mfma_f32_16x16x32_bf16 v[20:23], v[82:85], v[106:109], v[20:23]
	v_mfma_f32_16x16x32_bf16 v[16:19], v[90:93], v[106:109], v[16:19]
	v_mfma_f32_16x16x32_bf16 v[12:15], v[82:85], v[114:117], v[12:15]
	v_mfma_f32_16x16x32_bf16 v[8:11], v[90:93], v[114:117], v[8:11]
	v_mfma_f32_16x16x32_bf16 v[4:7], v[82:85], v[122:125], v[4:7]
	v_mfma_f32_16x16x32_bf16 v[0:3], v[90:93], v[122:125], v[0:3]
	s_add_u32 s16, s20, 0x10080
	v_mfma_f32_16x16x32_bf16 v[28:31], v[86:89], v[102:105], v[28:31]
	s_addc_u32 s17, s21, 0
	v_mfma_f32_16x16x32_bf16 v[24:27], v[94:97], v[102:105], v[24:27]
	s_mov_b32 m0, s36
	v_mfma_f32_16x16x32_bf16 v[20:23], v[86:89], v[110:113], v[20:23]
	v_mfma_f32_16x16x32_bf16 v[16:19], v[94:97], v[110:113], v[16:19]
	v_mfma_f32_16x16x32_bf16 v[12:15], v[86:89], v[118:121], v[12:15]
	v_mfma_f32_16x16x32_bf16 v[8:11], v[94:97], v[118:121], v[8:11]
	v_mfma_f32_16x16x32_bf16 v[4:7], v[86:89], v[126:129], v[4:7]
	v_mfma_f32_16x16x32_bf16 v[0:3], v[94:97], v[126:129], v[0:3]
	s_barrier
	s_setprio 0
	s_nop 0
	global_load_lds_dwordx4 v68, s[16:17]
	s_mov_b32 m0, s37
	s_nop 0
	global_load_lds_dwordx4 v64, s[16:17]
	s_waitcnt vmcnt(6)
	s_barrier
	s_setprio 1
	s_setprio 0
	s_add_u32 s58, s58, 0x100
	s_addc_u32 s59, s59, 0
	s_cmp_ge_i32 s60, s54
	s_mov_b64 s[16:17], s[18:19]
	s_mov_b32 s20, s60
	s_barrier
	s_cbranch_scc0 .LBB0_1298
	s_branch .LBB0_1293

; #define PG8_STAGE(bufoff, gbase, voff) do { _Pragma("unroll") for (int _i = 0; _i < 2; ++_i) \
;         __builtin_amdgcn_global_load_lds((const unsigned*)((const char*)(gbase) + (voff)[_i]), (LAS unsigned*)(lds + (bufoff) + ldsw + _i * 8192), 16, 0, 0); } while (0)
; #define PG8_LDA(dst, b, h) do { _Pragma("unroll") for (int m = 0; m < 4; ++m) _Pragma("unroll") for (int k = 0; k < 2; ++k) dst[m][k] = *(const LAS bf16x8*)(lds + PG8_SA(b, h) + aoff + m * 2048 + k * 1024); } while (0)
; #define PG8_LDB(dst, b, h) do { _Pragma("unroll") for (int n = 0; n < 2; ++n) _Pragma("unroll") for (int k = 0; k < 2; ++k) dst[n][k] = *(const LAS bf16x8*)(lds + PG8_SB(b, h) + boff + n * 2048 + k * 1024); } while (0)
; #define PG8_MMA(ai, bj, At, Bt) do { __builtin_amdgcn_s_setprio(1); _Pragma("unroll") for (int m = 0; m < 4; ++m) _Pragma("unroll") for (int n = 0; n < 2; ++n) _Pragma("unroll") for (int k = 0; k < 2; ++k) \
;         acc[ai][bj][m][n] = __builtin_amdgcn_mfma_f32_16x16x32_bf16(Bt[n][k], At[m][k], acc[ai][bj][m][n], 0, 0, 0); __builtin_amdgcn_s_setprio(0); } while (0)
; #define PG8_WAIT_L(n) asm volatile("s_waitcnt lgkmcnt(" #n ")" ::: "memory")
; #define PG8_BAR __builtin_amdgcn_s_barrier()
; #define PG8_SCHED __builtin_amdgcn_sched_barrier(0)
; template <class Epi, class Sched, bool ATILE = false>
; __device__ __forceinline__ void gemm_phase(LAS unsigned char* lds, const Gemm g, const Sched& S, const Epi& E) {
;     ...
;         for (int t = 0; t < nt; t += 2) {
;             const bool last = (t == nt - 2);
;             const char* a1 = cA + (size_t)(t + 1) * kstepA;
;             const char* a2 = last ? nA : cA + (size_t)(t + 2) * kstepA; const char* b2 = last ? nB : cB + (size_t)(t + 2) * kstep;
;             const char* a3 = a2 + kstepA; const char* b3 = b2 + kstep;
;             PG8_LDB(B0, 0, 0); PG8_SCHED; PG8_LDA(At, 0, 0); PG8_STAGE(PG8_SA(1, 1), a1 + hstepA, voffA);
;             PG8_WAIT_L(8); PG8_BAR; PG8_WAIT_L(0); PG8_MMA(0, 0, At, B0); PG8_BAR; PG8_SCHED;
;             PG8_LDB(B1, 0, 1); PG8_STAGE(PG8_SB(0, 0), b2, voffB);
;             PG8_BAR; PG8_WAIT_L(0); PG8_MMA(0, 1, At, B1); PG8_BAR;
;             PG8_LDA(At, 0, 1); PG8_STAGE(PG8_SA(0, 0), a2, voffA);
;             PG8_BAR; PG8_WAIT_L(0); PG8_MMA(1, 0, At, B0); PG8_BAR; PG8_SCHED;
.LBB0_1426:
	ds_read_b128 v[162:165], v147
	ds_read_b128 v[166:169], v147 offset:1024
	ds_read_b128 v[170:173], v147 offset:2048
	ds_read_b128 v[174:177], v147 offset:3072
	s_add_i32 s58, s18, 2
	s_add_u32 s16, s12, 0x100
	s_addc_u32 s17, s13, 0
	s_cmp_eq_u32 s55, s18
	s_cselect_b32 s18, s10, s56
	s_cselect_b32 s21, s7, s17
	s_cselect_b32 s20, s6, s16
	s_cselect_b32 s19, s11, s57
	s_mov_b32 m0, s30
	v_lshl_add_u64 v[144:145], s[12:13], 0, v[140:141]
	ds_read_b128 v[178:181], v148
	ds_read_b128 v[182:185], v148 offset:1024
	ds_read_b128 v[186:189], v148 offset:2048
	ds_read_b128 v[190:193], v148 offset:3072
	ds_read_b128 v[194:197], v148 offset:4096
	ds_read_b128 v[198:201], v148 offset:5120
	ds_read_b128 v[202:205], v148 offset:6144
	ds_read_b128 v[206:209], v148 offset:7168
	global_load_lds_dwordx4 v[144:145], off
	v_lshl_add_u64 v[144:145], s[12:13], 0, v[142:143]
	s_mov_b32 m0, s31
	s_nop 0
	global_load_lds_dwordx4 v[144:145], off
	s_waitcnt lgkmcnt(8)
	s_setprio 1
	s_barrier
	s_waitcnt lgkmcnt(0)
	v_mfma_f32_16x16x32_bf16 v[124:127], v[162:165], v[178:181], v[124:127]
	v_mfma_f32_16x16x32_bf16 v[120:123], v[170:173], v[178:181], v[120:123]
	v_mfma_f32_16x16x32_bf16 v[108:111], v[162:165], v[186:189], v[108:111]
	v_mfma_f32_16x16x32_bf16 v[104:107], v[170:173], v[186:189], v[104:107]
	v_mfma_f32_16x16x32_bf16 v[92:95], v[162:165], v[194:197], v[92:95]
	v_mfma_f32_16x16x32_bf16 v[88:91], v[170:173], v[194:197], v[88:91]
	v_mfma_f32_16x16x32_bf16 v[76:79], v[162:165], v[202:205], v[76:79]
	v_mfma_f32_16x16x32_bf16 v[72:75], v[170:173], v[202:205], v[72:75]
	s_mov_b32 m0, s33
	v_mfma_f32_16x16x32_bf16 v[124:127], v[166:169], v[182:185], v[124:127]
	v_mfma_f32_16x16x32_bf16 v[120:123], v[174:177], v[182:185], v[120:123]
	v_mfma_f32_16x16x32_bf16 v[108:111], v[166:169], v[190:193], v[108:111]
	v_mfma_f32_16x16x32_bf16 v[104:107], v[174:177], v[190:193], v[104:107]
	v_mfma_f32_16x16x32_bf16 v[92:95], v[166:169], v[198:201], v[92:95]
	v_mfma_f32_16x16x32_bf16 v[88:91], v[174:177], v[198:201], v[88:91]
	v_mfma_f32_16x16x32_bf16 v[76:79], v[166:169], v[206:209], v[76:79]
	v_mfma_f32_16x16x32_bf16 v[72:75], v[174:177], v[206:209], v[72:75]
	s_barrier
	s_setprio 0
	v_lshl_add_u64 v[144:145], s[18:19], 0, v[132:133]
	ds_read_b128 v[210:213], v149
	ds_read_b128 v[214:217], v149 offset:1024
	ds_read_b128 v[218:221], v149 offset:2048
	ds_read_b128 v[222:225], v149 offset:3072
	global_load_lds_dwordx4 v[144:145], off
	v_lshl_add_u64 v[226:227], s[18:19], 0, v[128:129]
	s_mov_b32 m0, s34
	s_nop 0
	global_load_lds_dwordx4 v[226:227], off
	s_setprio 1
	s_barrier
	s_waitcnt lgkmcnt(0)
	v_mfma_f32_16x16x32_bf16 v[116:119], v[210:213], v[178:181], v[116:119]
	v_mfma_f32_16x16x32_bf16 v[112:115], v[218:221], v[178:181], v[112:115]
	v_mfma_f32_16x16x32_bf16 v[100:103], v[210:213], v[186:189], v[100:103]
	v_mfma_f32_16x16x32_bf16 v[96:99], v[218:221], v[186:189], v[96:99]
	v_mfma_f32_16x16x32_bf16 v[84:87], v[210:213], v[194:197], v[84:87]
	v_mfma_f32_16x16x32_bf16 v[80:83], v[218:221], v[194:197], v[80:83]
	v_mfma_f32_16x16x32_bf16 v[68:71], v[210:213], v[202:205], v[68:71]
	v_mfma_f32_16x16x32_bf16 v[64:67], v[218:221], v[202:205], v[64:67]
	s_mov_b32 m0, s22
	v_mfma_f32_16x16x32_bf16 v[116:119], v[214:217], v[182:185], v[116:119]
	v_mfma_f32_16x16x32_bf16 v[112:115], v[222:225], v[182:185], v[112:115]
	v_mfma_f32_16x16x32_bf16 v[100:103], v[214:217], v[190:193], v[100:103]
	v_mfma_f32_16x16x32_bf16 v[96:99], v[222:225], v[190:193], v[96:99]
	v_mfma_f32_16x16x32_bf16 v[84:87], v[214:217], v[198:201], v[84:87]
	v_mfma_f32_16x16x32_bf16 v[80:83], v[222:225], v[198:201], v[80:83]
	v_mfma_f32_16x16x32_bf16 v[68:71], v[214:217], v[206:209], v[68:71]
	v_mfma_f32_16x16x32_bf16 v[64:67], v[222:225], v[206:209], v[64:67]
	s_barrier
	s_setprio 0
	v_lshl_add_u64 v[228:229], s[20:21], 0, v[134:135]
	ds_read_b128 v[178:181], v148 offset:16384
	ds_read_b128 v[182:185], v148 offset:17408
	ds_read_b128 v[186:189], v148 offset:18432
	ds_read_b128 v[190:193], v148 offset:19456
	ds_read_b128 v[194:197], v148 offset:20480
	ds_read_b128 v[198:201], v148 offset:21504
	ds_read_b128 v[202:205], v148 offset:22528
	ds_read_b128 v[206:209], v148 offset:23552
	global_load_lds_dwordx4 v[228:229], off
	v_lshl_add_u64 v[230:231], s[20:21], 0, v[130:131]
	s_mov_b32 m0, s23
	s_nop 0
	global_load_lds_dwordx4 v[230:231], off
	s_setprio 1
	s_barrier
	s_waitcnt lgkmcnt(0)
	v_mfma_f32_16x16x32_bf16 v[60:63], v[162:165], v[178:181], v[60:63]
	v_mfma_f32_16x16x32_bf16 v[56:59], v[170:173], v[178:181], v[56:59]
	v_mfma_f32_16x16x32_bf16 v[44:47], v[162:165], v[186:189], v[44:47]
	v_mfma_f32_16x16x32_bf16 v[40:43], v[170:173], v[186:189], v[40:43]
	v_mfma_f32_16x16x32_bf16 v[28:31], v[162:165], v[194:197], v[28:31]
	v_mfma_f32_16x16x32_bf16 v[24:27], v[170:173], v[194:197], v[24:27]
	v_mfma_f32_16x16x32_bf16 v[12:15], v[162:165], v[202:205], v[12:15]
	v_mfma_f32_16x16x32_bf16 v[8:11], v[170:173], v[202:205], v[8:11]
	s_add_u32 s12, s18, 0x18000
	v_mfma_f32_16x16x32_bf16 v[60:63], v[166:169], v[182:185], v[60:63]
	s_addc_u32 s13, s19, 0
	v_mfma_f32_16x16x32_bf16 v[56:59], v[174:177], v[182:185], v[56:59]
	s_mov_b32 m0, s35
	v_mfma_f32_16x16x32_bf16 v[44:47], v[166:169], v[190:193], v[44:47]
	v_mfma_f32_16x16x32_bf16 v[40:43], v[174:177], v[190:193], v[40:43]
	v_mfma_f32_16x16x32_bf16 v[28:31], v[166:169], v[198:201], v[28:31]
	v_mfma_f32_16x16x32_bf16 v[24:27], v[174:177], v[198:201], v[24:27]
	v_mfma_f32_16x16x32_bf16 v[12:15], v[166:169], v[206:209], v[12:15]
	v_mfma_f32_16x16x32_bf16 v[8:11], v[174:177], v[206:209], v[8:11]
	s_barrier
; #define PG8_STAGE(bufoff, gbase, voff) do { _Pragma("unroll") for (int _i = 0; _i < 2; ++_i) \
;         __builtin_amdgcn_global_load_lds((const unsigned*)((const char*)(gbase) + (voff)[_i]), (LAS unsigned*)(lds + (bufoff) + ldsw + _i * 8192), 16, 0, 0); } while (0)
; #define PG8_LDA(dst, b, h) do { _Pragma("unroll") for (int m = 0; m < 4; ++m) _Pragma("unroll") for (int k = 0; k < 2; ++k) dst[m][k] = *(const LAS bf16x8*)(lds + PG8_SA(b, h) + aoff + m * 2048 + k * 1024); } while (0)
; #define PG8_LDB(dst, b, h) do { _Pragma("unroll") for (int n = 0; n < 2; ++n) _Pragma("unroll") for (int k = 0; k < 2; ++k) dst[n][k] = *(const LAS bf16x8*)(lds + PG8_SB(b, h) + boff + n * 2048 + k * 1024); } while (0)
; #define PG8_MMA(ai, bj, At, Bt) do { __builtin_amdgcn_s_setprio(1); _Pragma("unroll") for (int m = 0; m < 4; ++m) _Pragma("unroll") for (int n = 0; n < 2; ++n) _Pragma("unroll") for (int k = 0; k < 2; ++k) \
;         acc[ai][bj][m][n] = __builtin_amdgcn_mfma_f32_16x16x32_bf16(Bt[n][k], At[m][k], acc[ai][bj][m][n], 0, 0, 0); __builtin_amdgcn_s_setprio(0); } while (0)
; #define PG8_WAIT_V(n) asm volatile("s_waitcnt vmcnt(" #n ")" ::: "memory")
; #define PG8_WAIT_L(n) asm volatile("s_waitcnt lgkmcnt(" #n ")" ::: "memory")
; #define PG8_BAR __builtin_amdgcn_s_barrier()
; #define PG8_SCHED __builtin_amdgcn_sched_barrier(0)
; template <class Epi, class Sched, bool ATILE = false>
; __device__ __forceinline__ void gemm_phase(LAS unsigned char* lds, const Gemm g, const Sched& S, const Epi& E) {
;     ...
;             PG8_BAR; PG8_WAIT_L(0); PG8_MMA(1, 0, At, B0); PG8_BAR; PG8_SCHED;
;             PG8_STAGE(PG8_SB(0, 1), b2 + hstepB, voffB);
;             PG8_WAIT_V(6); PG8_BAR; PG8_MMA(1, 1, At, B1); PG8_BAR;
;             PG8_LDB(B0, 1, 0); PG8_SCHED; PG8_LDA(At, 1, 0); PG8_STAGE(PG8_SA(0, 1), a2 + hstepA, voffA);
;             PG8_WAIT_L(8); PG8_BAR; PG8_WAIT_L(0); PG8_MMA(0, 0, At, B0); PG8_BAR; PG8_SCHED;
;             PG8_LDB(B1, 1, 1); PG8_STAGE(PG8_SB(1, 0), b3, voffB);
;             PG8_BAR; PG8_WAIT_L(0); PG8_MMA(0, 1, At, B1); PG8_BAR;
;             PG8_LDA(At, 1, 1); PG8_STAGE(PG8_SA(1, 0), a3, voffA);
	s_setprio 0
	s_nop 0
	global_load_lds_dwordx4 v132, s[12:13]
	s_mov_b32 m0, s36
	s_nop 0
	global_load_lds_dwordx4 v128, s[12:13]
	s_waitcnt vmcnt(6)
	s_setprio 1
	s_barrier
	v_mfma_f32_16x16x32_bf16 v[52:55], v[210:213], v[178:181], v[52:55]
	v_mfma_f32_16x16x32_bf16 v[48:51], v[218:221], v[178:181], v[48:51]
	v_mfma_f32_16x16x32_bf16 v[36:39], v[210:213], v[186:189], v[36:39]
	v_mfma_f32_16x16x32_bf16 v[32:35], v[218:221], v[186:189], v[32:35]
	v_mfma_f32_16x16x32_bf16 v[20:23], v[210:213], v[194:197], v[20:23]
	v_mfma_f32_16x16x32_bf16 v[16:19], v[218:221], v[194:197], v[16:19]
	v_mfma_f32_16x16x32_bf16 v[4:7], v[210:213], v[202:205], v[4:7]
	v_mfma_f32_16x16x32_bf16 v[0:3], v[218:221], v[202:205], v[0:3]
	v_mfma_f32_16x16x32_bf16 v[52:55], v[214:217], v[182:185], v[52:55]
	v_mfma_f32_16x16x32_bf16 v[48:51], v[222:225], v[182:185], v[48:51]
	v_mfma_f32_16x16x32_bf16 v[36:39], v[214:217], v[190:193], v[36:39]
	v_mfma_f32_16x16x32_bf16 v[32:35], v[222:225], v[190:193], v[32:35]
	v_mfma_f32_16x16x32_bf16 v[20:23], v[214:217], v[198:201], v[20:23]
	v_mfma_f32_16x16x32_bf16 v[16:19], v[222:225], v[198:201], v[16:19]
	v_mfma_f32_16x16x32_bf16 v[4:7], v[214:217], v[206:209], v[4:7]
	v_mfma_f32_16x16x32_bf16 v[0:3], v[222:225], v[206:209], v[0:3]
	s_barrier
	s_setprio 0
	ds_read_b128 v[162:165], v150
	ds_read_b128 v[166:169], v150 offset:1024
	ds_read_b128 v[170:173], v150 offset:2048
	ds_read_b128 v[174:177], v150 offset:3072
	s_add_u32 s12, s20, 0x18000
	s_addc_u32 s13, s21, 0
	s_mov_b32 m0, s24
	ds_read_b128 v[178:181], v148 offset:32768
	ds_read_b128 v[182:185], v148 offset:33792
	ds_read_b128 v[186:189], v148 offset:34816
	ds_read_b128 v[190:193], v148 offset:35840
	ds_read_b128 v[194:197], v148 offset:36864
	ds_read_b128 v[198:201], v148 offset:37888
	ds_read_b128 v[202:205], v148 offset:38912
	ds_read_b128 v[206:209], v148 offset:39936
	global_load_lds_dwordx4 v134, s[12:13]
	s_mov_b32 m0, s25
	s_nop 0
	global_load_lds_dwordx4 v130, s[12:13]
	s_waitcnt lgkmcnt(8)
	s_setprio 1
	s_barrier
	s_waitcnt lgkmcnt(0)
	v_mfma_f32_16x16x32_bf16 v[124:127], v[162:165], v[178:181], v[124:127]
	v_mfma_f32_16x16x32_bf16 v[120:123], v[170:173], v[178:181], v[120:123]
	v_mfma_f32_16x16x32_bf16 v[108:111], v[162:165], v[186:189], v[108:111]
	v_mfma_f32_16x16x32_bf16 v[104:107], v[170:173], v[186:189], v[104:107]
	v_mfma_f32_16x16x32_bf16 v[92:95], v[162:165], v[194:197], v[92:95]
	v_mfma_f32_16x16x32_bf16 v[88:91], v[170:173], v[194:197], v[88:91]
	v_mfma_f32_16x16x32_bf16 v[76:79], v[162:165], v[202:205], v[76:79]
	v_mfma_f32_16x16x32_bf16 v[72:75], v[170:173], v[202:205], v[72:75]
	s_mov_b32 m0, s40
	v_mfma_f32_16x16x32_bf16 v[124:127], v[166:169], v[182:185], v[124:127]
	v_mfma_f32_16x16x32_bf16 v[120:123], v[174:177], v[182:185], v[120:123]
	v_mfma_f32_16x16x32_bf16 v[108:111], v[166:169], v[190:193], v[108:111]
	v_mfma_f32_16x16x32_bf16 v[104:107], v[174:177], v[190:193], v[104:107]
	v_mfma_f32_16x16x32_bf16 v[92:95], v[166:169], v[198:201], v[92:95]
	v_mfma_f32_16x16x32_bf16 v[88:91], v[174:177], v[198:201], v[88:91]
	v_mfma_f32_16x16x32_bf16 v[76:79], v[166:169], v[206:209], v[76:79]
	v_mfma_f32_16x16x32_bf16 v[72:75], v[174:177], v[206:209], v[72:75]
	s_barrier
	s_setprio 0
	v_lshl_add_u64 v[144:145], v[144:145], 0, s[0:1]
	ds_read_b128 v[210:213], v157
	ds_read_b128 v[214:217], v157 offset:1024
	ds_read_b128 v[218:221], v157 offset:2048
	ds_read_b128 v[222:225], v157 offset:3072
	global_load_lds_dwordx4 v[144:145], off
	v_lshl_add_u64 v[144:145], v[226:227], 0, s[0:1]
	s_mov_b32 m0, s41
	s_nop 0
	global_load_lds_dwordx4 v[144:145], off
	s_setprio 1
	s_barrier
; #define PG8_STAGE(bufoff, gbase, voff) do { _Pragma("unroll") for (int _i = 0; _i < 2; ++_i) \
;         __builtin_amdgcn_global_load_lds((const unsigned*)((const char*)(gbase) + (voff)[_i]), (LAS unsigned*)(lds + (bufoff) + ldsw + _i * 8192), 16, 0, 0); } while (0)
; #define PG8_LDA(dst, b, h) do { _Pragma("unroll") for (int m = 0; m < 4; ++m) _Pragma("unroll") for (int k = 0; k < 2; ++k) dst[m][k] = *(const LAS bf16x8*)(lds + PG8_SA(b, h) + aoff + m * 2048 + k * 1024); } while (0)
; #define PG8_MMA(ai, bj, At, Bt) do { __builtin_amdgcn_s_setprio(1); _Pragma("unroll") for (int m = 0; m < 4; ++m) _Pragma("unroll") for (int n = 0; n < 2; ++n) _Pragma("unroll") for (int k = 0; k < 2; ++k) \
;         acc[ai][bj][m][n] = __builtin_amdgcn_mfma_f32_16x16x32_bf16(Bt[n][k], At[m][k], acc[ai][bj][m][n], 0, 0, 0); __builtin_amdgcn_s_setprio(0); } while (0)
; #define PG8_WAIT_V(n) asm volatile("s_waitcnt vmcnt(" #n ")" ::: "memory")
; #define PG8_WAIT_L(n) asm volatile("s_waitcnt lgkmcnt(" #n ")" ::: "memory")
; #define PG8_BAR __builtin_amdgcn_s_barrier()
; #define PG8_SCHED __builtin_amdgcn_sched_barrier(0)
; template <class Epi, class Sched, bool ATILE = false>
; __device__ __forceinline__ void gemm_phase(LAS unsigned char* lds, const Gemm g, const Sched& S, const Epi& E) {
;     ...
;             PG8_LDA(At, 1, 1); PG8_STAGE(PG8_SA(1, 0), a3, voffA);
;             PG8_BAR; PG8_WAIT_L(0); PG8_MMA(1, 0, At, B0); PG8_BAR; PG8_SCHED;
;             PG8_STAGE(PG8_SB(1, 1), b3 + hstepB, voffB);
;             PG8_WAIT_V(6); PG8_BAR; PG8_MMA(1, 1, At, B1); PG8_BAR;
;         }
	s_waitcnt lgkmcnt(0)
	v_mfma_f32_16x16x32_bf16 v[116:119], v[210:213], v[178:181], v[116:119]
	v_mfma_f32_16x16x32_bf16 v[112:115], v[218:221], v[178:181], v[112:115]
	v_mfma_f32_16x16x32_bf16 v[100:103], v[210:213], v[186:189], v[100:103]
	v_mfma_f32_16x16x32_bf16 v[96:99], v[218:221], v[186:189], v[96:99]
	v_mfma_f32_16x16x32_bf16 v[84:87], v[210:213], v[194:197], v[84:87]
	v_mfma_f32_16x16x32_bf16 v[80:83], v[218:221], v[194:197], v[80:83]
	v_mfma_f32_16x16x32_bf16 v[68:71], v[210:213], v[202:205], v[68:71]
	v_mfma_f32_16x16x32_bf16 v[64:67], v[218:221], v[202:205], v[64:67]
	s_mov_b32 m0, s28
	v_mfma_f32_16x16x32_bf16 v[116:119], v[214:217], v[182:185], v[116:119]
	v_mfma_f32_16x16x32_bf16 v[112:115], v[222:225], v[182:185], v[112:115]
	v_mfma_f32_16x16x32_bf16 v[100:103], v[214:217], v[190:193], v[100:103]
	v_mfma_f32_16x16x32_bf16 v[96:99], v[222:225], v[190:193], v[96:99]
	v_mfma_f32_16x16x32_bf16 v[84:87], v[214:217], v[198:201], v[84:87]
	v_mfma_f32_16x16x32_bf16 v[80:83], v[222:225], v[198:201], v[80:83]
	v_mfma_f32_16x16x32_bf16 v[68:71], v[214:217], v[206:209], v[68:71]
	v_mfma_f32_16x16x32_bf16 v[64:67], v[222:225], v[206:209], v[64:67]
	s_barrier
	s_setprio 0
	v_lshl_add_u64 v[144:145], v[228:229], 0, s[0:1]
	ds_read_b128 v[178:181], v148 offset:49152
	ds_read_b128 v[182:185], v148 offset:50176
	ds_read_b128 v[186:189], v148 offset:51200
	ds_read_b128 v[190:193], v148 offset:52224
	ds_read_b128 v[194:197], v148 offset:53248
	ds_read_b128 v[198:201], v148 offset:54272
	ds_read_b128 v[202:205], v148 offset:55296
	ds_read_b128 v[206:209], v148 offset:56320
	global_load_lds_dwordx4 v[144:145], off
	v_lshl_add_u64 v[144:145], v[230:231], 0, s[0:1]
	s_mov_b32 m0, s29
	s_nop 0
	global_load_lds_dwordx4 v[144:145], off
	s_setprio 1
	s_barrier
	s_waitcnt lgkmcnt(0)
	v_mfma_f32_16x16x32_bf16 v[60:63], v[162:165], v[178:181], v[60:63]
	v_mfma_f32_16x16x32_bf16 v[56:59], v[170:173], v[178:181], v[56:59]
	v_mfma_f32_16x16x32_bf16 v[44:47], v[162:165], v[186:189], v[44:47]
	v_mfma_f32_16x16x32_bf16 v[40:43], v[170:173], v[186:189], v[40:43]
	v_mfma_f32_16x16x32_bf16 v[28:31], v[162:165], v[194:197], v[28:31]
	v_mfma_f32_16x16x32_bf16 v[24:27], v[170:173], v[194:197], v[24:27]
	v_mfma_f32_16x16x32_bf16 v[12:15], v[162:165], v[202:205], v[12:15]
	v_mfma_f32_16x16x32_bf16 v[8:11], v[170:173], v[202:205], v[8:11]
	s_add_u32 s12, s18, 0x18080
	v_mfma_f32_16x16x32_bf16 v[60:63], v[166:169], v[182:185], v[60:63]
	s_addc_u32 s13, s19, 0
	v_mfma_f32_16x16x32_bf16 v[56:59], v[174:177], v[182:185], v[56:59]
	s_mov_b32 m0, s42
	v_mfma_f32_16x16x32_bf16 v[44:47], v[166:169], v[190:193], v[44:47]
	v_mfma_f32_16x16x32_bf16 v[40:43], v[174:177], v[190:193], v[40:43]
	v_mfma_f32_16x16x32_bf16 v[28:31], v[166:169], v[198:201], v[28:31]
	v_mfma_f32_16x16x32_bf16 v[24:27], v[174:177], v[198:201], v[24:27]
	v_mfma_f32_16x16x32_bf16 v[12:15], v[166:169], v[206:209], v[12:15]
	v_mfma_f32_16x16x32_bf16 v[8:11], v[174:177], v[206:209], v[8:11]
	s_barrier
	s_setprio 0
	s_nop 0
	global_load_lds_dwordx4 v132, s[12:13]
	s_mov_b32 m0, s43
	s_nop 0
	global_load_lds_dwordx4 v128, s[12:13]
	s_waitcnt vmcnt(6)
	s_setprio 1
	s_barrier
	v_mfma_f32_16x16x32_bf16 v[52:55], v[210:213], v[178:181], v[52:55]
	v_mfma_f32_16x16x32_bf16 v[48:51], v[218:221], v[178:181], v[48:51]
	v_mfma_f32_16x16x32_bf16 v[36:39], v[210:213], v[186:189], v[36:39]
	v_mfma_f32_16x16x32_bf16 v[32:35], v[218:221], v[186:189], v[32:35]
	v_mfma_f32_16x16x32_bf16 v[20:23], v[210:213], v[194:197], v[20:23]
	v_mfma_f32_16x16x32_bf16 v[16:19], v[218:221], v[194:197], v[16:19]
	v_mfma_f32_16x16x32_bf16 v[4:7], v[210:213], v[202:205], v[4:7]
	s_add_u32 s56, s56, 0x100
	v_mfma_f32_16x16x32_bf16 v[0:3], v[218:221], v[202:205], v[0:3]
	s_addc_u32 s57, s57, 0
	v_mfma_f32_16x16x32_bf16 v[52:55], v[214:217], v[182:185], v[52:55]
	s_cmp_ge_i32 s58, s54
	v_mfma_f32_16x16x32_bf16 v[48:51], v[222:225], v[182:185], v[48:51]
	s_mov_b64 s[12:13], s[16:17]
	v_mfma_f32_16x16x32_bf16 v[36:39], v[214:217], v[190:193], v[36:39]
	s_mov_b32 s18, s58
	v_mfma_f32_16x16x32_bf16 v[32:35], v[222:225], v[190:193], v[32:35]
	v_mfma_f32_16x16x32_bf16 v[20:23], v[214:217], v[198:201], v[20:23]
	v_mfma_f32_16x16x32_bf16 v[16:19], v[222:225], v[198:201], v[16:19]
	v_mfma_f32_16x16x32_bf16 v[4:7], v[214:217], v[206:209], v[4:7]
	v_mfma_f32_16x16x32_bf16 v[0:3], v[222:225], v[206:209], v[0:3]
	s_barrier
	s_setprio 0
	s_cbranch_scc0 .LBB0_1426
	s_nop 5
	s_branch .LBB0_1428

; #define PG8_STAGE(bufoff, gbase, voff) do { _Pragma("unroll") for (int _i = 0; _i < 2; ++_i) \
;         __builtin_amdgcn_global_load_lds((const unsigned*)((const char*)(gbase) + (voff)[_i]), (LAS unsigned*)(lds + (bufoff) + ldsw + _i * 8192), 16, 0, 0); } while (0)
; #define PG8_LDA(dst, b, h) do { _Pragma("unroll") for (int m = 0; m < 4; ++m) _Pragma("unroll") for (int k = 0; k < 2; ++k) dst[m][k] = *(const LAS bf16x8*)(lds + PG8_SA(b, h) + aoff + m * 2048 + k * 1024); } while (0)
; #define PG8_LDB(dst, b, h) do { _Pragma("unroll") for (int n = 0; n < 2; ++n) _Pragma("unroll") for (int k = 0; k < 2; ++k) dst[n][k] = *(const LAS bf16x8*)(lds + PG8_SB(b, h) + boff + n * 2048 + k * 1024); } while (0)
; #define PG8_MMA(ai, bj, At, Bt) do { __builtin_amdgcn_s_setprio(1); _Pragma("unroll") for (int m = 0; m < 4; ++m) _Pragma("unroll") for (int n = 0; n < 2; ++n) _Pragma("unroll") for (int k = 0; k < 2; ++k) \
;         acc[ai][bj][m][n] = __builtin_amdgcn_mfma_f32_16x16x32_bf16(Bt[n][k], At[m][k], acc[ai][bj][m][n], 0, 0, 0); __builtin_amdgcn_s_setprio(0); } while (0)
; #define PG8_WAIT_V(n) asm volatile("s_waitcnt vmcnt(" #n ")" ::: "memory")
; #define PG8_WAIT_L(n) asm volatile("s_waitcnt lgkmcnt(" #n ")" ::: "memory")
; template <class Epi, class Sched, bool ATILE = false>
; __device__ __forceinline__ void gemm_phase(LAS unsigned char* lds, const Gemm g, const Sched& S, const Epi& E) {
;     ...
;         for (int t = 0; t < nt; t += 2) {
;             const bool last = (t == nt - 2);
;             const char* a1 = cA + (size_t)(t + 1) * kstepA;
;             const char* a2 = last ? nA : cA + (size_t)(t + 2) * kstepA; const char* b2 = last ? nB : cB + (size_t)(t + 2) * kstep;
;             const char* a3 = a2 + kstepA; const char* b3 = b2 + kstep;
;             PG8_LDB(B0, 0, 0); PG8_SCHED; PG8_LDA(At, 0, 0); PG8_STAGE(PG8_SA(1, 1), a1 + hstepA, voffA);
;             PG8_WAIT_L(8); PG8_BAR; PG8_WAIT_L(0); PG8_MMA(0, 0, At, B0); PG8_BAR; PG8_SCHED;
;             PG8_LDB(B1, 0, 1); PG8_STAGE(PG8_SB(0, 0), b2, voffB);
;             PG8_BAR; PG8_WAIT_L(0); PG8_MMA(0, 1, At, B1); PG8_BAR;
;             PG8_LDA(At, 0, 1); PG8_STAGE(PG8_SA(0, 0), a2, voffA);
;             PG8_BAR; PG8_WAIT_L(0); PG8_MMA(1, 0, At, B0); PG8_BAR; PG8_SCHED;
;             PG8_STAGE(PG8_SB(0, 1), b2 + hstepB, voffB);
;             PG8_WAIT_V(6); PG8_BAR; PG8_MMA(1, 1, At, B1); PG8_BAR;
.LBB0_1517:
	ds_read_b128 v[96:99], v182
	ds_read_b128 v[100:103], v182 offset:1024
	ds_read_b128 v[112:115], v182 offset:2048
	ds_read_b128 v[116:119], v182 offset:3072
	s_add_i32 s54, s26, 2
	s_add_u32 s27, s24, 0xfffc0080
	s_addc_u32 s28, s25, -1
	s_cmp_eq_u32 s45, s26
	s_cselect_b32 s26, s44, s52
	s_cselect_b32 s29, s17, s28
	s_cselect_b32 s28, s42, s27
	s_cselect_b32 s27, s43, s53
	s_add_i32 m0, s23, 0xc000
	ds_read_b128 v[144:147], v183
	ds_read_b128 v[174:177], v183 offset:1024
	ds_read_b128 v[178:181], v183 offset:2048
	ds_read_b128 v[186:189], v183 offset:3072
	ds_read_b128 v[190:193], v183 offset:4096
	ds_read_b128 v[194:197], v183 offset:5120
	ds_read_b128 v[198:201], v183 offset:6144
	ds_read_b128 v[202:205], v183 offset:7168
	global_load_lds_dwordx4 v166, s[24:25]
	s_add_i32 m0, s23, 0xe000
	s_nop 0
	global_load_lds_dwordx4 v168, s[24:25]
	s_waitcnt lgkmcnt(8)
	s_setprio 1
	s_barrier
	s_waitcnt lgkmcnt(0)
	v_mfma_f32_16x16x32_bf16 v[140:143], v[96:99], v[144:147], v[140:143]
	v_mfma_f32_16x16x32_bf16 v[136:139], v[112:115], v[144:147], v[136:139]
	v_mfma_f32_16x16x32_bf16 v[124:127], v[96:99], v[178:181], v[124:127]
	v_mfma_f32_16x16x32_bf16 v[120:123], v[112:115], v[178:181], v[120:123]
	v_mfma_f32_16x16x32_bf16 v[92:95], v[96:99], v[190:193], v[92:95]
	v_mfma_f32_16x16x32_bf16 v[88:91], v[112:115], v[190:193], v[88:91]
	v_mfma_f32_16x16x32_bf16 v[76:79], v[96:99], v[198:201], v[76:79]
	v_mfma_f32_16x16x32_bf16 v[72:75], v[112:115], v[198:201], v[72:75]
	s_add_i32 s55, s39, s5
	v_mfma_f32_16x16x32_bf16 v[140:143], v[100:103], v[174:177], v[140:143]
	s_add_u32 s98, s26, s10
	v_mfma_f32_16x16x32_bf16 v[136:139], v[116:119], v[174:177], v[136:139]
	s_addc_u32 s99, s27, s11
	v_mfma_f32_16x16x32_bf16 v[124:127], v[100:103], v[186:189], v[124:127]
	s_mov_b32 m0, s55
	v_mfma_f32_16x16x32_bf16 v[120:123], v[116:119], v[186:189], v[120:123]
	v_mfma_f32_16x16x32_bf16 v[92:95], v[100:103], v[194:197], v[92:95]
	v_mfma_f32_16x16x32_bf16 v[88:91], v[116:119], v[194:197], v[88:91]
	v_mfma_f32_16x16x32_bf16 v[76:79], v[100:103], v[202:205], v[76:79]
	v_mfma_f32_16x16x32_bf16 v[72:75], v[116:119], v[202:205], v[72:75]
	s_barrier
	s_setprio 0
	ds_read_b128 v[206:209], v184
	ds_read_b128 v[210:213], v184 offset:1024
	ds_read_b128 v[214:217], v184 offset:2048
	ds_read_b128 v[218:221], v184 offset:3072
	global_load_lds_dwordx4 v150, s[26:27]
	s_add_i32 m0, s55, 0x2000
	s_nop 0
	global_load_lds_dwordx4 v164, s[26:27]
	s_setprio 1
	s_barrier
	s_waitcnt lgkmcnt(0)
	v_mfma_f32_16x16x32_bf16 v[132:135], v[206:209], v[144:147], v[132:135]
	v_mfma_f32_16x16x32_bf16 v[128:131], v[214:217], v[144:147], v[128:131]
	v_mfma_f32_16x16x32_bf16 v[108:111], v[206:209], v[178:181], v[108:111]
	v_mfma_f32_16x16x32_bf16 v[104:107], v[214:217], v[178:181], v[104:107]
	v_mfma_f32_16x16x32_bf16 v[84:87], v[206:209], v[190:193], v[84:87]
	v_mfma_f32_16x16x32_bf16 v[80:83], v[214:217], v[190:193], v[80:83]
	v_mfma_f32_16x16x32_bf16 v[68:71], v[206:209], v[198:201], v[68:71]
	v_mfma_f32_16x16x32_bf16 v[64:67], v[214:217], v[198:201], v[64:67]
	s_mov_b32 m0, s23
	v_mfma_f32_16x16x32_bf16 v[132:135], v[210:213], v[174:177], v[132:135]
	s_add_u32 s100, s28, s10
	v_mfma_f32_16x16x32_bf16 v[128:131], v[218:221], v[174:177], v[128:131]
	s_addc_u32 s101, s29, s11
	v_mfma_f32_16x16x32_bf16 v[108:111], v[210:213], v[186:189], v[108:111]
	v_mfma_f32_16x16x32_bf16 v[104:107], v[218:221], v[186:189], v[104:107]
	v_mfma_f32_16x16x32_bf16 v[84:87], v[210:213], v[194:197], v[84:87]
	v_mfma_f32_16x16x32_bf16 v[80:83], v[218:221], v[194:197], v[80:83]
	v_mfma_f32_16x16x32_bf16 v[68:71], v[210:213], v[202:205], v[68:71]
	v_mfma_f32_16x16x32_bf16 v[64:67], v[218:221], v[202:205], v[64:67]
	s_barrier
	s_setprio 0
	ds_read_b128 v[144:147], v183 offset:16384
	ds_read_b128 v[174:177], v183 offset:17408
	ds_read_b128 v[178:181], v183 offset:18432
	ds_read_b128 v[186:189], v183 offset:19456
	ds_read_b128 v[190:193], v183 offset:20480
	ds_read_b128 v[194:197], v183 offset:21504
	ds_read_b128 v[198:201], v183 offset:22528
	ds_read_b128 v[202:205], v183 offset:23552
	global_load_lds_dwordx4 v148, s[28:29]
	s_mov_b32 m0, s30
	s_nop 0
	global_load_lds_dwordx4 v162, s[28:29]
	s_setprio 1
	s_barrier
	s_waitcnt lgkmcnt(0)
	v_mfma_f32_16x16x32_bf16 v[60:63], v[96:99], v[144:147], v[60:63]
	v_mfma_f32_16x16x32_bf16 v[56:59], v[112:115], v[144:147], v[56:59]
	v_mfma_f32_16x16x32_bf16 v[44:47], v[96:99], v[178:181], v[44:47]
	v_mfma_f32_16x16x32_bf16 v[40:43], v[112:115], v[178:181], v[40:43]
	v_mfma_f32_16x16x32_bf16 v[28:31], v[96:99], v[190:193], v[28:31]
	v_mfma_f32_16x16x32_bf16 v[24:27], v[112:115], v[190:193], v[24:27]
	v_mfma_f32_16x16x32_bf16 v[12:15], v[96:99], v[198:201], v[12:15]
	v_mfma_f32_16x16x32_bf16 v[8:11], v[112:115], v[198:201], v[8:11]
	s_add_u32 s56, s26, 0x40000
	v_mfma_f32_16x16x32_bf16 v[60:63], v[100:103], v[174:177], v[60:63]
	s_addc_u32 s57, s27, 0
	v_mfma_f32_16x16x32_bf16 v[56:59], v[116:119], v[174:177], v[56:59]
	s_add_i32 s55, s40, s5
	v_mfma_f32_16x16x32_bf16 v[44:47], v[100:103], v[186:189], v[44:47]
	s_mov_b32 m0, s55
	v_mfma_f32_16x16x32_bf16 v[40:43], v[116:119], v[186:189], v[40:43]
	v_mfma_f32_16x16x32_bf16 v[28:31], v[100:103], v[194:197], v[28:31]
	v_mfma_f32_16x16x32_bf16 v[24:27], v[116:119], v[194:197], v[24:27]
	v_mfma_f32_16x16x32_bf16 v[12:15], v[100:103], v[202:205], v[12:15]
	v_mfma_f32_16x16x32_bf16 v[8:11], v[116:119], v[202:205], v[8:11]
	s_barrier
	s_setprio 0
	s_nop 0
	global_load_lds_dwordx4 v150, s[56:57]
	s_add_i32 m0, s55, 0x2000
	s_nop 0
	global_load_lds_dwordx4 v164, s[56:57]
	s_waitcnt vmcnt(6)
	s_setprio 1
	s_barrier
; #define PG8_STAGE(bufoff, gbase, voff) do { _Pragma("unroll") for (int _i = 0; _i < 2; ++_i) \
;         __builtin_amdgcn_global_load_lds((const unsigned*)((const char*)(gbase) + (voff)[_i]), (LAS unsigned*)(lds + (bufoff) + ldsw + _i * 8192), 16, 0, 0); } while (0)
; #define PG8_LDA(dst, b, h) do { _Pragma("unroll") for (int m = 0; m < 4; ++m) _Pragma("unroll") for (int k = 0; k < 2; ++k) dst[m][k] = *(const LAS bf16x8*)(lds + PG8_SA(b, h) + aoff + m * 2048 + k * 1024); } while (0)
; #define PG8_LDB(dst, b, h) do { _Pragma("unroll") for (int n = 0; n < 2; ++n) _Pragma("unroll") for (int k = 0; k < 2; ++k) dst[n][k] = *(const LAS bf16x8*)(lds + PG8_SB(b, h) + boff + n * 2048 + k * 1024); } while (0)
; #define PG8_MMA(ai, bj, At, Bt) do { __builtin_amdgcn_s_setprio(1); _Pragma("unroll") for (int m = 0; m < 4; ++m) _Pragma("unroll") for (int n = 0; n < 2; ++n) _Pragma("unroll") for (int k = 0; k < 2; ++k) \
;         acc[ai][bj][m][n] = __builtin_amdgcn_mfma_f32_16x16x32_bf16(Bt[n][k], At[m][k], acc[ai][bj][m][n], 0, 0, 0); __builtin_amdgcn_s_setprio(0); } while (0)
; #define PG8_WAIT_V(n) asm volatile("s_waitcnt vmcnt(" #n ")" ::: "memory")
; #define PG8_WAIT_L(n) asm volatile("s_waitcnt lgkmcnt(" #n ")" ::: "memory")
; #define PG8_BAR __builtin_amdgcn_s_barrier()
; #define PG8_SCHED __builtin_amdgcn_sched_barrier(0)
; template <class Epi, class Sched, bool ATILE = false>
; __device__ __forceinline__ void gemm_phase(LAS unsigned char* lds, const Gemm g, const Sched& S, const Epi& E) {
;     ...
;             PG8_WAIT_V(6); PG8_BAR; PG8_MMA(1, 1, At, B1); PG8_BAR;
;             PG8_LDB(B0, 1, 0); PG8_SCHED; PG8_LDA(At, 1, 0); PG8_STAGE(PG8_SA(0, 1), a2 + hstepA, voffA);
;             PG8_WAIT_L(8); PG8_BAR; PG8_WAIT_L(0); PG8_MMA(0, 0, At, B0); PG8_BAR; PG8_SCHED;
;             PG8_LDB(B1, 1, 1); PG8_STAGE(PG8_SB(1, 0), b3, voffB);
;             PG8_BAR; PG8_WAIT_L(0); PG8_MMA(0, 1, At, B1); PG8_BAR;
	v_mfma_f32_16x16x32_bf16 v[52:55], v[206:209], v[144:147], v[52:55]
	v_mfma_f32_16x16x32_bf16 v[48:51], v[214:217], v[144:147], v[48:51]
	v_mfma_f32_16x16x32_bf16 v[36:39], v[206:209], v[178:181], v[36:39]
	v_mfma_f32_16x16x32_bf16 v[32:35], v[214:217], v[178:181], v[32:35]
	v_mfma_f32_16x16x32_bf16 v[20:23], v[206:209], v[190:193], v[20:23]
	v_mfma_f32_16x16x32_bf16 v[16:19], v[214:217], v[190:193], v[16:19]
	v_mfma_f32_16x16x32_bf16 v[4:7], v[206:209], v[198:201], v[4:7]
	v_mfma_f32_16x16x32_bf16 v[0:3], v[214:217], v[198:201], v[0:3]
	s_add_i32 s55, 0, 0x18000
	v_mfma_f32_16x16x32_bf16 v[52:55], v[210:213], v[174:177], v[52:55]
	v_add_u32_e32 v116, s55, v159
	v_mfma_f32_16x16x32_bf16 v[48:51], v[218:221], v[174:177], v[48:51]
	v_mfma_f32_16x16x32_bf16 v[36:39], v[210:213], v[186:189], v[36:39]
	v_mfma_f32_16x16x32_bf16 v[32:35], v[218:221], v[186:189], v[32:35]
	v_mfma_f32_16x16x32_bf16 v[20:23], v[210:213], v[194:197], v[20:23]
	v_mfma_f32_16x16x32_bf16 v[16:19], v[218:221], v[194:197], v[16:19]
	v_mfma_f32_16x16x32_bf16 v[4:7], v[210:213], v[202:205], v[4:7]
	v_mfma_f32_16x16x32_bf16 v[0:3], v[218:221], v[202:205], v[0:3]
	s_barrier
	s_setprio 0
	ds_read_b128 v[96:99], v116
	ds_read_b128 v[100:103], v116 offset:1024
	ds_read_b128 v[112:115], v116 offset:2048
	ds_read_b128 v[116:119], v116 offset:3072
	s_add_u32 s28, s28, 0x40000
	s_addc_u32 s29, s29, 0
	s_mov_b32 m0, s31
	ds_read_b128 v[144:147], v183 offset:32768
	ds_read_b128 v[174:177], v183 offset:33792
	ds_read_b128 v[178:181], v183 offset:34816
	ds_read_b128 v[186:189], v183 offset:35840
	ds_read_b128 v[190:193], v183 offset:36864
	ds_read_b128 v[194:197], v183 offset:37888
	ds_read_b128 v[198:201], v183 offset:38912
	ds_read_b128 v[202:205], v183 offset:39936
	global_load_lds_dwordx4 v148, s[28:29]
	s_mov_b32 m0, s33
	s_nop 0
	global_load_lds_dwordx4 v162, s[28:29]
	s_waitcnt lgkmcnt(8)
	s_setprio 1
	s_barrier
	s_waitcnt lgkmcnt(0)
	v_mfma_f32_16x16x32_bf16 v[140:143], v[96:99], v[144:147], v[140:143]
	v_mfma_f32_16x16x32_bf16 v[136:139], v[112:115], v[144:147], v[136:139]
	v_mfma_f32_16x16x32_bf16 v[124:127], v[96:99], v[178:181], v[124:127]
	v_mfma_f32_16x16x32_bf16 v[120:123], v[112:115], v[178:181], v[120:123]
	v_mfma_f32_16x16x32_bf16 v[92:95], v[96:99], v[190:193], v[92:95]
	v_mfma_f32_16x16x32_bf16 v[88:91], v[112:115], v[190:193], v[88:91]
	v_mfma_f32_16x16x32_bf16 v[76:79], v[96:99], v[198:201], v[76:79]
	v_mfma_f32_16x16x32_bf16 v[72:75], v[112:115], v[198:201], v[72:75]
	s_add_i32 s28, 0, 0x1c000
	v_mfma_f32_16x16x32_bf16 v[140:143], v[100:103], v[174:177], v[140:143]
	s_add_i32 s29, s55, s5
	v_mfma_f32_16x16x32_bf16 v[136:139], v[116:119], v[174:177], v[136:139]
	v_add_u32_e32 v185, s28, v159
	v_mfma_f32_16x16x32_bf16 v[124:127], v[100:103], v[186:189], v[124:127]
	s_mov_b32 m0, s29
	v_mfma_f32_16x16x32_bf16 v[120:123], v[116:119], v[186:189], v[120:123]
	v_mfma_f32_16x16x32_bf16 v[92:95], v[100:103], v[194:197], v[92:95]
	v_mfma_f32_16x16x32_bf16 v[88:91], v[116:119], v[194:197], v[88:91]
	v_mfma_f32_16x16x32_bf16 v[76:79], v[100:103], v[202:205], v[76:79]
	v_mfma_f32_16x16x32_bf16 v[72:75], v[116:119], v[202:205], v[72:75]
	s_barrier
	s_setprio 0
	ds_read_b128 v[206:209], v185
	ds_read_b128 v[210:213], v185 offset:1024
	ds_read_b128 v[214:217], v185 offset:2048
	ds_read_b128 v[218:221], v185 offset:3072
	global_load_lds_dwordx4 v150, s[98:99]
	s_add_i32 m0, s29, 0x2000
	s_nop 0
	global_load_lds_dwordx4 v164, s[98:99]
	s_setprio 1
	s_barrier
; #define PG8_STAGE(bufoff, gbase, voff) do { _Pragma("unroll") for (int _i = 0; _i < 2; ++_i) \
;         __builtin_amdgcn_global_load_lds((const unsigned*)((const char*)(gbase) + (voff)[_i]), (LAS unsigned*)(lds + (bufoff) + ldsw + _i * 8192), 16, 0, 0); } while (0)
; #define PG8_LDA(dst, b, h) do { _Pragma("unroll") for (int m = 0; m < 4; ++m) _Pragma("unroll") for (int k = 0; k < 2; ++k) dst[m][k] = *(const LAS bf16x8*)(lds + PG8_SA(b, h) + aoff + m * 2048 + k * 1024); } while (0)
; #define PG8_MMA(ai, bj, At, Bt) do { __builtin_amdgcn_s_setprio(1); _Pragma("unroll") for (int m = 0; m < 4; ++m) _Pragma("unroll") for (int n = 0; n < 2; ++n) _Pragma("unroll") for (int k = 0; k < 2; ++k) \
;         acc[ai][bj][m][n] = __builtin_amdgcn_mfma_f32_16x16x32_bf16(Bt[n][k], At[m][k], acc[ai][bj][m][n], 0, 0, 0); __builtin_amdgcn_s_setprio(0); } while (0)
; #define PG8_WAIT_V(n) asm volatile("s_waitcnt vmcnt(" #n ")" ::: "memory")
; #define PG8_WAIT_L(n) asm volatile("s_waitcnt lgkmcnt(" #n ")" ::: "memory")
; #define PG8_BAR __builtin_amdgcn_s_barrier()
; #define PG8_SCHED __builtin_amdgcn_sched_barrier(0)
; template <class Epi, class Sched, bool ATILE = false>
; __device__ __forceinline__ void gemm_phase(LAS unsigned char* lds, const Gemm g, const Sched& S, const Epi& E) {
;     ...
;             PG8_BAR; PG8_WAIT_L(0); PG8_MMA(0, 1, At, B1); PG8_BAR;
;             PG8_LDA(At, 1, 1); PG8_STAGE(PG8_SA(1, 0), a3, voffA);
;             PG8_BAR; PG8_WAIT_L(0); PG8_MMA(1, 0, At, B0); PG8_BAR; PG8_SCHED;
;             PG8_STAGE(PG8_SB(1, 1), b3 + hstepB, voffB);
;             PG8_WAIT_V(6); PG8_BAR; PG8_MMA(1, 1, At, B1); PG8_BAR;
;         }
	s_waitcnt lgkmcnt(0)
	v_mfma_f32_16x16x32_bf16 v[132:135], v[206:209], v[144:147], v[132:135]
	v_mfma_f32_16x16x32_bf16 v[128:131], v[214:217], v[144:147], v[128:131]
	v_mfma_f32_16x16x32_bf16 v[108:111], v[206:209], v[178:181], v[108:111]
	v_mfma_f32_16x16x32_bf16 v[104:107], v[214:217], v[178:181], v[104:107]
	v_mfma_f32_16x16x32_bf16 v[84:87], v[206:209], v[190:193], v[84:87]
	v_mfma_f32_16x16x32_bf16 v[80:83], v[214:217], v[190:193], v[80:83]
	v_mfma_f32_16x16x32_bf16 v[68:71], v[206:209], v[198:201], v[68:71]
	v_mfma_f32_16x16x32_bf16 v[64:67], v[214:217], v[198:201], v[64:67]
	s_mov_b32 m0, s35
	v_mfma_f32_16x16x32_bf16 v[132:135], v[210:213], v[174:177], v[132:135]
	v_mfma_f32_16x16x32_bf16 v[128:131], v[218:221], v[174:177], v[128:131]
	v_mfma_f32_16x16x32_bf16 v[108:111], v[210:213], v[186:189], v[108:111]
	v_mfma_f32_16x16x32_bf16 v[104:107], v[218:221], v[186:189], v[104:107]
	v_mfma_f32_16x16x32_bf16 v[84:87], v[210:213], v[194:197], v[84:87]
	v_mfma_f32_16x16x32_bf16 v[80:83], v[218:221], v[194:197], v[80:83]
	v_mfma_f32_16x16x32_bf16 v[68:71], v[210:213], v[202:205], v[68:71]
	v_mfma_f32_16x16x32_bf16 v[64:67], v[218:221], v[202:205], v[64:67]
	s_barrier
	s_setprio 0
	ds_read_b128 v[144:147], v183 offset:49152
	ds_read_b128 v[174:177], v183 offset:50176
	ds_read_b128 v[178:181], v183 offset:51200
	ds_read_b128 v[186:189], v183 offset:52224
	ds_read_b128 v[190:193], v183 offset:53248
	ds_read_b128 v[194:197], v183 offset:54272
	ds_read_b128 v[198:201], v183 offset:55296
	ds_read_b128 v[202:205], v183 offset:56320
	global_load_lds_dwordx4 v148, s[100:101]
	s_mov_b32 m0, s36
	s_nop 0
	global_load_lds_dwordx4 v162, s[100:101]
	s_setprio 1
	s_barrier
	s_waitcnt lgkmcnt(0)
	v_mfma_f32_16x16x32_bf16 v[60:63], v[96:99], v[144:147], v[60:63]
	v_mfma_f32_16x16x32_bf16 v[56:59], v[112:115], v[144:147], v[56:59]
	v_mfma_f32_16x16x32_bf16 v[44:47], v[96:99], v[178:181], v[44:47]
	v_mfma_f32_16x16x32_bf16 v[40:43], v[112:115], v[178:181], v[40:43]
	v_mfma_f32_16x16x32_bf16 v[28:31], v[96:99], v[190:193], v[28:31]
	v_mfma_f32_16x16x32_bf16 v[24:27], v[112:115], v[190:193], v[24:27]
	v_mfma_f32_16x16x32_bf16 v[12:15], v[96:99], v[198:201], v[12:15]
	v_mfma_f32_16x16x32_bf16 v[8:11], v[112:115], v[198:201], v[8:11]
	s_add_u32 s26, s26, 0x40080
	v_mfma_f32_16x16x32_bf16 v[60:63], v[100:103], v[174:177], v[60:63]
	s_addc_u32 s27, s27, 0
	v_mfma_f32_16x16x32_bf16 v[56:59], v[116:119], v[174:177], v[56:59]
	s_add_i32 s28, s28, s5
	v_mfma_f32_16x16x32_bf16 v[44:47], v[100:103], v[186:189], v[44:47]
	s_mov_b32 m0, s28
	v_mfma_f32_16x16x32_bf16 v[40:43], v[116:119], v[186:189], v[40:43]
	v_mfma_f32_16x16x32_bf16 v[28:31], v[100:103], v[194:197], v[28:31]
	v_mfma_f32_16x16x32_bf16 v[24:27], v[116:119], v[194:197], v[24:27]
	v_mfma_f32_16x16x32_bf16 v[12:15], v[100:103], v[202:205], v[12:15]
	v_mfma_f32_16x16x32_bf16 v[8:11], v[116:119], v[202:205], v[8:11]
	s_barrier
	s_setprio 0
	s_nop 0
	global_load_lds_dwordx4 v150, s[26:27]
	s_add_i32 m0, s28, 0x2000
	s_nop 0
	global_load_lds_dwordx4 v164, s[26:27]
	s_waitcnt vmcnt(6)
	s_setprio 1
	s_barrier
	v_mfma_f32_16x16x32_bf16 v[52:55], v[206:209], v[144:147], v[52:55]
	v_mfma_f32_16x16x32_bf16 v[48:51], v[214:217], v[144:147], v[48:51]
	v_mfma_f32_16x16x32_bf16 v[36:39], v[206:209], v[178:181], v[36:39]
	v_mfma_f32_16x16x32_bf16 v[32:35], v[214:217], v[178:181], v[32:35]
	v_mfma_f32_16x16x32_bf16 v[20:23], v[206:209], v[190:193], v[20:23]
	v_mfma_f32_16x16x32_bf16 v[16:19], v[214:217], v[190:193], v[16:19]
	v_mfma_f32_16x16x32_bf16 v[4:7], v[206:209], v[198:201], v[4:7]
	s_add_u32 s24, s24, 0x100
	v_mfma_f32_16x16x32_bf16 v[0:3], v[214:217], v[198:201], v[0:3]
	s_addc_u32 s25, s25, 0
	v_mfma_f32_16x16x32_bf16 v[52:55], v[210:213], v[174:177], v[52:55]
	s_add_u32 s52, s52, 0x100
	v_mfma_f32_16x16x32_bf16 v[48:51], v[218:221], v[174:177], v[48:51]
	s_addc_u32 s53, s53, 0
	v_mfma_f32_16x16x32_bf16 v[36:39], v[210:213], v[186:189], v[36:39]
	s_cmp_ge_i32 s54, s13
	v_mfma_f32_16x16x32_bf16 v[32:35], v[218:221], v[186:189], v[32:35]
	s_mov_b32 s26, s54
	v_mfma_f32_16x16x32_bf16 v[20:23], v[210:213], v[194:197], v[20:23]
	v_mfma_f32_16x16x32_bf16 v[16:19], v[218:221], v[194:197], v[16:19]
	v_mfma_f32_16x16x32_bf16 v[4:7], v[210:213], v[202:205], v[4:7]
	v_mfma_f32_16x16x32_bf16 v[0:3], v[218:221], v[202:205], v[0:3]
	s_barrier
	s_setprio 0
	s_cbranch_scc0 .LBB0_1517
	s_nop 5
	s_branch .LBB0_1508

; #define PG8_STAGE(bufoff, gbase, voff) do { _Pragma("unroll") for (int _i = 0; _i < 2; ++_i) \
;         __builtin_amdgcn_global_load_lds((const unsigned*)((const char*)(gbase) + (voff)[_i]), (LAS unsigned*)(lds + (bufoff) + ldsw + _i * 8192), 16, 0, 0); } while (0)
; #define PG8_LDA(dst, b, h) do { _Pragma("unroll") for (int m = 0; m < 4; ++m) _Pragma("unroll") for (int k = 0; k < 2; ++k) dst[m][k] = *(const LAS bf16x8*)(lds + PG8_SA(b, h) + aoff + m * 2048 + k * 1024); } while (0)
; #define PG8_LDB(dst, b, h) do { _Pragma("unroll") for (int n = 0; n < 2; ++n) _Pragma("unroll") for (int k = 0; k < 2; ++k) dst[n][k] = *(const LAS bf16x8*)(lds + PG8_SB(b, h) + boff + n * 2048 + k * 1024); } while (0)
; #define PG8_MMA(ai, bj, At, Bt) do { __builtin_amdgcn_s_setprio(1); _Pragma("unroll") for (int m = 0; m < 4; ++m) _Pragma("unroll") for (int n = 0; n < 2; ++n) _Pragma("unroll") for (int k = 0; k < 2; ++k) \
;         acc[ai][bj][m][n] = __builtin_amdgcn_mfma_f32_16x16x32_bf16(Bt[n][k], At[m][k], acc[ai][bj][m][n], 0, 0, 0); __builtin_amdgcn_s_setprio(0); } while (0)
; #define PG8_WAIT_V(n) asm volatile("s_waitcnt vmcnt(" #n ")" ::: "memory")
; #define PG8_WAIT_L(n) asm volatile("s_waitcnt lgkmcnt(" #n ")" ::: "memory")
; template <class Epi, class Sched, bool ATILE = false>
; __device__ __forceinline__ void gemm_phase(LAS unsigned char* lds, const Gemm g, const Sched& S, const Epi& E) {
;     ...
;         for (int t = 0; t < nt; t += 2) {
;             const bool last = (t == nt - 2);
;             const char* a1 = cA + (size_t)(t + 1) * kstepA;
;             const char* a2 = last ? nA : cA + (size_t)(t + 2) * kstepA; const char* b2 = last ? nB : cB + (size_t)(t + 2) * kstep;
;             const char* a3 = a2 + kstepA; const char* b3 = b2 + kstep;
;             PG8_LDB(B0, 0, 0); PG8_SCHED; PG8_LDA(At, 0, 0); PG8_STAGE(PG8_SA(1, 1), a1 + hstepA, voffA);
;             PG8_WAIT_L(8); PG8_BAR; PG8_WAIT_L(0); PG8_MMA(0, 0, At, B0); PG8_BAR; PG8_SCHED;
;             PG8_LDB(B1, 0, 1); PG8_STAGE(PG8_SB(0, 0), b2, voffB);
;             PG8_BAR; PG8_WAIT_L(0); PG8_MMA(0, 1, At, B1); PG8_BAR;
;             PG8_LDA(At, 0, 1); PG8_STAGE(PG8_SA(0, 0), a2, voffA);
;             PG8_BAR; PG8_WAIT_L(0); PG8_MMA(1, 0, At, B0); PG8_BAR; PG8_SCHED;
;             PG8_STAGE(PG8_SB(0, 1), b2 + hstepB, voffB);
;             PG8_WAIT_V(6); PG8_BAR; PG8_MMA(1, 1, At, B1); PG8_BAR;
.LBB0_1658:
	s_waitcnt lgkmcnt(0)
	ds_read_b128 v[128:131], v169
	ds_read_b128 v[132:135], v169 offset:1024
	ds_read_b128 v[136:139], v169 offset:2048
	ds_read_b128 v[140:143], v169 offset:3072
	s_add_i32 s29, s27, 2
	s_add_u32 s34, s30, 0x4000
	s_addc_u32 s35, s31, 0
	s_cmp_eq_u32 s11, s27
	s_cselect_b32 s38, s22, s34
	s_cselect_b32 s39, s23, s35
	s_cselect_b32 s34, s24, s13
	s_cselect_b32 s35, s25, s17
	s_add_u32 s36, s38, 0x8000
	s_addc_u32 s37, s39, 0
	s_add_i32 m0, s5, 0xc000
	ds_read_b128 v[144:147], v210
	ds_read_b128 v[148:151], v210 offset:1024
	ds_read_b128 v[192:195], v210 offset:2048
	ds_read_b128 v[196:199], v210 offset:3072
	ds_read_b128 v[200:203], v210 offset:4096
	ds_read_b128 v[204:207], v210 offset:5120
	ds_read_b128 v[214:217], v210 offset:6144
	ds_read_b128 v[218:221], v210 offset:7168
	global_load_lds_dwordx4 v186, s[30:31]
	s_add_i32 m0, s5, 0xe000
	s_nop 0
	global_load_lds_dwordx4 v188, s[30:31]
	s_waitcnt lgkmcnt(8)
	s_setprio 1
	s_barrier
	s_waitcnt lgkmcnt(0)
	v_mfma_f32_16x16x32_bf16 v[120:123], v[128:131], v[144:147], v[120:123]
	v_mfma_f32_16x16x32_bf16 v[116:119], v[136:139], v[144:147], v[116:119]
	v_mfma_f32_16x16x32_bf16 v[108:111], v[128:131], v[192:195], v[108:111]
	v_mfma_f32_16x16x32_bf16 v[100:103], v[136:139], v[192:195], v[100:103]
	v_mfma_f32_16x16x32_bf16 v[92:95], v[128:131], v[200:203], v[92:95]
	v_mfma_f32_16x16x32_bf16 v[84:87], v[136:139], v[200:203], v[84:87]
	v_mfma_f32_16x16x32_bf16 v[76:79], v[128:131], v[214:217], v[76:79]
	v_mfma_f32_16x16x32_bf16 v[68:71], v[136:139], v[214:217], v[68:71]
	s_add_i32 s27, s52, s4
	v_mfma_f32_16x16x32_bf16 v[120:123], v[132:135], v[148:151], v[120:123]
	s_add_u32 s98, s34, s8
	v_mfma_f32_16x16x32_bf16 v[116:119], v[140:143], v[148:151], v[116:119]
	s_addc_u32 s99, s35, s9
	v_mfma_f32_16x16x32_bf16 v[108:111], v[132:135], v[196:199], v[108:111]
	s_mov_b32 m0, s27
	v_mfma_f32_16x16x32_bf16 v[100:103], v[140:143], v[196:199], v[100:103]
	v_mfma_f32_16x16x32_bf16 v[92:95], v[132:135], v[204:207], v[92:95]
	v_mfma_f32_16x16x32_bf16 v[84:87], v[140:143], v[204:207], v[84:87]
	v_mfma_f32_16x16x32_bf16 v[76:79], v[132:135], v[218:221], v[76:79]
	v_mfma_f32_16x16x32_bf16 v[68:71], v[140:143], v[218:221], v[68:71]
	s_barrier
	s_setprio 0
	ds_read_b128 v[222:225], v211
	ds_read_b128 v[226:229], v211 offset:1024
	ds_read_b128 v[230:233], v211 offset:2048
	ds_read_b128 v[234:237], v211 offset:3072
	global_load_lds_dwordx4 v162, s[34:35]
	s_add_i32 m0, s27, 0x2000
	s_nop 0
	global_load_lds_dwordx4 v166, s[34:35]
	s_setprio 1
	s_barrier
	s_waitcnt lgkmcnt(0)
	v_mfma_f32_16x16x32_bf16 v[124:127], v[222:225], v[144:147], v[124:127]
	v_mfma_f32_16x16x32_bf16 v[112:115], v[230:233], v[144:147], v[112:115]
	v_mfma_f32_16x16x32_bf16 v[104:107], v[222:225], v[192:195], v[104:107]
	v_mfma_f32_16x16x32_bf16 v[96:99], v[230:233], v[192:195], v[96:99]
	v_mfma_f32_16x16x32_bf16 v[88:91], v[222:225], v[200:203], v[88:91]
	v_mfma_f32_16x16x32_bf16 v[80:83], v[230:233], v[200:203], v[80:83]
	v_mfma_f32_16x16x32_bf16 v[72:75], v[222:225], v[214:217], v[72:75]
	v_mfma_f32_16x16x32_bf16 v[64:67], v[230:233], v[214:217], v[64:67]
	s_mov_b32 m0, s5
	v_mfma_f32_16x16x32_bf16 v[124:127], v[226:229], v[148:151], v[124:127]
	v_mfma_f32_16x16x32_bf16 v[112:115], v[234:237], v[148:151], v[112:115]
	v_mfma_f32_16x16x32_bf16 v[104:107], v[226:229], v[196:199], v[104:107]
	v_mfma_f32_16x16x32_bf16 v[96:99], v[234:237], v[196:199], v[96:99]
	v_mfma_f32_16x16x32_bf16 v[88:91], v[226:229], v[204:207], v[88:91]
	v_mfma_f32_16x16x32_bf16 v[80:83], v[234:237], v[204:207], v[80:83]
	v_mfma_f32_16x16x32_bf16 v[72:75], v[226:229], v[218:221], v[72:75]
	v_mfma_f32_16x16x32_bf16 v[64:67], v[234:237], v[218:221], v[64:67]
	s_barrier
	s_setprio 0
	ds_read_b128 v[144:147], v210 offset:16384
	ds_read_b128 v[148:151], v210 offset:17408
	ds_read_b128 v[192:195], v210 offset:18432
	ds_read_b128 v[196:199], v210 offset:19456
	ds_read_b128 v[200:203], v210 offset:20480
	ds_read_b128 v[204:207], v210 offset:21504
	ds_read_b128 v[214:217], v210 offset:22528
	ds_read_b128 v[218:221], v210 offset:23552
	global_load_lds_dwordx4 v160, s[38:39]
	s_mov_b32 m0, s33
	s_nop 0
	global_load_lds_dwordx4 v164, s[38:39]
	s_setprio 1
	s_barrier
	s_waitcnt lgkmcnt(0)
	v_mfma_f32_16x16x32_bf16 v[60:63], v[128:131], v[144:147], v[60:63]
	v_mfma_f32_16x16x32_bf16 v[56:59], v[136:139], v[144:147], v[56:59]
	v_mfma_f32_16x16x32_bf16 v[44:47], v[128:131], v[192:195], v[44:47]
	v_mfma_f32_16x16x32_bf16 v[40:43], v[136:139], v[192:195], v[40:43]
	v_mfma_f32_16x16x32_bf16 v[28:31], v[128:131], v[200:203], v[28:31]
	v_mfma_f32_16x16x32_bf16 v[24:27], v[136:139], v[200:203], v[24:27]
	v_mfma_f32_16x16x32_bf16 v[12:15], v[128:131], v[214:217], v[12:15]
	v_mfma_f32_16x16x32_bf16 v[8:11], v[136:139], v[214:217], v[8:11]
	s_add_u32 s56, s34, 0x80000
	v_mfma_f32_16x16x32_bf16 v[60:63], v[132:135], v[148:151], v[60:63]
	s_addc_u32 s57, s35, 0
	v_mfma_f32_16x16x32_bf16 v[56:59], v[140:143], v[148:151], v[56:59]
	s_add_i32 s27, s53, s4
	v_mfma_f32_16x16x32_bf16 v[44:47], v[132:135], v[196:199], v[44:47]
	s_mov_b32 m0, s27
	v_mfma_f32_16x16x32_bf16 v[40:43], v[140:143], v[196:199], v[40:43]
	v_mfma_f32_16x16x32_bf16 v[28:31], v[132:135], v[204:207], v[28:31]
	v_mfma_f32_16x16x32_bf16 v[24:27], v[140:143], v[204:207], v[24:27]
	v_mfma_f32_16x16x32_bf16 v[12:15], v[132:135], v[218:221], v[12:15]
	v_mfma_f32_16x16x32_bf16 v[8:11], v[140:143], v[218:221], v[8:11]
	s_barrier
	s_setprio 0
	s_nop 0
	global_load_lds_dwordx4 v162, s[56:57]
	s_add_i32 m0, s27, 0x2000
	s_nop 0
	global_load_lds_dwordx4 v166, s[56:57]
	s_waitcnt vmcnt(6)
	s_setprio 1
	s_barrier
; #define PG8_STAGE(bufoff, gbase, voff) do { _Pragma("unroll") for (int _i = 0; _i < 2; ++_i) \
;         __builtin_amdgcn_global_load_lds((const unsigned*)((const char*)(gbase) + (voff)[_i]), (LAS unsigned*)(lds + (bufoff) + ldsw + _i * 8192), 16, 0, 0); } while (0)
; #define PG8_LDA(dst, b, h) do { _Pragma("unroll") for (int m = 0; m < 4; ++m) _Pragma("unroll") for (int k = 0; k < 2; ++k) dst[m][k] = *(const LAS bf16x8*)(lds + PG8_SA(b, h) + aoff + m * 2048 + k * 1024); } while (0)
; #define PG8_LDB(dst, b, h) do { _Pragma("unroll") for (int n = 0; n < 2; ++n) _Pragma("unroll") for (int k = 0; k < 2; ++k) dst[n][k] = *(const LAS bf16x8*)(lds + PG8_SB(b, h) + boff + n * 2048 + k * 1024); } while (0)
; #define PG8_MMA(ai, bj, At, Bt) do { __builtin_amdgcn_s_setprio(1); _Pragma("unroll") for (int m = 0; m < 4; ++m) _Pragma("unroll") for (int n = 0; n < 2; ++n) _Pragma("unroll") for (int k = 0; k < 2; ++k) \
;         acc[ai][bj][m][n] = __builtin_amdgcn_mfma_f32_16x16x32_bf16(Bt[n][k], At[m][k], acc[ai][bj][m][n], 0, 0, 0); __builtin_amdgcn_s_setprio(0); } while (0)
; #define PG8_WAIT_V(n) asm volatile("s_waitcnt vmcnt(" #n ")" ::: "memory")
; #define PG8_WAIT_L(n) asm volatile("s_waitcnt lgkmcnt(" #n ")" ::: "memory")
; #define PG8_BAR __builtin_amdgcn_s_barrier()
; #define PG8_SCHED __builtin_amdgcn_sched_barrier(0)
; template <class Epi, class Sched, bool ATILE = false>
; __device__ __forceinline__ void gemm_phase(LAS unsigned char* lds, const Gemm g, const Sched& S, const Epi& E) {
;     ...
;             PG8_WAIT_V(6); PG8_BAR; PG8_MMA(1, 1, At, B1); PG8_BAR;
;             PG8_LDB(B0, 1, 0); PG8_SCHED; PG8_LDA(At, 1, 0); PG8_STAGE(PG8_SA(0, 1), a2 + hstepA, voffA);
;             PG8_WAIT_L(8); PG8_BAR; PG8_WAIT_L(0); PG8_MMA(0, 0, At, B0); PG8_BAR; PG8_SCHED;
;             PG8_LDB(B1, 1, 1); PG8_STAGE(PG8_SB(1, 0), b3, voffB);
;             PG8_BAR; PG8_WAIT_L(0); PG8_MMA(0, 1, At, B1); PG8_BAR;
	v_mfma_f32_16x16x32_bf16 v[52:55], v[222:225], v[144:147], v[52:55]
	v_mfma_f32_16x16x32_bf16 v[48:51], v[230:233], v[144:147], v[48:51]
	v_mfma_f32_16x16x32_bf16 v[36:39], v[222:225], v[192:195], v[36:39]
	v_mfma_f32_16x16x32_bf16 v[32:35], v[230:233], v[192:195], v[32:35]
	v_mfma_f32_16x16x32_bf16 v[20:23], v[222:225], v[200:203], v[20:23]
	v_mfma_f32_16x16x32_bf16 v[16:19], v[230:233], v[200:203], v[16:19]
	v_mfma_f32_16x16x32_bf16 v[4:7], v[222:225], v[214:217], v[4:7]
	v_mfma_f32_16x16x32_bf16 v[0:3], v[230:233], v[214:217], v[0:3]
	s_add_i32 s27, 0, 0x18000
	v_mfma_f32_16x16x32_bf16 v[52:55], v[226:229], v[148:151], v[52:55]
	v_add_u32_e32 v140, s27, v157
	v_mfma_f32_16x16x32_bf16 v[48:51], v[234:237], v[148:151], v[48:51]
	v_mfma_f32_16x16x32_bf16 v[36:39], v[226:229], v[196:199], v[36:39]
	v_mfma_f32_16x16x32_bf16 v[32:35], v[234:237], v[196:199], v[32:35]
	v_mfma_f32_16x16x32_bf16 v[20:23], v[226:229], v[204:207], v[20:23]
	v_mfma_f32_16x16x32_bf16 v[16:19], v[234:237], v[204:207], v[16:19]
	v_mfma_f32_16x16x32_bf16 v[4:7], v[226:229], v[218:221], v[4:7]
	v_mfma_f32_16x16x32_bf16 v[0:3], v[234:237], v[218:221], v[0:3]
	s_barrier
	s_setprio 0
	ds_read_b128 v[128:131], v140
	ds_read_b128 v[132:135], v140 offset:1024
	ds_read_b128 v[136:139], v140 offset:2048
	ds_read_b128 v[140:143], v140 offset:3072
	s_add_u32 s38, s38, 0x4000
	s_addc_u32 s39, s39, 0
	s_mov_b32 m0, s40
	ds_read_b128 v[144:147], v210 offset:32768
	ds_read_b128 v[148:151], v210 offset:33792
	ds_read_b128 v[192:195], v210 offset:34816
	ds_read_b128 v[196:199], v210 offset:35840
	ds_read_b128 v[200:203], v210 offset:36864
	ds_read_b128 v[204:207], v210 offset:37888
	ds_read_b128 v[214:217], v210 offset:38912
	ds_read_b128 v[218:221], v210 offset:39936
	global_load_lds_dwordx4 v160, s[38:39]
	s_mov_b32 m0, s41
	s_nop 0
	global_load_lds_dwordx4 v164, s[38:39]
	s_waitcnt lgkmcnt(8)
	s_setprio 1
	s_barrier
	s_waitcnt lgkmcnt(0)
	v_mfma_f32_16x16x32_bf16 v[120:123], v[128:131], v[144:147], v[120:123]
	v_mfma_f32_16x16x32_bf16 v[116:119], v[136:139], v[144:147], v[116:119]
	v_mfma_f32_16x16x32_bf16 v[108:111], v[128:131], v[192:195], v[108:111]
	v_mfma_f32_16x16x32_bf16 v[100:103], v[136:139], v[192:195], v[100:103]
	v_mfma_f32_16x16x32_bf16 v[92:95], v[128:131], v[200:203], v[92:95]
	v_mfma_f32_16x16x32_bf16 v[84:87], v[136:139], v[200:203], v[84:87]
	v_mfma_f32_16x16x32_bf16 v[76:79], v[128:131], v[214:217], v[76:79]
	v_mfma_f32_16x16x32_bf16 v[68:71], v[136:139], v[214:217], v[68:71]
	s_add_i32 s38, 0, 0x1c000
	v_mfma_f32_16x16x32_bf16 v[120:123], v[132:135], v[148:151], v[120:123]
	s_add_i32 s27, s27, s4
	v_mfma_f32_16x16x32_bf16 v[116:119], v[140:143], v[148:151], v[116:119]
	v_add_u32_e32 v213, s38, v157
	v_mfma_f32_16x16x32_bf16 v[108:111], v[132:135], v[196:199], v[108:111]
	s_mov_b32 m0, s27
	v_mfma_f32_16x16x32_bf16 v[100:103], v[140:143], v[196:199], v[100:103]
	v_mfma_f32_16x16x32_bf16 v[92:95], v[132:135], v[204:207], v[92:95]
	v_mfma_f32_16x16x32_bf16 v[84:87], v[140:143], v[204:207], v[84:87]
	v_mfma_f32_16x16x32_bf16 v[76:79], v[132:135], v[218:221], v[76:79]
	v_mfma_f32_16x16x32_bf16 v[68:71], v[140:143], v[218:221], v[68:71]
	s_barrier
	s_setprio 0
	ds_read_b128 v[222:225], v213
	ds_read_b128 v[226:229], v213 offset:1024
	ds_read_b128 v[230:233], v213 offset:2048
	ds_read_b128 v[234:237], v213 offset:3072
	global_load_lds_dwordx4 v162, s[98:99]
	s_add_i32 m0, s27, 0x2000
	s_nop 0
	global_load_lds_dwordx4 v166, s[98:99]
	s_setprio 1
	s_barrier
; #define PG8_STAGE(bufoff, gbase, voff) do { _Pragma("unroll") for (int _i = 0; _i < 2; ++_i) \
;         __builtin_amdgcn_global_load_lds((const unsigned*)((const char*)(gbase) + (voff)[_i]), (LAS unsigned*)(lds + (bufoff) + ldsw + _i * 8192), 16, 0, 0); } while (0)
; #define PG8_LDA(dst, b, h) do { _Pragma("unroll") for (int m = 0; m < 4; ++m) _Pragma("unroll") for (int k = 0; k < 2; ++k) dst[m][k] = *(const LAS bf16x8*)(lds + PG8_SA(b, h) + aoff + m * 2048 + k * 1024); } while (0)
; #define PG8_LDB(dst, b, h) do { _Pragma("unroll") for (int n = 0; n < 2; ++n) _Pragma("unroll") for (int k = 0; k < 2; ++k) dst[n][k] = *(const LAS bf16x8*)(lds + PG8_SB(b, h) + boff + n * 2048 + k * 1024); } while (0)
; #define PG8_MMA(ai, bj, At, Bt) do { __builtin_amdgcn_s_setprio(1); _Pragma("unroll") for (int m = 0; m < 4; ++m) _Pragma("unroll") for (int n = 0; n < 2; ++n) _Pragma("unroll") for (int k = 0; k < 2; ++k) \
;         acc[ai][bj][m][n] = __builtin_amdgcn_mfma_f32_16x16x32_bf16(Bt[n][k], At[m][k], acc[ai][bj][m][n], 0, 0, 0); __builtin_amdgcn_s_setprio(0); } while (0)
; #define PG8_WAIT_V(n) asm volatile("s_waitcnt vmcnt(" #n ")" ::: "memory")
; #define PG8_WAIT_L(n) asm volatile("s_waitcnt lgkmcnt(" #n ")" ::: "memory")
; template <class Epi, class Sched, bool ATILE = false>
; __device__ __forceinline__ void gemm_phase(LAS unsigned char* lds, const Gemm g, const Sched& S, const Epi& E) {
;     ...
;             PG8_BAR; PG8_WAIT_L(0); PG8_MMA(0, 1, At, B1); PG8_BAR;
;             PG8_LDA(At, 0, 1); PG8_STAGE(PG8_SA(0, 0), a2, voffA);
;             PG8_BAR; PG8_WAIT_L(0); PG8_MMA(1, 0, At, B0); PG8_BAR; PG8_SCHED;
;             PG8_STAGE(PG8_SB(0, 1), b2 + hstepB, voffB);
;             PG8_WAIT_V(6); PG8_BAR; PG8_MMA(1, 1, At, B1); PG8_BAR;
;             PG8_LDB(B0, 1, 0); PG8_SCHED; PG8_LDA(At, 1, 0); PG8_STAGE(PG8_SA(0, 1), a2 + hstepA, voffA);
;             PG8_WAIT_L(8); PG8_BAR; PG8_WAIT_L(0); PG8_MMA(0, 0, At, B0); PG8_BAR; PG8_SCHED;
;             PG8_LDB(B1, 1, 1); PG8_STAGE(PG8_SB(1, 0), b3, voffB);
;             PG8_BAR; PG8_WAIT_L(0); PG8_MMA(0, 1, At, B1); PG8_BAR;
;             PG8_LDA(At, 1, 1); PG8_STAGE(PG8_SA(1, 0), a3, voffA);
;             PG8_BAR; PG8_WAIT_L(0); PG8_MMA(1, 0, At, B0); PG8_BAR; PG8_SCHED;
;             PG8_STAGE(PG8_SB(1, 1), b3 + hstepB, voffB);
;             PG8_WAIT_V(6); PG8_BAR; PG8_MMA(1, 1, At, B1); PG8_BAR;
	s_waitcnt lgkmcnt(0)
	v_mfma_f32_16x16x32_bf16 v[124:127], v[222:225], v[144:147], v[124:127]
	v_mfma_f32_16x16x32_bf16 v[112:115], v[230:233], v[144:147], v[112:115]
	v_mfma_f32_16x16x32_bf16 v[104:107], v[222:225], v[192:195], v[104:107]
	v_mfma_f32_16x16x32_bf16 v[96:99], v[230:233], v[192:195], v[96:99]
	v_mfma_f32_16x16x32_bf16 v[88:91], v[222:225], v[200:203], v[88:91]
	v_mfma_f32_16x16x32_bf16 v[80:83], v[230:233], v[200:203], v[80:83]
	v_mfma_f32_16x16x32_bf16 v[72:75], v[222:225], v[214:217], v[72:75]
	v_mfma_f32_16x16x32_bf16 v[64:67], v[230:233], v[214:217], v[64:67]
	s_mov_b32 m0, s43
	v_mfma_f32_16x16x32_bf16 v[124:127], v[226:229], v[148:151], v[124:127]
	v_mfma_f32_16x16x32_bf16 v[112:115], v[234:237], v[148:151], v[112:115]
	v_mfma_f32_16x16x32_bf16 v[104:107], v[226:229], v[196:199], v[104:107]
	v_mfma_f32_16x16x32_bf16 v[96:99], v[234:237], v[196:199], v[96:99]
	v_mfma_f32_16x16x32_bf16 v[88:91], v[226:229], v[204:207], v[88:91]
	v_mfma_f32_16x16x32_bf16 v[80:83], v[234:237], v[204:207], v[80:83]
	v_mfma_f32_16x16x32_bf16 v[72:75], v[226:229], v[218:221], v[72:75]
	v_mfma_f32_16x16x32_bf16 v[64:67], v[234:237], v[218:221], v[64:67]
	s_barrier
	s_setprio 0
	ds_read_b128 v[144:147], v210 offset:49152
	ds_read_b128 v[148:151], v210 offset:50176
	ds_read_b128 v[192:195], v210 offset:51200
	ds_read_b128 v[196:199], v210 offset:52224
	ds_read_b128 v[200:203], v210 offset:53248
	ds_read_b128 v[204:207], v210 offset:54272
	ds_read_b128 v[214:217], v210 offset:55296
	ds_read_b128 v[218:221], v210 offset:56320
	global_load_lds_dwordx4 v160, s[36:37]
	s_mov_b32 m0, s44
	s_nop 0
	global_load_lds_dwordx4 v164, s[36:37]
	s_setprio 1
	s_barrier
	s_waitcnt lgkmcnt(0)
	v_mfma_f32_16x16x32_bf16 v[60:63], v[128:131], v[144:147], v[60:63]
	v_mfma_f32_16x16x32_bf16 v[56:59], v[136:139], v[144:147], v[56:59]
	v_mfma_f32_16x16x32_bf16 v[44:47], v[128:131], v[192:195], v[44:47]
	v_mfma_f32_16x16x32_bf16 v[40:43], v[136:139], v[192:195], v[40:43]
	v_mfma_f32_16x16x32_bf16 v[28:31], v[128:131], v[200:203], v[28:31]
	v_mfma_f32_16x16x32_bf16 v[24:27], v[136:139], v[200:203], v[24:27]
	v_mfma_f32_16x16x32_bf16 v[12:15], v[128:131], v[214:217], v[12:15]
	v_mfma_f32_16x16x32_bf16 v[8:11], v[136:139], v[214:217], v[8:11]
	s_add_u32 s34, s34, 0x80080
	v_mfma_f32_16x16x32_bf16 v[60:63], v[132:135], v[148:151], v[60:63]
	s_addc_u32 s35, s35, 0
	v_mfma_f32_16x16x32_bf16 v[56:59], v[140:143], v[148:151], v[56:59]
	s_add_i32 s27, s38, s4
	v_mfma_f32_16x16x32_bf16 v[44:47], v[132:135], v[196:199], v[44:47]
	s_mov_b32 m0, s27
	v_mfma_f32_16x16x32_bf16 v[40:43], v[140:143], v[196:199], v[40:43]
	v_mfma_f32_16x16x32_bf16 v[28:31], v[132:135], v[204:207], v[28:31]
	v_mfma_f32_16x16x32_bf16 v[24:27], v[140:143], v[204:207], v[24:27]
	v_mfma_f32_16x16x32_bf16 v[12:15], v[132:135], v[218:221], v[12:15]
	v_mfma_f32_16x16x32_bf16 v[8:11], v[140:143], v[218:221], v[8:11]
	s_barrier
	s_setprio 0
	s_nop 0
	global_load_lds_dwordx4 v162, s[34:35]
	s_add_i32 m0, s27, 0x2000
	s_nop 0
	global_load_lds_dwordx4 v166, s[34:35]
	s_waitcnt vmcnt(6)
	s_setprio 1
	s_barrier
	v_mfma_f32_16x16x32_bf16 v[52:55], v[222:225], v[144:147], v[52:55]
	v_mfma_f32_16x16x32_bf16 v[48:51], v[230:233], v[144:147], v[48:51]
	v_mfma_f32_16x16x32_bf16 v[36:39], v[222:225], v[192:195], v[36:39]
	v_mfma_f32_16x16x32_bf16 v[32:35], v[230:233], v[192:195], v[32:35]
	v_mfma_f32_16x16x32_bf16 v[20:23], v[222:225], v[200:203], v[20:23]
	v_mfma_f32_16x16x32_bf16 v[16:19], v[230:233], v[200:203], v[16:19]
	v_mfma_f32_16x16x32_bf16 v[4:7], v[222:225], v[214:217], v[4:7]
	s_add_u32 s13, s13, 0x100
	v_mfma_f32_16x16x32_bf16 v[0:3], v[230:233], v[214:217], v[0:3]
	s_addc_u32 s17, s17, 0
	v_mfma_f32_16x16x32_bf16 v[52:55], v[226:229], v[148:151], v[52:55]
	s_add_u32 s30, s30, 0x10000
	v_mfma_f32_16x16x32_bf16 v[48:51], v[234:237], v[148:151], v[48:51]
	s_addc_u32 s31, s31, 0
	v_mfma_f32_16x16x32_bf16 v[36:39], v[226:229], v[196:199], v[36:39]
	s_cmp_ge_i32 s29, s1
	v_mfma_f32_16x16x32_bf16 v[32:35], v[234:237], v[196:199], v[32:35]
	s_mov_b32 s27, s29
	v_mfma_f32_16x16x32_bf16 v[20:23], v[226:229], v[204:207], v[20:23]
	v_mfma_f32_16x16x32_bf16 v[16:19], v[234:237], v[204:207], v[16:19]
	v_mfma_f32_16x16x32_bf16 v[4:7], v[226:229], v[218:221], v[4:7]
	v_mfma_f32_16x16x32_bf16 v[0:3], v[234:237], v[218:221], v[0:3]
	s_barrier
	s_setprio 0
	s_cbranch_scc0 .LBB0_1658
	s_nop 5
	s_branch .LBB0_1662

; #define PG8_STAGE(bufoff, gbase, voff) do { _Pragma("unroll") for (int _i = 0; _i < 2; ++_i) \
;         __builtin_amdgcn_global_load_lds((const unsigned*)((const char*)(gbase) + (voff)[_i]), (LAS unsigned*)(lds + (bufoff) + ldsw + _i * 8192), 16, 0, 0); } while (0)
; #define PG8_LDA(dst, b, h) do { _Pragma("unroll") for (int m = 0; m < 4; ++m) _Pragma("unroll") for (int k = 0; k < 2; ++k) dst[m][k] = *(const LAS bf16x8*)(lds + PG8_SA(b, h) + aoff + m * 2048 + k * 1024); } while (0)
; #define PG8_LDB(dst, b, h) do { _Pragma("unroll") for (int n = 0; n < 2; ++n) _Pragma("unroll") for (int k = 0; k < 2; ++k) dst[n][k] = *(const LAS bf16x8*)(lds + PG8_SB(b, h) + boff + n * 2048 + k * 1024); } while (0)
; #define PG8_MMA(ai, bj, At, Bt) do { __builtin_amdgcn_s_setprio(1); _Pragma("unroll") for (int m = 0; m < 4; ++m) _Pragma("unroll") for (int n = 0; n < 2; ++n) _Pragma("unroll") for (int k = 0; k < 2; ++k) \
;         acc[ai][bj][m][n] = __builtin_amdgcn_mfma_f32_16x16x32_bf16(Bt[n][k], At[m][k], acc[ai][bj][m][n], 0, 0, 0); __builtin_amdgcn_s_setprio(0); } while (0)
; #define PG8_WAIT_V(n) asm volatile("s_waitcnt vmcnt(" #n ")" ::: "memory")
; #define PG8_WAIT_L(n) asm volatile("s_waitcnt lgkmcnt(" #n ")" ::: "memory")
; template <class Epi, class Sched, bool ATILE = false>
; __device__ __forceinline__ void gemm_phase(LAS unsigned char* lds, const Gemm g, const Sched& S, const Epi& E) {
;     ...
;         for (int t = 0; t < nt; t += 2) {
;             const bool last = (t == nt - 2);
;             const char* a1 = cA + (size_t)(t + 1) * kstepA;
;             const char* a2 = last ? nA : cA + (size_t)(t + 2) * kstepA; const char* b2 = last ? nB : cB + (size_t)(t + 2) * kstep;
;             const char* a3 = a2 + kstepA; const char* b3 = b2 + kstep;
;             PG8_LDB(B0, 0, 0); PG8_SCHED; PG8_LDA(At, 0, 0); PG8_STAGE(PG8_SA(1, 1), a1 + hstepA, voffA);
;             PG8_WAIT_L(8); PG8_BAR; PG8_WAIT_L(0); PG8_MMA(0, 0, At, B0); PG8_BAR; PG8_SCHED;
;             PG8_LDB(B1, 0, 1); PG8_STAGE(PG8_SB(0, 0), b2, voffB);
;             PG8_BAR; PG8_WAIT_L(0); PG8_MMA(0, 1, At, B1); PG8_BAR;
;             PG8_LDA(At, 0, 1); PG8_STAGE(PG8_SA(0, 0), a2, voffA);
;             PG8_BAR; PG8_WAIT_L(0); PG8_MMA(1, 0, At, B0); PG8_BAR; PG8_SCHED;
;             PG8_STAGE(PG8_SB(0, 1), b2 + hstepB, voffB);
;             PG8_WAIT_V(6); PG8_BAR; PG8_MMA(1, 1, At, B1); PG8_BAR;
.LBB0_1812:
	ds_read_b128 v[176:179], v139
	ds_read_b128 v[180:183], v139 offset:1024
	ds_read_b128 v[184:187], v139 offset:2048
	ds_read_b128 v[188:191], v139 offset:3072
	s_add_i32 s34, s8, 2
	s_add_u32 s9, s6, 0xfff80080
	s_addc_u32 s10, s7, -1
	s_cmp_eq_u32 s19, s8
	s_cselect_b32 s8, s18, s25
	s_cselect_b32 s11, s13, s10
	s_cselect_b32 s10, s16, s9
	s_cselect_b32 s9, s17, s27
	s_add_i32 m0, s37, 0xc000
	ds_read_b128 v[192:195], v159
	ds_read_b128 v[196:199], v159 offset:1024
	ds_read_b128 v[200:203], v159 offset:2048
	ds_read_b128 v[204:207], v159 offset:3072
	ds_read_b128 v[208:211], v159 offset:4096
	ds_read_b128 v[212:215], v159 offset:5120
	ds_read_b128 v[216:219], v159 offset:6144
	ds_read_b128 v[220:223], v159 offset:7168
	global_load_lds_dwordx4 v164, s[6:7]
	s_add_i32 m0, s37, 0xe000
	s_nop 0
	global_load_lds_dwordx4 v166, s[6:7]
	s_waitcnt lgkmcnt(8)
	s_setprio 1
	s_barrier
	s_waitcnt lgkmcnt(0)
	v_mfma_f32_16x16x32_bf16 v[120:123], v[176:179], v[192:195], v[120:123]
	v_mfma_f32_16x16x32_bf16 v[112:115], v[184:187], v[192:195], v[112:115]
	v_mfma_f32_16x16x32_bf16 v[104:107], v[176:179], v[200:203], v[104:107]
	v_mfma_f32_16x16x32_bf16 v[96:99], v[184:187], v[200:203], v[96:99]
	v_mfma_f32_16x16x32_bf16 v[88:91], v[176:179], v[208:211], v[88:91]
	v_mfma_f32_16x16x32_bf16 v[80:83], v[184:187], v[208:211], v[80:83]
	v_mfma_f32_16x16x32_bf16 v[72:75], v[176:179], v[216:219], v[72:75]
	v_mfma_f32_16x16x32_bf16 v[64:67], v[184:187], v[216:219], v[64:67]
	s_add_i32 s35, s51, s36
	v_mfma_f32_16x16x32_bf16 v[120:123], v[180:183], v[196:199], v[120:123]
	s_add_u32 s98, s8, s22
	v_mfma_f32_16x16x32_bf16 v[112:115], v[188:191], v[196:199], v[112:115]
	s_addc_u32 s99, s9, s23
	v_mfma_f32_16x16x32_bf16 v[104:107], v[180:183], v[204:207], v[104:107]
	s_mov_b32 m0, s35
	v_mfma_f32_16x16x32_bf16 v[96:99], v[188:191], v[204:207], v[96:99]
	v_mfma_f32_16x16x32_bf16 v[88:91], v[180:183], v[212:215], v[88:91]
	v_mfma_f32_16x16x32_bf16 v[80:83], v[188:191], v[212:215], v[80:83]
	v_mfma_f32_16x16x32_bf16 v[72:75], v[180:183], v[220:223], v[72:75]
	v_mfma_f32_16x16x32_bf16 v[64:67], v[188:191], v[220:223], v[64:67]
	s_barrier
	s_setprio 0
	ds_read_b128 v[224:227], v173
	ds_read_b128 v[228:231], v173 offset:1024
	ds_read_b128 v[232:235], v173 offset:2048
	ds_read_b128 v[236:239], v173 offset:3072
	global_load_lds_dwordx4 v130, s[8:9]
	s_add_i32 m0, s35, 0x2000
	s_nop 0
	global_load_lds_dwordx4 v134, s[8:9]
	s_setprio 1
	s_barrier
	s_waitcnt lgkmcnt(0)
	v_mfma_f32_16x16x32_bf16 v[124:127], v[224:227], v[192:195], v[124:127]
	v_mfma_f32_16x16x32_bf16 v[116:119], v[232:235], v[192:195], v[116:119]
	v_mfma_f32_16x16x32_bf16 v[108:111], v[224:227], v[200:203], v[108:111]
	v_mfma_f32_16x16x32_bf16 v[100:103], v[232:235], v[200:203], v[100:103]
	v_mfma_f32_16x16x32_bf16 v[92:95], v[224:227], v[208:211], v[92:95]
	v_mfma_f32_16x16x32_bf16 v[84:87], v[232:235], v[208:211], v[84:87]
	v_mfma_f32_16x16x32_bf16 v[76:79], v[224:227], v[216:219], v[76:79]
	v_mfma_f32_16x16x32_bf16 v[68:71], v[232:235], v[216:219], v[68:71]
	s_mov_b32 m0, s37
	v_mfma_f32_16x16x32_bf16 v[124:127], v[228:231], v[196:199], v[124:127]
	s_add_u32 s100, s10, s22
	v_mfma_f32_16x16x32_bf16 v[116:119], v[236:239], v[196:199], v[116:119]
	s_addc_u32 s101, s11, s23
	v_mfma_f32_16x16x32_bf16 v[108:111], v[228:231], v[204:207], v[108:111]
	v_mfma_f32_16x16x32_bf16 v[100:103], v[236:239], v[204:207], v[100:103]
	v_mfma_f32_16x16x32_bf16 v[92:95], v[228:231], v[212:215], v[92:95]
	v_mfma_f32_16x16x32_bf16 v[84:87], v[236:239], v[212:215], v[84:87]
	v_mfma_f32_16x16x32_bf16 v[76:79], v[228:231], v[220:223], v[76:79]
	v_mfma_f32_16x16x32_bf16 v[68:71], v[236:239], v[220:223], v[68:71]
	s_barrier
	s_setprio 0
	ds_read_b128 v[192:195], v159 offset:16384
	ds_read_b128 v[196:199], v159 offset:17408
	ds_read_b128 v[200:203], v159 offset:18432
	ds_read_b128 v[204:207], v159 offset:19456
	ds_read_b128 v[208:211], v159 offset:20480
	ds_read_b128 v[212:215], v159 offset:21504
	ds_read_b128 v[216:219], v159 offset:22528
	ds_read_b128 v[220:223], v159 offset:23552
	global_load_lds_dwordx4 v128, s[10:11]
	s_mov_b32 m0, s38
	s_nop 0
	global_load_lds_dwordx4 v132, s[10:11]
	s_setprio 1
	s_barrier
	s_waitcnt lgkmcnt(0)
	v_mfma_f32_16x16x32_bf16 v[56:59], v[176:179], v[192:195], v[56:59]
	v_mfma_f32_16x16x32_bf16 v[48:51], v[184:187], v[192:195], v[48:51]
	v_mfma_f32_16x16x32_bf16 v[40:43], v[176:179], v[200:203], v[40:43]
	v_mfma_f32_16x16x32_bf16 v[32:35], v[184:187], v[200:203], v[32:35]
	v_mfma_f32_16x16x32_bf16 v[24:27], v[176:179], v[208:211], v[24:27]
	v_mfma_f32_16x16x32_bf16 v[16:19], v[184:187], v[208:211], v[16:19]
	v_mfma_f32_16x16x32_bf16 v[8:11], v[176:179], v[216:219], v[8:11]
	v_mfma_f32_16x16x32_bf16 v[4:7], v[184:187], v[216:219], v[4:7]
	s_add_u32 s54, s8, 0x80000
	v_mfma_f32_16x16x32_bf16 v[56:59], v[180:183], v[196:199], v[56:59]
	s_addc_u32 s55, s9, 0
	v_mfma_f32_16x16x32_bf16 v[48:51], v[188:191], v[196:199], v[48:51]
	s_add_i32 s35, s52, s36
	v_mfma_f32_16x16x32_bf16 v[40:43], v[180:183], v[204:207], v[40:43]
	s_mov_b32 m0, s35
	v_mfma_f32_16x16x32_bf16 v[32:35], v[188:191], v[204:207], v[32:35]
	v_mfma_f32_16x16x32_bf16 v[24:27], v[180:183], v[212:215], v[24:27]
	v_mfma_f32_16x16x32_bf16 v[16:19], v[188:191], v[212:215], v[16:19]
	v_mfma_f32_16x16x32_bf16 v[8:11], v[180:183], v[220:223], v[8:11]
	v_mfma_f32_16x16x32_bf16 v[4:7], v[188:191], v[220:223], v[4:7]
	s_barrier
	s_setprio 0
	s_nop 0
	global_load_lds_dwordx4 v130, s[54:55]
	s_add_i32 m0, s35, 0x2000
	s_nop 0
	global_load_lds_dwordx4 v134, s[54:55]
	s_waitcnt vmcnt(6)
	s_setprio 1
	s_barrier
; #define PG8_STAGE(bufoff, gbase, voff) do { _Pragma("unroll") for (int _i = 0; _i < 2; ++_i) \
;         __builtin_amdgcn_global_load_lds((const unsigned*)((const char*)(gbase) + (voff)[_i]), (LAS unsigned*)(lds + (bufoff) + ldsw + _i * 8192), 16, 0, 0); } while (0)
; #define PG8_LDA(dst, b, h) do { _Pragma("unroll") for (int m = 0; m < 4; ++m) _Pragma("unroll") for (int k = 0; k < 2; ++k) dst[m][k] = *(const LAS bf16x8*)(lds + PG8_SA(b, h) + aoff + m * 2048 + k * 1024); } while (0)
; #define PG8_LDB(dst, b, h) do { _Pragma("unroll") for (int n = 0; n < 2; ++n) _Pragma("unroll") for (int k = 0; k < 2; ++k) dst[n][k] = *(const LAS bf16x8*)(lds + PG8_SB(b, h) + boff + n * 2048 + k * 1024); } while (0)
; #define PG8_MMA(ai, bj, At, Bt) do { __builtin_amdgcn_s_setprio(1); _Pragma("unroll") for (int m = 0; m < 4; ++m) _Pragma("unroll") for (int n = 0; n < 2; ++n) _Pragma("unroll") for (int k = 0; k < 2; ++k) \
;         acc[ai][bj][m][n] = __builtin_amdgcn_mfma_f32_16x16x32_bf16(Bt[n][k], At[m][k], acc[ai][bj][m][n], 0, 0, 0); __builtin_amdgcn_s_setprio(0); } while (0)
; #define PG8_WAIT_V(n) asm volatile("s_waitcnt vmcnt(" #n ")" ::: "memory")
; #define PG8_WAIT_L(n) asm volatile("s_waitcnt lgkmcnt(" #n ")" ::: "memory")
; #define PG8_BAR __builtin_amdgcn_s_barrier()
; #define PG8_SCHED __builtin_amdgcn_sched_barrier(0)
; template <class Epi, class Sched, bool ATILE = false>
; __device__ __forceinline__ void gemm_phase(LAS unsigned char* lds, const Gemm g, const Sched& S, const Epi& E) {
;     ...
;             PG8_WAIT_V(6); PG8_BAR; PG8_MMA(1, 1, At, B1); PG8_BAR;
;             PG8_LDB(B0, 1, 0); PG8_SCHED; PG8_LDA(At, 1, 0); PG8_STAGE(PG8_SA(0, 1), a2 + hstepA, voffA);
;             PG8_WAIT_L(8); PG8_BAR; PG8_WAIT_L(0); PG8_MMA(0, 0, At, B0); PG8_BAR; PG8_SCHED;
;             PG8_LDB(B1, 1, 1); PG8_STAGE(PG8_SB(1, 0), b3, voffB);
;             PG8_BAR; PG8_WAIT_L(0); PG8_MMA(0, 1, At, B1); PG8_BAR;
;             PG8_LDA(At, 1, 1); PG8_STAGE(PG8_SA(1, 0), a3, voffA);
;             PG8_BAR; PG8_WAIT_L(0); PG8_MMA(1, 0, At, B0); PG8_BAR; PG8_SCHED;
	v_mfma_f32_16x16x32_bf16 v[60:63], v[224:227], v[192:195], v[60:63]
	v_mfma_f32_16x16x32_bf16 v[52:55], v[232:235], v[192:195], v[52:55]
	v_mfma_f32_16x16x32_bf16 v[44:47], v[224:227], v[200:203], v[44:47]
	v_mfma_f32_16x16x32_bf16 v[36:39], v[232:235], v[200:203], v[36:39]
	v_mfma_f32_16x16x32_bf16 v[28:31], v[224:227], v[208:211], v[28:31]
	v_mfma_f32_16x16x32_bf16 v[20:23], v[232:235], v[208:211], v[20:23]
	v_mfma_f32_16x16x32_bf16 v[12:15], v[224:227], v[216:219], v[12:15]
	v_mfma_f32_16x16x32_bf16 v[0:3], v[232:235], v[216:219], v[0:3]
	s_add_i32 s35, 0, 0x18000
	v_mfma_f32_16x16x32_bf16 v[60:63], v[228:231], v[196:199], v[60:63]
	v_add_u32_e32 v172, s35, v157
	v_mfma_f32_16x16x32_bf16 v[52:55], v[236:239], v[196:199], v[52:55]
	v_mfma_f32_16x16x32_bf16 v[44:47], v[228:231], v[204:207], v[44:47]
	v_mfma_f32_16x16x32_bf16 v[36:39], v[236:239], v[204:207], v[36:39]
	v_mfma_f32_16x16x32_bf16 v[28:31], v[228:231], v[212:215], v[28:31]
	v_mfma_f32_16x16x32_bf16 v[20:23], v[236:239], v[212:215], v[20:23]
	v_mfma_f32_16x16x32_bf16 v[12:15], v[228:231], v[220:223], v[12:15]
	v_mfma_f32_16x16x32_bf16 v[0:3], v[236:239], v[220:223], v[0:3]
	s_barrier
	s_setprio 0
	ds_read_b128 v[176:179], v172
	ds_read_b128 v[180:183], v172 offset:1024
	ds_read_b128 v[184:187], v172 offset:2048
	ds_read_b128 v[188:191], v172 offset:3072
	s_add_u32 s10, s10, 0x80000
	s_addc_u32 s11, s11, 0
	s_mov_b32 m0, s39
	ds_read_b128 v[192:195], v159 offset:32768
	ds_read_b128 v[196:199], v159 offset:33792
	ds_read_b128 v[200:203], v159 offset:34816
	ds_read_b128 v[204:207], v159 offset:35840
	ds_read_b128 v[208:211], v159 offset:36864
	ds_read_b128 v[212:215], v159 offset:37888
	ds_read_b128 v[216:219], v159 offset:38912
	ds_read_b128 v[220:223], v159 offset:39936
	global_load_lds_dwordx4 v128, s[10:11]
	s_mov_b32 m0, s40
	s_nop 0
	global_load_lds_dwordx4 v132, s[10:11]
	s_waitcnt lgkmcnt(8)
	s_setprio 1
	s_barrier
	s_waitcnt lgkmcnt(0)
	v_mfma_f32_16x16x32_bf16 v[120:123], v[176:179], v[192:195], v[120:123]
	v_mfma_f32_16x16x32_bf16 v[112:115], v[184:187], v[192:195], v[112:115]
	v_mfma_f32_16x16x32_bf16 v[104:107], v[176:179], v[200:203], v[104:107]
	v_mfma_f32_16x16x32_bf16 v[96:99], v[184:187], v[200:203], v[96:99]
	v_mfma_f32_16x16x32_bf16 v[88:91], v[176:179], v[208:211], v[88:91]
	v_mfma_f32_16x16x32_bf16 v[80:83], v[184:187], v[208:211], v[80:83]
	v_mfma_f32_16x16x32_bf16 v[72:75], v[176:179], v[216:219], v[72:75]
	v_mfma_f32_16x16x32_bf16 v[64:67], v[184:187], v[216:219], v[64:67]
	s_add_i32 s10, 0, 0x1c000
	v_mfma_f32_16x16x32_bf16 v[120:123], v[180:183], v[196:199], v[120:123]
	s_add_i32 s11, s35, s36
	v_mfma_f32_16x16x32_bf16 v[112:115], v[188:191], v[196:199], v[112:115]
	v_add_u32_e32 v172, s10, v157
	v_mfma_f32_16x16x32_bf16 v[104:107], v[180:183], v[204:207], v[104:107]
	s_mov_b32 m0, s11
	v_mfma_f32_16x16x32_bf16 v[96:99], v[188:191], v[204:207], v[96:99]
	v_mfma_f32_16x16x32_bf16 v[88:91], v[180:183], v[212:215], v[88:91]
	v_mfma_f32_16x16x32_bf16 v[80:83], v[188:191], v[212:215], v[80:83]
	v_mfma_f32_16x16x32_bf16 v[72:75], v[180:183], v[220:223], v[72:75]
	v_mfma_f32_16x16x32_bf16 v[64:67], v[188:191], v[220:223], v[64:67]
	s_barrier
	s_setprio 0
	ds_read_b128 v[224:227], v172
	ds_read_b128 v[228:231], v172 offset:1024
	ds_read_b128 v[232:235], v172 offset:2048
	ds_read_b128 v[236:239], v172 offset:3072
	global_load_lds_dwordx4 v130, s[98:99]
	s_add_i32 m0, s11, 0x2000
	s_nop 0
	global_load_lds_dwordx4 v134, s[98:99]
	s_setprio 1
	s_barrier
; #define PG8_STAGE(bufoff, gbase, voff) do { _Pragma("unroll") for (int _i = 0; _i < 2; ++_i) \
;         __builtin_amdgcn_global_load_lds((const unsigned*)((const char*)(gbase) + (voff)[_i]), (LAS unsigned*)(lds + (bufoff) + ldsw + _i * 8192), 16, 0, 0); } while (0)
; #define PG8_LDA(dst, b, h) do { _Pragma("unroll") for (int m = 0; m < 4; ++m) _Pragma("unroll") for (int k = 0; k < 2; ++k) dst[m][k] = *(const LAS bf16x8*)(lds + PG8_SA(b, h) + aoff + m * 2048 + k * 1024); } while (0)
; #define PG8_MMA(ai, bj, At, Bt) do { __builtin_amdgcn_s_setprio(1); _Pragma("unroll") for (int m = 0; m < 4; ++m) _Pragma("unroll") for (int n = 0; n < 2; ++n) _Pragma("unroll") for (int k = 0; k < 2; ++k) \
;         acc[ai][bj][m][n] = __builtin_amdgcn_mfma_f32_16x16x32_bf16(Bt[n][k], At[m][k], acc[ai][bj][m][n], 0, 0, 0); __builtin_amdgcn_s_setprio(0); } while (0)
; #define PG8_WAIT_V(n) asm volatile("s_waitcnt vmcnt(" #n ")" ::: "memory")
; #define PG8_WAIT_L(n) asm volatile("s_waitcnt lgkmcnt(" #n ")" ::: "memory")
; #define PG8_BAR __builtin_amdgcn_s_barrier()
; #define PG8_SCHED __builtin_amdgcn_sched_barrier(0)
; template <class Epi, class Sched, bool ATILE = false>
; __device__ __forceinline__ void gemm_phase(LAS unsigned char* lds, const Gemm g, const Sched& S, const Epi& E) {
;     ...
;             PG8_BAR; PG8_WAIT_L(0); PG8_MMA(0, 1, At, B1); PG8_BAR;
;             PG8_LDA(At, 1, 1); PG8_STAGE(PG8_SA(1, 0), a3, voffA);
;             PG8_BAR; PG8_WAIT_L(0); PG8_MMA(1, 0, At, B0); PG8_BAR; PG8_SCHED;
;             PG8_STAGE(PG8_SB(1, 1), b3 + hstepB, voffB);
;             PG8_WAIT_V(6); PG8_BAR; PG8_MMA(1, 1, At, B1); PG8_BAR;
	s_waitcnt lgkmcnt(0)
	v_mfma_f32_16x16x32_bf16 v[124:127], v[224:227], v[192:195], v[124:127]
	v_mfma_f32_16x16x32_bf16 v[116:119], v[232:235], v[192:195], v[116:119]
	v_mfma_f32_16x16x32_bf16 v[108:111], v[224:227], v[200:203], v[108:111]
	v_mfma_f32_16x16x32_bf16 v[100:103], v[232:235], v[200:203], v[100:103]
	v_mfma_f32_16x16x32_bf16 v[92:95], v[224:227], v[208:211], v[92:95]
	v_mfma_f32_16x16x32_bf16 v[84:87], v[232:235], v[208:211], v[84:87]
	v_mfma_f32_16x16x32_bf16 v[76:79], v[224:227], v[216:219], v[76:79]
	v_mfma_f32_16x16x32_bf16 v[68:71], v[232:235], v[216:219], v[68:71]
	s_mov_b32 m0, s43
	v_mfma_f32_16x16x32_bf16 v[124:127], v[228:231], v[196:199], v[124:127]
	v_mfma_f32_16x16x32_bf16 v[116:119], v[236:239], v[196:199], v[116:119]
	v_mfma_f32_16x16x32_bf16 v[108:111], v[228:231], v[204:207], v[108:111]
	v_mfma_f32_16x16x32_bf16 v[100:103], v[236:239], v[204:207], v[100:103]
	v_mfma_f32_16x16x32_bf16 v[92:95], v[228:231], v[212:215], v[92:95]
	v_mfma_f32_16x16x32_bf16 v[84:87], v[236:239], v[212:215], v[84:87]
	v_mfma_f32_16x16x32_bf16 v[76:79], v[228:231], v[220:223], v[76:79]
	v_mfma_f32_16x16x32_bf16 v[68:71], v[236:239], v[220:223], v[68:71]
	s_barrier
	s_setprio 0
	ds_read_b128 v[192:195], v159 offset:49152
	ds_read_b128 v[196:199], v159 offset:50176
	ds_read_b128 v[200:203], v159 offset:51200
	ds_read_b128 v[204:207], v159 offset:52224
	ds_read_b128 v[208:211], v159 offset:53248
	ds_read_b128 v[212:215], v159 offset:54272
	ds_read_b128 v[216:219], v159 offset:55296
	ds_read_b128 v[220:223], v159 offset:56320
	global_load_lds_dwordx4 v128, s[100:101]
	s_mov_b32 m0, s44
	s_nop 0
	global_load_lds_dwordx4 v132, s[100:101]
	s_setprio 1
	s_barrier
	s_waitcnt lgkmcnt(0)
	v_mfma_f32_16x16x32_bf16 v[56:59], v[176:179], v[192:195], v[56:59]
	v_mfma_f32_16x16x32_bf16 v[48:51], v[184:187], v[192:195], v[48:51]
	v_mfma_f32_16x16x32_bf16 v[40:43], v[176:179], v[200:203], v[40:43]
	v_mfma_f32_16x16x32_bf16 v[32:35], v[184:187], v[200:203], v[32:35]
	v_mfma_f32_16x16x32_bf16 v[24:27], v[176:179], v[208:211], v[24:27]
	v_mfma_f32_16x16x32_bf16 v[16:19], v[184:187], v[208:211], v[16:19]
	v_mfma_f32_16x16x32_bf16 v[8:11], v[176:179], v[216:219], v[8:11]
	v_mfma_f32_16x16x32_bf16 v[4:7], v[184:187], v[216:219], v[4:7]
	s_add_u32 s8, s8, 0x80080
	v_mfma_f32_16x16x32_bf16 v[56:59], v[180:183], v[196:199], v[56:59]
	s_addc_u32 s9, s9, 0
	v_mfma_f32_16x16x32_bf16 v[48:51], v[188:191], v[196:199], v[48:51]
	s_add_i32 s10, s10, s36
	v_mfma_f32_16x16x32_bf16 v[40:43], v[180:183], v[204:207], v[40:43]
	s_mov_b32 m0, s10
	v_mfma_f32_16x16x32_bf16 v[32:35], v[188:191], v[204:207], v[32:35]
	v_mfma_f32_16x16x32_bf16 v[24:27], v[180:183], v[212:215], v[24:27]
	v_mfma_f32_16x16x32_bf16 v[16:19], v[188:191], v[212:215], v[16:19]
	v_mfma_f32_16x16x32_bf16 v[8:11], v[180:183], v[220:223], v[8:11]
	v_mfma_f32_16x16x32_bf16 v[4:7], v[188:191], v[220:223], v[4:7]
	s_barrier
	s_setprio 0
	s_nop 0
	global_load_lds_dwordx4 v130, s[8:9]
	s_add_i32 m0, s10, 0x2000
	s_nop 0
	global_load_lds_dwordx4 v134, s[8:9]
	s_waitcnt vmcnt(6)
	s_setprio 1
	s_barrier
	v_mfma_f32_16x16x32_bf16 v[60:63], v[224:227], v[192:195], v[60:63]
	v_mfma_f32_16x16x32_bf16 v[52:55], v[232:235], v[192:195], v[52:55]
	v_mfma_f32_16x16x32_bf16 v[44:47], v[224:227], v[200:203], v[44:47]
	v_mfma_f32_16x16x32_bf16 v[36:39], v[232:235], v[200:203], v[36:39]
	v_mfma_f32_16x16x32_bf16 v[28:31], v[224:227], v[208:211], v[28:31]
	v_mfma_f32_16x16x32_bf16 v[20:23], v[232:235], v[208:211], v[20:23]
	v_mfma_f32_16x16x32_bf16 v[12:15], v[224:227], v[216:219], v[12:15]
	s_add_u32 s6, s6, 0x100
	v_mfma_f32_16x16x32_bf16 v[0:3], v[232:235], v[216:219], v[0:3]
	s_addc_u32 s7, s7, 0
	v_mfma_f32_16x16x32_bf16 v[60:63], v[228:231], v[196:199], v[60:63]
	s_add_u32 s25, s25, 0x100
	v_mfma_f32_16x16x32_bf16 v[52:55], v[236:239], v[196:199], v[52:55]
	s_addc_u32 s27, s27, 0
	v_mfma_f32_16x16x32_bf16 v[44:47], v[228:231], v[204:207], v[44:47]
	s_cmp_ge_i32 s34, s12
	v_mfma_f32_16x16x32_bf16 v[36:39], v[236:239], v[204:207], v[36:39]
	s_mov_b32 s8, s34
	v_mfma_f32_16x16x32_bf16 v[28:31], v[228:231], v[212:215], v[28:31]
	v_mfma_f32_16x16x32_bf16 v[20:23], v[236:239], v[212:215], v[20:23]
	v_mfma_f32_16x16x32_bf16 v[12:15], v[228:231], v[220:223], v[12:15]
	v_mfma_f32_16x16x32_bf16 v[0:3], v[236:239], v[220:223], v[0:3]
	s_barrier
	s_setprio 0
	s_cbranch_scc0 .LBB0_1812
	s_nop 5
	s_branch .LBB0_1803

; #define PG8_STAGE(bufoff, gbase, voff) do { _Pragma("unroll") for (int _i = 0; _i < 2; ++_i) \
;         __builtin_amdgcn_global_load_lds((const unsigned*)((const char*)(gbase) + (voff)[_i]), (LAS unsigned*)(lds + (bufoff) + ldsw + _i * 8192), 16, 0, 0); } while (0)
; #define PG8_LDA(dst, b, h) do { _Pragma("unroll") for (int m = 0; m < 4; ++m) _Pragma("unroll") for (int k = 0; k < 2; ++k) dst[m][k] = *(const LAS bf16x8*)(lds + PG8_SA(b, h) + aoff + m * 2048 + k * 1024); } while (0)
; #define PG8_LDB(dst, b, h) do { _Pragma("unroll") for (int n = 0; n < 2; ++n) _Pragma("unroll") for (int k = 0; k < 2; ++k) dst[n][k] = *(const LAS bf16x8*)(lds + PG8_SB(b, h) + boff + n * 2048 + k * 1024); } while (0)
; #define PG8_MMA(ai, bj, At, Bt) do { __builtin_amdgcn_s_setprio(1); _Pragma("unroll") for (int m = 0; m < 4; ++m) _Pragma("unroll") for (int n = 0; n < 2; ++n) _Pragma("unroll") for (int k = 0; k < 2; ++k) \
;         acc[ai][bj][m][n] = __builtin_amdgcn_mfma_f32_16x16x32_bf16(Bt[n][k], At[m][k], acc[ai][bj][m][n], 0, 0, 0); __builtin_amdgcn_s_setprio(0); } while (0)
; #define PG8_WAIT_V(n) asm volatile("s_waitcnt vmcnt(" #n ")" ::: "memory")
; #define PG8_WAIT_L(n) asm volatile("s_waitcnt lgkmcnt(" #n ")" ::: "memory")
; template <class Epi, class Sched, bool ATILE = false>
; __device__ __forceinline__ void gemm_phase(LAS unsigned char* lds, const Gemm g, const Sched& S, const Epi& E) {
;     ...
;         for (int t = 0; t < nt; t += 2) {
;             const bool last = (t == nt - 2);
;             const char* a1 = cA + (size_t)(t + 1) * kstepA;
;             const char* a2 = last ? nA : cA + (size_t)(t + 2) * kstepA; const char* b2 = last ? nB : cB + (size_t)(t + 2) * kstep;
;             const char* a3 = a2 + kstepA; const char* b3 = b2 + kstep;
;             PG8_LDB(B0, 0, 0); PG8_SCHED; PG8_LDA(At, 0, 0); PG8_STAGE(PG8_SA(1, 1), a1 + hstepA, voffA);
;             PG8_WAIT_L(8); PG8_BAR; PG8_WAIT_L(0); PG8_MMA(0, 0, At, B0); PG8_BAR; PG8_SCHED;
;             PG8_LDB(B1, 0, 1); PG8_STAGE(PG8_SB(0, 0), b2, voffB);
;             PG8_BAR; PG8_WAIT_L(0); PG8_MMA(0, 1, At, B1); PG8_BAR;
;             PG8_LDA(At, 0, 1); PG8_STAGE(PG8_SA(0, 0), a2, voffA);
;             PG8_BAR; PG8_WAIT_L(0); PG8_MMA(1, 0, At, B0); PG8_BAR; PG8_SCHED;
;             PG8_STAGE(PG8_SB(0, 1), b2 + hstepB, voffB);
;             PG8_WAIT_V(6); PG8_BAR; PG8_MMA(1, 1, At, B1); PG8_BAR;
.LBB0_1898:
	ds_read_b128 v[20:23], v180
	ds_read_b128 v[28:31], v180 offset:1024
	ds_read_b128 v[174:177], v180 offset:2048
	ds_read_b128 v[184:187], v180 offset:3072
	s_add_i32 s58, s26, 2
	s_add_u32 s27, s24, 0x4000
	s_addc_u32 s28, s25, 0
	s_cmp_eq_u32 s17, s26
	s_cselect_b32 s30, s20, s27
	s_cselect_b32 s31, s21, s28
	s_cselect_b32 s26, s22, s56
	s_cselect_b32 s27, s23, s57
	s_add_u32 s28, s30, 0x8000
	s_addc_u32 s29, s31, 0
	s_add_i32 m0, s34, 0xc000
	ds_read_b128 v[188:191], v181
	ds_read_b128 v[192:195], v181 offset:1024
	ds_read_b128 v[196:199], v181 offset:2048
	ds_read_b128 v[200:203], v181 offset:3072
	ds_read_b128 v[204:207], v181 offset:4096
	ds_read_b128 v[208:211], v181 offset:5120
	ds_read_b128 v[212:215], v181 offset:6144
	ds_read_b128 v[216:219], v181 offset:7168
	global_load_lds_dwordx4 v168, s[24:25]
	s_add_i32 m0, s34, 0xe000
	s_nop 0
	global_load_lds_dwordx4 v170, s[24:25]
	s_waitcnt lgkmcnt(8)
	s_setprio 1
	s_barrier
	s_waitcnt lgkmcnt(0)
	v_mfma_f32_16x16x32_bf16 v[0:3], v[20:23], v[188:191], v[0:3]
	v_mfma_f32_16x16x32_bf16 v[4:7], v[174:177], v[188:191], v[4:7]
	v_mfma_f32_16x16x32_bf16 v[44:47], v[20:23], v[196:199], v[44:47]
	v_mfma_f32_16x16x32_bf16 v[36:39], v[174:177], v[196:199], v[36:39]
	v_mfma_f32_16x16x32_bf16 v[52:55], v[20:23], v[204:207], v[52:55]
	v_mfma_f32_16x16x32_bf16 v[48:51], v[174:177], v[204:207], v[48:51]
	v_mfma_f32_16x16x32_bf16 v[92:95], v[20:23], v[212:215], v[92:95]
	v_mfma_f32_16x16x32_bf16 v[84:87], v[174:177], v[212:215], v[84:87]
	s_add_i32 s59, s44, s33
	v_mfma_f32_16x16x32_bf16 v[0:3], v[28:31], v[192:195], v[0:3]
	s_add_u32 s98, s26, s4
	v_mfma_f32_16x16x32_bf16 v[4:7], v[184:187], v[192:195], v[4:7]
	s_addc_u32 s99, s27, s5
	v_mfma_f32_16x16x32_bf16 v[44:47], v[28:31], v[200:203], v[44:47]
	s_mov_b32 m0, s59
	v_mfma_f32_16x16x32_bf16 v[36:39], v[184:187], v[200:203], v[36:39]
	v_mfma_f32_16x16x32_bf16 v[52:55], v[28:31], v[208:211], v[52:55]
	v_mfma_f32_16x16x32_bf16 v[48:51], v[184:187], v[208:211], v[48:51]
	v_mfma_f32_16x16x32_bf16 v[92:95], v[28:31], v[216:219], v[92:95]
	v_mfma_f32_16x16x32_bf16 v[84:87], v[184:187], v[216:219], v[84:87]
	s_barrier
	s_setprio 0
	ds_read_b128 v[220:223], v182
	ds_read_b128 v[224:227], v182 offset:1024
	ds_read_b128 v[228:231], v182 offset:2048
	ds_read_b128 v[232:235], v182 offset:3072
	global_load_lds_dwordx4 v138, s[26:27]
	s_add_i32 m0, s59, 0x2000
	s_nop 0
	global_load_lds_dwordx4 v142, s[26:27]
	s_setprio 1
	s_barrier
	s_waitcnt lgkmcnt(0)
	v_mfma_f32_16x16x32_bf16 v[12:15], v[220:223], v[188:191], v[12:15]
	v_mfma_f32_16x16x32_bf16 v[8:11], v[228:231], v[188:191], v[8:11]
	v_mfma_f32_16x16x32_bf16 v[24:27], v[220:223], v[196:199], v[24:27]
	v_mfma_f32_16x16x32_bf16 v[16:19], v[228:231], v[196:199], v[16:19]
	v_mfma_f32_16x16x32_bf16 v[40:43], v[220:223], v[204:207], v[40:43]
	v_mfma_f32_16x16x32_bf16 v[32:35], v[228:231], v[204:207], v[32:35]
	v_mfma_f32_16x16x32_bf16 v[56:59], v[220:223], v[212:215], v[56:59]
	v_mfma_f32_16x16x32_bf16 v[60:63], v[228:231], v[212:215], v[60:63]
	s_mov_b32 m0, s34
	v_mfma_f32_16x16x32_bf16 v[12:15], v[224:227], v[192:195], v[12:15]
	v_mfma_f32_16x16x32_bf16 v[8:11], v[232:235], v[192:195], v[8:11]
	v_mfma_f32_16x16x32_bf16 v[24:27], v[224:227], v[200:203], v[24:27]
	v_mfma_f32_16x16x32_bf16 v[16:19], v[232:235], v[200:203], v[16:19]
	v_mfma_f32_16x16x32_bf16 v[40:43], v[224:227], v[208:211], v[40:43]
	v_mfma_f32_16x16x32_bf16 v[32:35], v[232:235], v[208:211], v[32:35]
	v_mfma_f32_16x16x32_bf16 v[56:59], v[224:227], v[216:219], v[56:59]
	v_mfma_f32_16x16x32_bf16 v[60:63], v[232:235], v[216:219], v[60:63]
	s_barrier
	s_setprio 0
	ds_read_b128 v[188:191], v181 offset:16384
	ds_read_b128 v[192:195], v181 offset:17408
	ds_read_b128 v[196:199], v181 offset:18432
	ds_read_b128 v[200:203], v181 offset:19456
	ds_read_b128 v[204:207], v181 offset:20480
	ds_read_b128 v[208:211], v181 offset:21504
	ds_read_b128 v[212:215], v181 offset:22528
	ds_read_b128 v[216:219], v181 offset:23552
	global_load_lds_dwordx4 v136, s[30:31]
	s_mov_b32 m0, s35
	s_nop 0
	global_load_lds_dwordx4 v140, s[30:31]
	s_setprio 1
	s_barrier
	s_waitcnt lgkmcnt(0)
	v_mfma_f32_16x16x32_bf16 v[64:67], v[20:23], v[188:191], v[64:67]
	v_mfma_f32_16x16x32_bf16 v[68:71], v[174:177], v[188:191], v[68:71]
	v_mfma_f32_16x16x32_bf16 v[108:111], v[20:23], v[196:199], v[108:111]
	v_mfma_f32_16x16x32_bf16 v[100:103], v[174:177], v[196:199], v[100:103]
	v_mfma_f32_16x16x32_bf16 v[116:119], v[20:23], v[204:207], v[116:119]
	v_mfma_f32_16x16x32_bf16 v[112:115], v[174:177], v[204:207], v[112:115]
	v_mfma_f32_16x16x32_bf16 v[20:23], v[20:23], v[212:215], v[132:135]
	v_mfma_f32_16x16x32_bf16 v[64:67], v[28:31], v[192:195], v[64:67]
	s_add_u32 s60, s26, 0x158000
	v_mfma_f32_16x16x32_bf16 v[68:71], v[184:187], v[192:195], v[68:71]
	s_addc_u32 s61, s27, 0
	v_mfma_f32_16x16x32_bf16 v[108:111], v[28:31], v[200:203], v[108:111]
	s_add_i32 s59, s45, s33
	v_mfma_f32_16x16x32_bf16 v[100:103], v[184:187], v[200:203], v[100:103]
	s_mov_b32 m0, s59
	v_mfma_f32_16x16x32_bf16 v[116:119], v[28:31], v[208:211], v[116:119]
	v_mfma_f32_16x16x32_bf16 v[112:115], v[184:187], v[208:211], v[112:115]
	v_mfma_f32_16x16x32_bf16 v[20:23], v[28:31], v[216:219], v[20:23]
	v_mfma_f32_16x16x32_bf16 v[28:31], v[174:177], v[212:215], v[128:131]
	v_mfma_f32_16x16x32_bf16 v[28:31], v[184:187], v[216:219], v[28:31]
	s_barrier
	s_setprio 0
	s_nop 0
	global_load_lds_dwordx4 v138, s[60:61]
	s_add_i32 m0, s59, 0x2000
	s_nop 0
	global_load_lds_dwordx4 v142, s[60:61]
	s_waitcnt vmcnt(6)
	s_setprio 1
	s_barrier
; #define PG8_STAGE(bufoff, gbase, voff) do { _Pragma("unroll") for (int _i = 0; _i < 2; ++_i) \
;         __builtin_amdgcn_global_load_lds((const unsigned*)((const char*)(gbase) + (voff)[_i]), (LAS unsigned*)(lds + (bufoff) + ldsw + _i * 8192), 16, 0, 0); } while (0)
; #define PG8_LDA(dst, b, h) do { _Pragma("unroll") for (int m = 0; m < 4; ++m) _Pragma("unroll") for (int k = 0; k < 2; ++k) dst[m][k] = *(const LAS bf16x8*)(lds + PG8_SA(b, h) + aoff + m * 2048 + k * 1024); } while (0)
; #define PG8_LDB(dst, b, h) do { _Pragma("unroll") for (int n = 0; n < 2; ++n) _Pragma("unroll") for (int k = 0; k < 2; ++k) dst[n][k] = *(const LAS bf16x8*)(lds + PG8_SB(b, h) + boff + n * 2048 + k * 1024); } while (0)
; #define PG8_MMA(ai, bj, At, Bt) do { __builtin_amdgcn_s_setprio(1); _Pragma("unroll") for (int m = 0; m < 4; ++m) _Pragma("unroll") for (int n = 0; n < 2; ++n) _Pragma("unroll") for (int k = 0; k < 2; ++k) \
;         acc[ai][bj][m][n] = __builtin_amdgcn_mfma_f32_16x16x32_bf16(Bt[n][k], At[m][k], acc[ai][bj][m][n], 0, 0, 0); __builtin_amdgcn_s_setprio(0); } while (0)
; #define PG8_WAIT_V(n) asm volatile("s_waitcnt vmcnt(" #n ")" ::: "memory")
; #define PG8_WAIT_L(n) asm volatile("s_waitcnt lgkmcnt(" #n ")" ::: "memory")
; #define PG8_BAR __builtin_amdgcn_s_barrier()
; #define PG8_SCHED __builtin_amdgcn_sched_barrier(0)
; template <class Epi, class Sched, bool ATILE = false>
; __device__ __forceinline__ void gemm_phase(LAS unsigned char* lds, const Gemm g, const Sched& S, const Epi& E) {
;     ...
;             PG8_WAIT_V(6); PG8_BAR; PG8_MMA(1, 1, At, B1); PG8_BAR;
;             PG8_LDB(B0, 1, 0); PG8_SCHED; PG8_LDA(At, 1, 0); PG8_STAGE(PG8_SA(0, 1), a2 + hstepA, voffA);
;             PG8_WAIT_L(8); PG8_BAR; PG8_WAIT_L(0); PG8_MMA(0, 0, At, B0); PG8_BAR; PG8_SCHED;
;             PG8_LDB(B1, 1, 1); PG8_STAGE(PG8_SB(1, 0), b3, voffB);
;             PG8_BAR; PG8_WAIT_L(0); PG8_MMA(0, 1, At, B1); PG8_BAR;
;             PG8_LDA(At, 1, 1); PG8_STAGE(PG8_SA(1, 0), a3, voffA);
;             PG8_BAR; PG8_WAIT_L(0); PG8_MMA(1, 0, At, B0); PG8_BAR; PG8_SCHED;
	v_mfma_f32_16x16x32_bf16 v[76:79], v[220:223], v[188:191], v[76:79]
	v_mfma_f32_16x16x32_bf16 v[72:75], v[228:231], v[188:191], v[72:75]
	v_mfma_f32_16x16x32_bf16 v[88:91], v[220:223], v[196:199], v[88:91]
	v_mfma_f32_16x16x32_bf16 v[80:83], v[228:231], v[196:199], v[80:83]
	v_mfma_f32_16x16x32_bf16 v[104:107], v[220:223], v[204:207], v[104:107]
	v_mfma_f32_16x16x32_bf16 v[96:99], v[228:231], v[204:207], v[96:99]
	v_mfma_f32_16x16x32_bf16 v[120:123], v[220:223], v[212:215], v[120:123]
	v_mfma_f32_16x16x32_bf16 v[124:127], v[228:231], v[212:215], v[124:127]
	s_add_i32 s59, 0, 0x18000
	v_mfma_f32_16x16x32_bf16 v[76:79], v[224:227], v[192:195], v[76:79]
	v_add_u32_e32 v183, s59, v157
	v_mfma_f32_16x16x32_bf16 v[72:75], v[232:235], v[192:195], v[72:75]
	v_mfma_f32_16x16x32_bf16 v[88:91], v[224:227], v[200:203], v[88:91]
	v_mfma_f32_16x16x32_bf16 v[80:83], v[232:235], v[200:203], v[80:83]
	v_mfma_f32_16x16x32_bf16 v[104:107], v[224:227], v[208:211], v[104:107]
	v_mfma_f32_16x16x32_bf16 v[96:99], v[232:235], v[208:211], v[96:99]
	v_mfma_f32_16x16x32_bf16 v[120:123], v[224:227], v[216:219], v[120:123]
	v_mfma_f32_16x16x32_bf16 v[124:127], v[232:235], v[216:219], v[124:127]
	s_barrier
	s_setprio 0
	ds_read_b128 v[128:131], v183
	ds_read_b128 v[132:135], v183 offset:1024
	ds_read_b128 v[174:177], v183 offset:2048
	ds_read_b128 v[184:187], v183 offset:3072
	s_add_u32 s30, s30, 0x4000
	s_addc_u32 s31, s31, 0
	s_mov_b32 m0, s36
	ds_read_b128 v[188:191], v181 offset:32768
	ds_read_b128 v[192:195], v181 offset:33792
	ds_read_b128 v[196:199], v181 offset:34816
	ds_read_b128 v[200:203], v181 offset:35840
	ds_read_b128 v[204:207], v181 offset:36864
	ds_read_b128 v[208:211], v181 offset:37888
	ds_read_b128 v[212:215], v181 offset:38912
	ds_read_b128 v[216:219], v181 offset:39936
	global_load_lds_dwordx4 v136, s[30:31]
	s_mov_b32 m0, s37
	s_nop 0
	global_load_lds_dwordx4 v140, s[30:31]
	s_waitcnt lgkmcnt(8)
	s_setprio 1
	s_barrier
	s_waitcnt lgkmcnt(0)
	v_mfma_f32_16x16x32_bf16 v[0:3], v[128:131], v[188:191], v[0:3]
	v_mfma_f32_16x16x32_bf16 v[4:7], v[174:177], v[188:191], v[4:7]
	v_mfma_f32_16x16x32_bf16 v[44:47], v[128:131], v[196:199], v[44:47]
	v_mfma_f32_16x16x32_bf16 v[36:39], v[174:177], v[196:199], v[36:39]
	v_mfma_f32_16x16x32_bf16 v[52:55], v[128:131], v[204:207], v[52:55]
	v_mfma_f32_16x16x32_bf16 v[48:51], v[174:177], v[204:207], v[48:51]
	v_mfma_f32_16x16x32_bf16 v[92:95], v[128:131], v[212:215], v[92:95]
	v_mfma_f32_16x16x32_bf16 v[84:87], v[174:177], v[212:215], v[84:87]
	s_add_i32 s30, 0, 0x1c000
	v_mfma_f32_16x16x32_bf16 v[0:3], v[132:135], v[192:195], v[0:3]
	s_add_i32 s31, s59, s33
	v_mfma_f32_16x16x32_bf16 v[4:7], v[184:187], v[192:195], v[4:7]
	v_add_u32_e32 v183, s30, v157
	v_mfma_f32_16x16x32_bf16 v[44:47], v[132:135], v[200:203], v[44:47]
	s_mov_b32 m0, s31
	v_mfma_f32_16x16x32_bf16 v[36:39], v[184:187], v[200:203], v[36:39]
	v_mfma_f32_16x16x32_bf16 v[52:55], v[132:135], v[208:211], v[52:55]
	v_mfma_f32_16x16x32_bf16 v[48:51], v[184:187], v[208:211], v[48:51]
	v_mfma_f32_16x16x32_bf16 v[92:95], v[132:135], v[216:219], v[92:95]
	v_mfma_f32_16x16x32_bf16 v[84:87], v[184:187], v[216:219], v[84:87]
	s_barrier
	s_setprio 0
	ds_read_b128 v[220:223], v183
	ds_read_b128 v[224:227], v183 offset:1024
	ds_read_b128 v[228:231], v183 offset:2048
	ds_read_b128 v[232:235], v183 offset:3072
	global_load_lds_dwordx4 v138, s[98:99]
	s_add_i32 m0, s31, 0x2000
	s_nop 0
	global_load_lds_dwordx4 v142, s[98:99]
	s_setprio 1
	s_barrier
	s_waitcnt lgkmcnt(0)
	v_mfma_f32_16x16x32_bf16 v[12:15], v[220:223], v[188:191], v[12:15]
	v_mfma_f32_16x16x32_bf16 v[8:11], v[228:231], v[188:191], v[8:11]
	v_mfma_f32_16x16x32_bf16 v[24:27], v[220:223], v[196:199], v[24:27]
	v_mfma_f32_16x16x32_bf16 v[16:19], v[228:231], v[196:199], v[16:19]
	v_mfma_f32_16x16x32_bf16 v[40:43], v[220:223], v[204:207], v[40:43]
	v_mfma_f32_16x16x32_bf16 v[32:35], v[228:231], v[204:207], v[32:35]
	v_mfma_f32_16x16x32_bf16 v[56:59], v[220:223], v[212:215], v[56:59]
	v_mfma_f32_16x16x32_bf16 v[60:63], v[228:231], v[212:215], v[60:63]
	s_mov_b32 m0, s39
	v_mfma_f32_16x16x32_bf16 v[12:15], v[224:227], v[192:195], v[12:15]
	v_mfma_f32_16x16x32_bf16 v[8:11], v[232:235], v[192:195], v[8:11]
	v_mfma_f32_16x16x32_bf16 v[24:27], v[224:227], v[200:203], v[24:27]
	v_mfma_f32_16x16x32_bf16 v[16:19], v[232:235], v[200:203], v[16:19]
	v_mfma_f32_16x16x32_bf16 v[40:43], v[224:227], v[208:211], v[40:43]
	v_mfma_f32_16x16x32_bf16 v[32:35], v[232:235], v[208:211], v[32:35]
	v_mfma_f32_16x16x32_bf16 v[56:59], v[224:227], v[216:219], v[56:59]
	v_mfma_f32_16x16x32_bf16 v[60:63], v[232:235], v[216:219], v[60:63]
	s_barrier
	s_setprio 0
	ds_read_b128 v[188:191], v181 offset:49152
	ds_read_b128 v[192:195], v181 offset:50176
	ds_read_b128 v[196:199], v181 offset:51200
	ds_read_b128 v[200:203], v181 offset:52224
	ds_read_b128 v[204:207], v181 offset:53248
	ds_read_b128 v[208:211], v181 offset:54272
	ds_read_b128 v[212:215], v181 offset:55296
	ds_read_b128 v[216:219], v181 offset:56320
	global_load_lds_dwordx4 v136, s[28:29]
	s_mov_b32 m0, s40
	s_nop 0
	global_load_lds_dwordx4 v140, s[28:29]
	s_setprio 1
	s_barrier
; __device__ __forceinline__ float bflo(unsigned w) { return __uint_as_float(w << 16); }
; __device__ __forceinline__ float bfhi(unsigned w) { return __uint_as_float(w & 0xffff0000u); }
; #define PG8_STAGE(bufoff, gbase, voff) do { _Pragma("unroll") for (int _i = 0; _i < 2; ++_i) \
;         __builtin_amdgcn_global_load_lds((const unsigned*)((const char*)(gbase) + (voff)[_i]), (LAS unsigned*)(lds + (bufoff) + ldsw + _i * 8192), 16, 0, 0); } while (0)
; #define PG8_LDA(dst, b, h) do { _Pragma("unroll") for (int m = 0; m < 4; ++m) _Pragma("unroll") for (int k = 0; k < 2; ++k) dst[m][k] = *(const LAS bf16x8*)(lds + PG8_SA(b, h) + aoff + m * 2048 + k * 1024); } while (0)
; #define PG8_MMA(ai, bj, At, Bt) do { __builtin_amdgcn_s_setprio(1); _Pragma("unroll") for (int m = 0; m < 4; ++m) _Pragma("unroll") for (int n = 0; n < 2; ++n) _Pragma("unroll") for (int k = 0; k < 2; ++k) \
;         acc[ai][bj][m][n] = __builtin_amdgcn_mfma_f32_16x16x32_bf16(Bt[n][k], At[m][k], acc[ai][bj][m][n], 0, 0, 0); __builtin_amdgcn_s_setprio(0); } while (0)
; #define PG8_WAIT_V(n) asm volatile("s_waitcnt vmcnt(" #n ")" ::: "memory")
; #define PG8_WAIT_L(n) asm volatile("s_waitcnt lgkmcnt(" #n ")" ::: "memory")
; #define PG8_BAR __builtin_amdgcn_s_barrier()
; #define PG8_SCHED __builtin_amdgcn_sched_barrier(0)
; template <class Epi, class Sched, bool ATILE = false>
; __device__ __forceinline__ void gemm_phase(LAS unsigned char* lds, const Gemm g, const Sched& S, const Epi& E) {
;     ...
;             PG8_BAR; PG8_WAIT_L(0); PG8_MMA(0, 1, At, B1); PG8_BAR;
;             PG8_LDA(At, 1, 1); PG8_STAGE(PG8_SA(1, 0), a3, voffA);
;             PG8_BAR; PG8_WAIT_L(0); PG8_MMA(1, 0, At, B0); PG8_BAR; PG8_SCHED;
;             PG8_STAGE(PG8_SB(1, 1), b3 + hstepB, voffB);
;             PG8_WAIT_V(6); PG8_BAR; PG8_MMA(1, 1, At, B1); PG8_BAR;
;     __device__ __forceinline__ void operator()(const f32x4 (&acc)[2][2][4][2], const Unit& u, int wr, int wc, int fr, int fq) const {
;     ...
;                     const f32x4 v0 = (f32x4){bflo(x.x), bfhi(x.x), bflo(x.y), bfhi(x.y)} + alpha * acc[ai][bj][m][0];
;                     const f32x4 v1 = (f32x4){bflo(x.z), bfhi(x.z), bflo(x.w), bfhi(x.w)} + alpha * acc[ai][bj][m][1];
	s_waitcnt lgkmcnt(0)
	v_mfma_f32_16x16x32_bf16 v[64:67], v[128:131], v[188:191], v[64:67]
	v_mfma_f32_16x16x32_bf16 v[108:111], v[128:131], v[196:199], v[108:111]
	v_mfma_f32_16x16x32_bf16 v[116:119], v[128:131], v[204:207], v[116:119]
	v_mfma_f32_16x16x32_bf16 v[20:23], v[128:131], v[212:215], v[20:23]
	v_mfma_f32_16x16x32_bf16 v[64:67], v[132:135], v[192:195], v[64:67]
	v_mfma_f32_16x16x32_bf16 v[68:71], v[174:177], v[188:191], v[68:71]
	v_mfma_f32_16x16x32_bf16 v[108:111], v[132:135], v[200:203], v[108:111]
	v_mfma_f32_16x16x32_bf16 v[100:103], v[174:177], v[196:199], v[100:103]
	s_add_u32 s26, s26, 0x158080
	v_mfma_f32_16x16x32_bf16 v[116:119], v[132:135], v[208:211], v[116:119]
	s_addc_u32 s27, s27, 0
	v_mfma_f32_16x16x32_bf16 v[112:115], v[174:177], v[204:207], v[112:115]
	s_add_i32 s28, s30, s33
	v_mfma_f32_16x16x32_bf16 v[132:135], v[132:135], v[216:219], v[20:23]
	s_mov_b32 m0, s28
	v_mfma_f32_16x16x32_bf16 v[20:23], v[174:177], v[212:215], v[28:31]
	v_mfma_f32_16x16x32_bf16 v[68:71], v[184:187], v[192:195], v[68:71]
	v_mfma_f32_16x16x32_bf16 v[100:103], v[184:187], v[200:203], v[100:103]
	v_mfma_f32_16x16x32_bf16 v[112:115], v[184:187], v[208:211], v[112:115]
	v_mfma_f32_16x16x32_bf16 v[128:131], v[184:187], v[216:219], v[20:23]
	s_barrier
	s_setprio 0
	s_nop 0
	global_load_lds_dwordx4 v138, s[26:27]
	s_add_i32 m0, s28, 0x2000
	s_nop 0
	global_load_lds_dwordx4 v142, s[26:27]
	s_waitcnt vmcnt(6)
	s_setprio 1
	s_barrier
	v_mfma_f32_16x16x32_bf16 v[20:23], v[220:223], v[188:191], v[76:79]
	v_mfma_f32_16x16x32_bf16 v[76:79], v[224:227], v[192:195], v[20:23]
	v_mfma_f32_16x16x32_bf16 v[20:23], v[228:231], v[188:191], v[72:75]
	v_mfma_f32_16x16x32_bf16 v[72:75], v[232:235], v[192:195], v[20:23]
	v_mfma_f32_16x16x32_bf16 v[20:23], v[220:223], v[196:199], v[88:91]
	v_mfma_f32_16x16x32_bf16 v[88:91], v[224:227], v[200:203], v[20:23]
	v_mfma_f32_16x16x32_bf16 v[20:23], v[228:231], v[196:199], v[80:83]
	s_add_u32 s56, s56, 0x100
	v_mfma_f32_16x16x32_bf16 v[80:83], v[232:235], v[200:203], v[20:23]
	s_addc_u32 s57, s57, 0
	v_mfma_f32_16x16x32_bf16 v[20:23], v[220:223], v[204:207], v[104:107]
	s_add_u32 s24, s24, 0x10000
	v_mfma_f32_16x16x32_bf16 v[104:107], v[224:227], v[208:211], v[20:23]
	s_addc_u32 s25, s25, 0
	v_mfma_f32_16x16x32_bf16 v[20:23], v[228:231], v[204:207], v[96:99]
	s_cmp_ge_i32 s58, s55
	v_mfma_f32_16x16x32_bf16 v[96:99], v[232:235], v[208:211], v[20:23]
	s_mov_b32 s26, s58
	v_mfma_f32_16x16x32_bf16 v[20:23], v[220:223], v[212:215], v[120:123]
	v_mfma_f32_16x16x32_bf16 v[120:123], v[224:227], v[216:219], v[20:23]
	v_mfma_f32_16x16x32_bf16 v[20:23], v[228:231], v[212:215], v[124:127]
	v_mfma_f32_16x16x32_bf16 v[124:127], v[232:235], v[216:219], v[20:23]
	s_barrier
	s_setprio 0
	s_cbranch_scc0 .LBB0_1898
	s_nop 5
	v_pk_mul_f32 v[2:3], v[2:3], 0.5 op_sel_hi:[1,0]
	v_pk_mul_f32 v[0:1], v[0:1], 0.5 op_sel_hi:[1,0]
	v_pk_mul_f32 v[6:7], v[6:7], 0.5 op_sel_hi:[1,0]
	v_pk_mul_f32 v[4:5], v[4:5], 0.5 op_sel_hi:[1,0]
	v_pk_mul_f32 v[22:23], v[14:15], 0.5 op_sel_hi:[1,0]
	v_pk_mul_f32 v[20:21], v[12:13], 0.5 op_sel_hi:[1,0]
	v_pk_mul_f32 v[30:31], v[10:11], 0.5 op_sel_hi:[1,0]
	v_pk_mul_f32 v[28:29], v[8:9], 0.5 op_sel_hi:[1,0]
	v_pk_mul_f32 v[10:11], v[46:47], 0.5 op_sel_hi:[1,0]
	v_pk_mul_f32 v[8:9], v[44:45], 0.5 op_sel_hi:[1,0]
	v_pk_mul_f32 v[14:15], v[38:39], 0.5 op_sel_hi:[1,0]
	v_pk_mul_f32 v[12:13], v[36:37], 0.5 op_sel_hi:[1,0]
	v_pk_mul_f32 v[38:39], v[26:27], 0.5 op_sel_hi:[1,0]
	v_pk_mul_f32 v[36:37], v[24:25], 0.5 op_sel_hi:[1,0]
	v_pk_mul_f32 v[46:47], v[18:19], 0.5 op_sel_hi:[1,0]
	v_pk_mul_f32 v[44:45], v[16:17], 0.5 op_sel_hi:[1,0]
	v_pk_mul_f32 v[18:19], v[54:55], 0.5 op_sel_hi:[1,0]
	v_pk_mul_f32 v[16:17], v[52:53], 0.5 op_sel_hi:[1,0]
	v_pk_mul_f32 v[26:27], v[50:51], 0.5 op_sel_hi:[1,0]
	v_pk_mul_f32 v[24:25], v[48:49], 0.5 op_sel_hi:[1,0]
	v_pk_mul_f32 v[50:51], v[42:43], 0.5 op_sel_hi:[1,0]
	v_pk_mul_f32 v[48:49], v[40:41], 0.5 op_sel_hi:[1,0]
	v_pk_mul_f32 v[54:55], v[34:35], 0.5 op_sel_hi:[1,0]
	v_pk_mul_f32 v[52:53], v[32:33], 0.5 op_sel_hi:[1,0]
	v_pk_mul_f32 v[34:35], v[94:95], 0.5 op_sel_hi:[1,0]
	v_pk_mul_f32 v[32:33], v[92:93], 0.5 op_sel_hi:[1,0]
	v_pk_mul_f32 v[42:43], v[86:87], 0.5 op_sel_hi:[1,0]
	v_pk_mul_f32 v[40:41], v[84:85], 0.5 op_sel_hi:[1,0]
	v_pk_mul_f32 v[58:59], v[58:59], 0.5 op_sel_hi:[1,0]
	v_pk_mul_f32 v[56:57], v[56:57], 0.5 op_sel_hi:[1,0]
	v_pk_mul_f32 v[62:63], v[62:63], 0.5 op_sel_hi:[1,0]
	v_pk_mul_f32 v[60:61], v[60:61], 0.5 op_sel_hi:[1,0]
	v_pk_mul_f32 v[66:67], v[66:67], 0.5 op_sel_hi:[1,0]
	v_pk_mul_f32 v[64:65], v[64:65], 0.5 op_sel_hi:[1,0]
	v_pk_mul_f32 v[70:71], v[70:71], 0.5 op_sel_hi:[1,0]
	v_pk_mul_f32 v[68:69], v[68:69], 0.5 op_sel_hi:[1,0]
	v_pk_mul_f32 v[86:87], v[78:79], 0.5 op_sel_hi:[1,0]
	v_pk_mul_f32 v[84:85], v[76:77], 0.5 op_sel_hi:[1,0]
	v_pk_mul_f32 v[94:95], v[74:75], 0.5 op_sel_hi:[1,0]
	v_pk_mul_f32 v[92:93], v[72:73], 0.5 op_sel_hi:[1,0]
	v_pk_mul_f32 v[74:75], v[110:111], 0.5 op_sel_hi:[1,0]
	v_pk_mul_f32 v[72:73], v[108:109], 0.5 op_sel_hi:[1,0]
	v_pk_mul_f32 v[78:79], v[102:103], 0.5 op_sel_hi:[1,0]
	v_pk_mul_f32 v[76:77], v[100:101], 0.5 op_sel_hi:[1,0]
	v_pk_mul_f32 v[102:103], v[90:91], 0.5 op_sel_hi:[1,0]
	v_pk_mul_f32 v[100:101], v[88:89], 0.5 op_sel_hi:[1,0]
	v_pk_mul_f32 v[110:111], v[82:83], 0.5 op_sel_hi:[1,0]
	v_pk_mul_f32 v[108:109], v[80:81], 0.5 op_sel_hi:[1,0]
	v_pk_mul_f32 v[82:83], v[118:119], 0.5 op_sel_hi:[1,0]
	v_pk_mul_f32 v[80:81], v[116:117], 0.5 op_sel_hi:[1,0]
	v_pk_mul_f32 v[90:91], v[114:115], 0.5 op_sel_hi:[1,0]
	v_pk_mul_f32 v[88:89], v[112:113], 0.5 op_sel_hi:[1,0]
	v_pk_mul_f32 v[114:115], v[106:107], 0.5 op_sel_hi:[1,0]
	v_pk_mul_f32 v[112:113], v[104:105], 0.5 op_sel_hi:[1,0]
	v_pk_mul_f32 v[118:119], v[98:99], 0.5 op_sel_hi:[1,0]
	v_pk_mul_f32 v[116:117], v[96:97], 0.5 op_sel_hi:[1,0]
	v_pk_mul_f32 v[98:99], v[134:135], 0.5 op_sel_hi:[1,0]
	v_pk_mul_f32 v[96:97], v[132:133], 0.5 op_sel_hi:[1,0]
	v_pk_mul_f32 v[106:107], v[130:131], 0.5 op_sel_hi:[1,0]
	v_pk_mul_f32 v[104:105], v[128:129], 0.5 op_sel_hi:[1,0]
	v_pk_mul_f32 v[122:123], v[122:123], 0.5 op_sel_hi:[1,0]
	v_pk_mul_f32 v[120:121], v[120:121], 0.5 op_sel_hi:[1,0]
	v_pk_mul_f32 v[126:127], v[126:127], 0.5 op_sel_hi:[1,0]
	v_pk_mul_f32 v[124:125], v[124:125], 0.5 op_sel_hi:[1,0]
	s_branch .LBB0_1903
